# EpiRes epilogues (phases 7,9): in-place residual loads prefetched half a block ahead with counted vmcnt instead of 16 serial round trips; stacked
# baseline (speedup 1.0000x reference)
; __device__ __forceinline__ float bf_lo(unsigned w) { return __uint_as_float(w << 16); }
; __device__ __forceinline__ float bf_hi(unsigned w) { return __uint_as_float(w & 0xffff0000u); }
; __device__ __forceinline__ u32x4 pack8(const f32x4 a, const f32x4 b) { u32x4 w; w.x = cvt_pk_bf16(a[0], a[1]); w.y = cvt_pk_bf16(a[2], a[3]); w.z = cvt_pk_bf16(b[0], b[1]); w.w = cvt_pk_bf16(b[2], b[3]); return w; }
;     __device__ __forceinline__ void operator()(const f32x4 (&acc)[2][2][4][2], const pg8::Unit& u, int wr, int wc, int fr, int fq, LAS unsigned char* lds, int par) const {
;     ...
;         if (prev) {
; #pragma unroll
;             for (int i = 0; i < 4; ++i) { gg[i] = *(const f32x4*)(pg + c0 + 4 * i); bb[i] = *(const f32x4*)(pb + c0 + 4 * i); }
;         }
; #pragma unroll
;         for (int ai = 0; ai < 2; ++ai)
; #pragma unroll
;             for (int m = 0; m < 4; ++m) {
;                 const int row = row0 + ai * 128 + m * 16, lrow = ai * 128 + wr * 64 + m * 16 + fr;
;                 const size_t ro = (size_t)row * D + c0;
;                 float mu = 0.f, rstd = 1.f; if (prev) { mu = rsb[2 * lrow]; rstd = rsb[2 * lrow + 1]; }
;                 float s1 = 0.f, s2 = 0.f;
; #pragma unroll
;                 for (int bj = 0; bj < 2; ++bj) {
;                     f32x4 r0, r1;
;                     if (prev) {
;                         const u32x4 w = *(const u32x4*)(tb + ro + bj * 8);
;                         r0 = (f32x4){bf_lo(w.x), bf_hi(w.x), bf_lo(w.y), bf_hi(w.y)}; r1 = (f32x4){bf_lo(w.z), bf_hi(w.z), bf_lo(w.w), bf_hi(w.w)};
;                         r0 = (r0 - mu) * rstd * gg[2 * bj] + bb[2 * bj]; r1 = (r1 - mu) * rstd * gg[2 * bj + 1] + bb[2 * bj + 1];
;                     } else { r0 = *(const f32x4*)(xin + ro + bj * 8); r1 = *(const f32x4*)(xin + ro + bj * 8 + 4); }
;                     const f32x4 t0 = r0 * ALPHA + acc[ai][bj][m][0], t1 = r1 * ALPHA + acc[ai][bj][m][1];
;                     if (xout != nullptr) { *(f32x4*)(xout + ro + bj * 8) = t0; *(f32x4*)(xout + ro + bj * 8 + 4) = t1; }
;                     const u32x4 pw = pack8(t0, t1);
;                     *(u32x4*)(tb + ro + bj * 8) = pw;
.LBB0_129:
	v_lshl_add_u32 v184, s26, 8, v192
	v_ashrrev_i32_e32 v185, 31, v184
	v_readlane_b32 s26, v251, 31
	v_lshl_or_b32 v182, s24, 8, v198
	v_lshlrev_b64 v[18:19], 12, v[184:185]
	v_readlane_b32 s27, v251, 32
	v_ashrrev_i32_e32 v183, 31, v182
	s_lshl_b32 s15, s25, 11
	v_lshl_add_u64 v[18:19], s[26:27], 0, v[18:19]
	v_lshl_add_u64 v[186:187], v[182:183], 1, v[18:19]
	s_nop 1
	v_lshlrev_b32_e32 v210, 12, v184
	v_lshl_add_u32 v210, v182, 1, v210
	global_load_dwordx4 v[244:247], v210, s[26:27]
	global_load_dwordx4 v[252:255], v210, s[26:27] offset:16
	v_lshlrev_b64 v[18:19], 2, v[182:183]
	v_lshl_add_u64 v[30:31], s[6:7], 0, v[18:19]
	v_lshl_add_u64 v[22:23], s[4:5], 0, v[18:19]
	global_load_dwordx4 v[50:53], v[30:31], off
	global_load_dwordx4 v[54:57], v[22:23], off
	global_load_dwordx4 v[42:45], v[22:23], off offset:16
	global_load_dwordx4 v[46:49], v[30:31], off offset:16
	s_and_b32 s15, s15, 0x800
	v_add_u32_e32 v200, s15, v197
	ds_read_b64 v[172:173], v200
	global_load_dwordx4 v[18:21], v[22:23], off offset:48
	global_load_dwordx4 v[26:29], v[22:23], off offset:32
	s_nop 0
	global_load_dwordx4 v[22:25], v[30:31], off offset:48
	s_nop 0
	global_load_dwordx4 v[30:33], v[30:31], off offset:32
	s_lshl_b32 s24, s24, 2
	s_ashr_i32 s25, s24, 31
	s_or_b64 s[24:25], s[24:25], s[2:3]
	s_waitcnt vmcnt(0) lgkmcnt(0)
	v_mov_b32_e32 v212, v244
	v_mov_b32_e32 v213, v245
	v_mov_b32_e32 v214, v246
	v_mov_b32_e32 v215, v247
	v_lshlrev_b32_e32 v174, 16, v212
	v_and_b32_e32 v175, 0xffff0000, v212
	v_lshlrev_b32_e32 v176, 16, v213
	v_and_b32_e32 v177, 0xffff0000, v213
	v_lshlrev_b32_e32 v188, 16, v214
	v_and_b32_e32 v189, 0xffff0000, v214
	v_lshlrev_b32_e32 v201, 16, v215
	v_and_b32_e32 v211, 0xffff0000, v215
	v_sub_f32_e32 v175, v175, v172
	v_sub_f32_e32 v174, v174, v172
	v_sub_f32_e32 v177, v177, v172
	v_sub_f32_e32 v176, v176, v172
	v_sub_f32_e32 v189, v189, v172
	v_sub_f32_e32 v188, v188, v172
	v_sub_f32_e32 v213, v211, v172
	v_sub_f32_e32 v212, v201, v172
	v_pk_mul_f32 v[176:177], v[172:173], v[176:177] op_sel:[1,0]
	v_pk_mul_f32 v[174:175], v[172:173], v[174:175] op_sel:[1,0]
	v_pk_mul_f32 v[212:213], v[172:173], v[212:213] op_sel:[1,0]
	v_pk_mul_f32 v[188:189], v[172:173], v[188:189] op_sel:[1,0]
	v_pk_fma_f32 v[174:175], v[54:55], v[174:175], v[50:51]
	v_pk_fma_f32 v[176:177], v[56:57], v[176:177], v[52:53]
	v_pk_fma_f32 v[188:189], v[42:43], v[188:189], v[46:47]
	v_pk_fma_f32 v[212:213], v[44:45], v[212:213], v[48:49]
	v_pk_fma_f32 v[160:161], v[176:177], s[72:73], v[160:161] op_sel_hi:[1,0,1]
	v_pk_fma_f32 v[158:159], v[174:175], s[72:73], v[158:159] op_sel_hi:[1,0,1]
	v_pk_fma_f32 v[174:175], v[212:213], s[72:73], v[156:157] op_sel_hi:[1,0,1]
	v_pk_fma_f32 v[156:157], v[188:189], s[72:73], v[154:155] op_sel_hi:[1,0,1]
	v_cvt_pk_bf16_f32 v154, v158, v159
	v_cvt_pk_bf16_f32 v155, v160, v161
	s_nop 0
	v_cvt_pk_bf16_f32 v156, v156, v157
	v_cvt_pk_bf16_f32 v157, v174, v175
	v_mov_b32_e32 v158, v252
	v_mov_b32_e32 v159, v253
	v_mov_b32_e32 v160, v254
	v_mov_b32_e32 v161, v255
	v_add_u32_e32 v210, 0x10000, v210
	global_load_dwordx4 v[244:247], v210, s[26:27]
	global_load_dwordx4 v[252:255], v210, s[26:27] offset:16
	v_lshlrev_b32_e32 v176, 16, v155
	global_store_dwordx4 v[186:187], v[154:157], off
	v_lshlrev_b32_e32 v212, 16, v157
	v_and_b32_e32 v214, 0xffff0000, v155
	v_and_b32_e32 v216, 0xffff0000, v157
	v_and_b32_e32 v174, 0xffff0000, v154
	v_lshlrev_b32_e32 v154, 16, v154
	v_and_b32_e32 v188, 0xffff0000, v156
	v_lshlrev_b32_e32 v156, 16, v156
	s_waitcnt lgkmcnt(0)
	v_lshlrev_b32_e32 v155, 16, v158
	v_and_b32_e32 v157, 0xffff0000, v158
	v_lshlrev_b32_e32 v175, 16, v159
	v_and_b32_e32 v177, 0xffff0000, v159
	v_lshlrev_b32_e32 v211, 16, v161
	v_and_b32_e32 v213, 0xffff0000, v161
	v_sub_f32_e32 v159, v157, v172
	v_sub_f32_e32 v158, v155, v172
	v_lshlrev_b32_e32 v189, 16, v160
	v_and_b32_e32 v201, 0xffff0000, v160
	v_sub_f32_e32 v161, v177, v172
	v_sub_f32_e32 v160, v175, v172
	v_sub_f32_e32 v221, v213, v172
	v_sub_f32_e32 v220, v211, v172
	v_pk_mul_f32 v[158:159], v[172:173], v[158:159] op_sel:[1,0]
	v_sub_f32_e32 v219, v201, v172
	v_sub_f32_e32 v218, v189, v172
	v_pk_mul_f32 v[160:161], v[172:173], v[160:161] op_sel:[1,0]
	v_pk_mul_f32 v[220:221], v[172:173], v[220:221] op_sel:[1,0]
	v_pk_fma_f32 v[158:159], v[26:27], v[158:159], v[30:31]
	v_pk_mul_f32 v[172:173], v[172:173], v[218:219] op_sel:[1,0]
	v_pk_fma_f32 v[160:161], v[28:29], v[160:161], v[32:33]
	v_pk_fma_f32 v[218:219], v[20:21], v[220:221], v[24:25]
	v_pk_fma_f32 v[150:151], v[158:159], s[72:73], v[150:151] op_sel_hi:[1,0,1]
	v_pk_fma_f32 v[172:173], v[18:19], v[172:173], v[22:23]
	v_pk_fma_f32 v[152:153], v[160:161], s[72:73], v[152:153] op_sel_hi:[1,0,1]
	v_pk_fma_f32 v[148:149], v[218:219], s[72:73], v[148:149] op_sel_hi:[1,0,1]
	v_cvt_pk_bf16_f32 v150, v150, v151
	v_cvt_pk_bf16_f32 v151, v152, v153
	v_pk_fma_f32 v[146:147], v[172:173], s[72:73], v[146:147] op_sel_hi:[1,0,1]
	v_lshlrev_b32_e32 v155, 16, v150
	v_and_b32_e32 v215, 0xffff0000, v150
	v_lshlrev_b32_e32 v157, 16, v151
	v_and_b32_e32 v217, 0xffff0000, v151
	v_cvt_pk_bf16_f32 v152, v146, v147
	v_cvt_pk_bf16_f32 v153, v148, v149
	v_pk_mul_f32 v[160:161], v[154:155], v[154:155]
	v_and_b32_e32 v149, 0xffff0000, v153
	v_and_b32_e32 v148, 0xffff0000, v152
	v_mov_b32_e32 v175, v155
	v_mov_b32_e32 v177, v215
	v_mov_b32_e32 v189, v157
	v_mov_b32_e32 v213, v217
	v_lshlrev_b32_e32 v146, 16, v152
	v_lshlrev_b32_e32 v147, 16, v153
	v_pk_mul_f32 v[158:159], v[148:149], v[148:149]
	v_pk_mul_f32 v[172:173], v[214:215], v[214:215]
	v_pk_mul_f32 v[218:219], v[156:157], v[156:157]
	v_pk_mul_f32 v[220:221], v[216:217], v[216:217]
; __device__ __forceinline__ float bf_lo(unsigned w) { return __uint_as_float(w << 16); }
; __device__ __forceinline__ float bf_hi(unsigned w) { return __uint_as_float(w & 0xffff0000u); }
; __device__ __forceinline__ float shflx(float v, int k, int lane) { return __int_as_float(__builtin_amdgcn_ds_bpermute((lane ^ k) << 2, __float_as_int(v))); }
;     __device__ __forceinline__ void operator()(const f32x4 (&acc)[2][2][4][2], const pg8::Unit& u, int wr, int wc, int fr, int fq, LAS unsigned char* lds, int par) const {
;     ...
;                 const int row = row0 + ai * 128 + m * 16, lrow = ai * 128 + wr * 64 + m * 16 + fr;
;                 const size_t ro = (size_t)row * D + c0;
;                 float mu = 0.f, rstd = 1.f; if (prev) { mu = rsb[2 * lrow]; rstd = rsb[2 * lrow + 1]; }
;                 float s1 = 0.f, s2 = 0.f;
; #pragma unroll
;                 for (int bj = 0; bj < 2; ++bj) {
;                     f32x4 r0, r1;
;                     if (prev) {
;                         const u32x4 w = *(const u32x4*)(tb + ro + bj * 8);
;                         r0 = (f32x4){bf_lo(w.x), bf_hi(w.x), bf_lo(w.y), bf_hi(w.y)}; r1 = (f32x4){bf_lo(w.z), bf_hi(w.z), bf_lo(w.w), bf_hi(w.w)};
;                         r0 = (r0 - mu) * rstd * gg[2 * bj] + bb[2 * bj]; r1 = (r1 - mu) * rstd * gg[2 * bj + 1] + bb[2 * bj + 1];
;                     } else { r0 = *(const f32x4*)(xin + ro + bj * 8); r1 = *(const f32x4*)(xin + ro + bj * 8 + 4); }
;     ...
;                     const float a0 = bf_lo(pw.x), a1 = bf_hi(pw.x), a2 = bf_lo(pw.y), a3 = bf_hi(pw.y), a4 = bf_lo(pw.z), a5 = bf_hi(pw.z), a6 = bf_lo(pw.w), a7 = bf_hi(pw.w);
;                     s1 += ((a0 + a1) + (a2 + a3)) + ((a4 + a5) + (a6 + a7));
;                     s2 += ((a0 * a0 + a1 * a1) + (a2 * a2 + a3 * a3)) + ((a4 * a4 + a5 * a5) + (a6 * a6 + a7 * a7));
;                 }
;                 s1 += shflx(s1, 16, fr + 16 * fq); s1 += shflx(s1, 32, fr + 16 * fq); s2 += shflx(s2, 16, fr + 16 * fq); s2 += shflx(s2, 32, fr + 16 * fq);
;                 if (fq == 0) { float* sp = stats_out + ((size_t)row * 32 + u.pn * 4 + wc) * 2; sp[0] = s1; sp[1] = s2; }
	v_pk_mul_f32 v[226:227], v[174:175], v[174:175]
	v_pk_mul_f32 v[228:229], v[176:177], v[176:177]
	v_pk_mul_f32 v[230:231], v[188:189], v[188:189]
	v_pk_mul_f32 v[232:233], v[212:213], v[212:213]
	v_pk_mov_b32 v[234:235], v[154:155], v[160:161] op_sel:[1,0]
	v_pk_add_f32 v[154:155], v[154:155], v[174:175]
	v_pk_add_f32 v[174:175], v[214:215], v[176:177]
	v_pk_add_f32 v[176:177], v[156:157], v[188:189]
	v_pk_add_f32 v[188:189], v[216:217], v[212:213]
	v_mov_b32_e32 v222, v146
	v_mov_b32_e32 v224, v148
	v_pk_fma_f32 v[158:159], v[146:147], v[146:147], v[158:159]
	v_pk_mov_b32 v[236:237], v[216:217], v[172:173] op_sel:[1,0]
	v_mov_b32_e32 v223, v218
	v_pk_mov_b32 v[148:149], v[148:149], v[220:221] op_sel:[1,0]
	v_pk_mov_b32 v[212:213], v[214:215], v[226:227] op_sel:[1,0]
	v_pk_mov_b32 v[156:157], v[156:157], v[228:229] op_sel:[1,0]
	v_mov_b32_e32 v225, v230
	v_pk_mov_b32 v[146:147], v[146:147], v[232:233] op_sel:[1,0]
	v_mov_b32_e32 v155, v161
	v_mov_b32_e32 v175, v173
	v_mov_b32_e32 v177, v219
	v_mov_b32_e32 v189, v221
	v_pk_add_f32 v[158:159], v[158:159], v[158:159] op_sel_hi:[0,1]
	v_pk_add_f32 v[160:161], v[234:235], v[212:213]
	v_pk_add_f32 v[156:157], v[156:157], v[236:237]
	v_pk_add_f32 v[172:173], v[222:223], v[224:225]
	v_pk_add_f32 v[146:147], v[146:147], v[148:149]
	v_pk_add_f32 v[148:149], v[154:155], v[174:175]
	v_pk_add_f32 v[154:155], v[176:177], v[188:189]
	v_mov_b32_e32 v158, v1
	v_pk_add_f32 v[156:157], v[160:161], v[156:157]
	v_pk_add_f32 v[146:147], v[172:173], v[146:147]
	v_pk_add_f32 v[148:149], v[148:149], v[154:155]
	v_pk_add_f32 v[146:147], v[156:157], v[146:147]
	v_pk_add_f32 v[148:149], v[148:149], v[158:159]
	global_store_dwordx4 v[186:187], v[150:153], off offset:16
	v_pk_add_f32 v[146:147], v[146:147], v[148:149]
	ds_bpermute_b32 v148, v194, v146
	ds_bpermute_b32 v149, v194, v147
	s_waitcnt lgkmcnt(0)
	v_pk_add_f32 v[146:147], v[146:147], v[148:149]
	ds_bpermute_b32 v148, v195, v146
	ds_bpermute_b32 v149, v195, v147
	s_and_saveexec_b64 s[26:27], s[42:43]
	s_cbranch_execz .LBB0_131
	v_lshlrev_b64 v[150:151], 8, v[184:185]
	v_lshl_add_u64 v[150:151], s[10:11], 0, v[150:151]
	v_lshl_add_u64 v[150:151], s[24:25], 3, v[150:151]
	s_waitcnt lgkmcnt(0)
	v_pk_add_f32 v[146:147], v[146:147], v[148:149]
	global_store_dwordx2 v[150:151], v[146:147], off
.LBB0_131:
	s_or_b64 exec, exec, s[26:27]
	v_or_b32_e32 v146, 16, v184
	v_ashrrev_i32_e32 v147, 31, v146
	v_readlane_b32 s26, v251, 31
	s_waitcnt lgkmcnt(0)
	v_lshlrev_b64 v[148:149], 12, v[146:147]
	v_readlane_b32 s27, v251, 32
	ds_read_b64 v[156:157], v200 offset:128
	s_nop 0
	v_lshl_add_u64 v[148:149], s[26:27], 0, v[148:149]
	v_lshl_add_u64 v[158:159], v[182:183], 1, v[148:149]
	s_waitcnt vmcnt(3) lgkmcnt(0)
	v_mov_b32_e32 v148, v244
	v_mov_b32_e32 v149, v245
	v_mov_b32_e32 v150, v246
	v_mov_b32_e32 v151, v247
	v_lshlrev_b32_e32 v152, 16, v148
	v_and_b32_e32 v148, 0xffff0000, v148
	v_lshlrev_b32_e32 v153, 16, v149
	v_and_b32_e32 v154, 0xffff0000, v149
	v_lshlrev_b32_e32 v155, 16, v150
	v_and_b32_e32 v160, 0xffff0000, v150
	v_lshlrev_b32_e32 v161, 16, v151
	v_and_b32_e32 v172, 0xffff0000, v151
	v_sub_f32_e32 v149, v148, v156
	v_sub_f32_e32 v148, v152, v156
	v_sub_f32_e32 v151, v154, v156
	v_sub_f32_e32 v150, v153, v156
	v_sub_f32_e32 v153, v160, v156
	v_sub_f32_e32 v152, v155, v156
	v_sub_f32_e32 v155, v172, v156
	v_sub_f32_e32 v154, v161, v156
	v_pk_mul_f32 v[148:149], v[156:157], v[148:149] op_sel:[1,0]
	v_pk_mul_f32 v[154:155], v[156:157], v[154:155] op_sel:[1,0]
	v_pk_mul_f32 v[152:153], v[156:157], v[152:153] op_sel:[1,0]
	v_pk_mul_f32 v[150:151], v[156:157], v[150:151] op_sel:[1,0]
	v_pk_fma_f32 v[148:149], v[54:55], v[148:149], v[50:51]
	v_pk_fma_f32 v[152:153], v[42:43], v[152:153], v[46:47]
	v_pk_fma_f32 v[154:155], v[44:45], v[154:155], v[48:49]
	v_pk_fma_f32 v[150:151], v[56:57], v[150:151], v[52:53]
	v_pk_fma_f32 v[142:143], v[148:149], s[72:73], v[142:143] op_sel_hi:[1,0,1]
	v_pk_fma_f32 v[148:149], v[154:155], s[72:73], v[140:141] op_sel_hi:[1,0,1]
	v_pk_fma_f32 v[140:141], v[152:153], s[72:73], v[138:139] op_sel_hi:[1,0,1]
	v_pk_fma_f32 v[144:145], v[150:151], s[72:73], v[144:145] op_sel_hi:[1,0,1]
	v_cvt_pk_bf16_f32 v138, v142, v143
	s_nop 0
	v_cvt_pk_bf16_f32 v139, v144, v145
	v_cvt_pk_bf16_f32 v140, v140, v141
	v_cvt_pk_bf16_f32 v141, v148, v149
	s_waitcnt vmcnt(2)
	v_mov_b32_e32 v152, v252
	v_mov_b32_e32 v153, v253
	v_mov_b32_e32 v154, v254
	v_mov_b32_e32 v155, v255
	v_add_u32_e32 v210, 0x10000, v210
	global_load_dwordx4 v[244:247], v210, s[26:27]
	global_load_dwordx4 v[252:255], v210, s[26:27] offset:16
	v_and_b32_e32 v150, 0xffff0000, v138
	global_store_dwordx4 v[158:159], v[138:141], off
	v_lshlrev_b32_e32 v148, 16, v139
	v_lshlrev_b32_e32 v142, 16, v141
	v_and_b32_e32 v144, 0xffff0000, v140
	s_waitcnt lgkmcnt(0)
; __device__ __forceinline__ float bf_lo(unsigned w) { return __uint_as_float(w << 16); }
; __device__ __forceinline__ float bf_hi(unsigned w) { return __uint_as_float(w & 0xffff0000u); }
; __device__ __forceinline__ float shflx(float v, int k, int lane) { return __int_as_float(__builtin_amdgcn_ds_bpermute((lane ^ k) << 2, __float_as_int(v))); }
; __device__ __forceinline__ u32x4 pack8(const f32x4 a, const f32x4 b) { u32x4 w; w.x = cvt_pk_bf16(a[0], a[1]); w.y = cvt_pk_bf16(a[2], a[3]); w.z = cvt_pk_bf16(b[0], b[1]); w.w = cvt_pk_bf16(b[2], b[3]); return w; }
;     __device__ __forceinline__ void operator()(const f32x4 (&acc)[2][2][4][2], const pg8::Unit& u, int wr, int wc, int fr, int fq, LAS unsigned char* lds, int par) const {
;     ...
;                         const u32x4 w = *(const u32x4*)(tb + ro + bj * 8);
;                         r0 = (f32x4){bf_lo(w.x), bf_hi(w.x), bf_lo(w.y), bf_hi(w.y)}; r1 = (f32x4){bf_lo(w.z), bf_hi(w.z), bf_lo(w.w), bf_hi(w.w)};
;                         r0 = (r0 - mu) * rstd * gg[2 * bj] + bb[2 * bj]; r1 = (r1 - mu) * rstd * gg[2 * bj + 1] + bb[2 * bj + 1];
;                     } else { r0 = *(const f32x4*)(xin + ro + bj * 8); r1 = *(const f32x4*)(xin + ro + bj * 8 + 4); }
;                     const f32x4 t0 = r0 * ALPHA + acc[ai][bj][m][0], t1 = r1 * ALPHA + acc[ai][bj][m][1];
;                     if (xout != nullptr) { *(f32x4*)(xout + ro + bj * 8) = t0; *(f32x4*)(xout + ro + bj * 8 + 4) = t1; }
;                     const u32x4 pw = pack8(t0, t1);
;                     *(u32x4*)(tb + ro + bj * 8) = pw;
;                     const float a0 = bf_lo(pw.x), a1 = bf_hi(pw.x), a2 = bf_lo(pw.y), a3 = bf_hi(pw.y), a4 = bf_lo(pw.z), a5 = bf_hi(pw.z), a6 = bf_lo(pw.w), a7 = bf_hi(pw.w);
;                     s1 += ((a0 + a1) + (a2 + a3)) + ((a4 + a5) + (a6 + a7));
;                     s2 += ((a0 * a0 + a1 * a1) + (a2 * a2 + a3 * a3)) + ((a4 * a4 + a5 * a5) + (a6 * a6 + a7 * a7));
;                 }
;                 s1 += shflx(s1, 16, fr + 16 * fq); s1 += shflx(s1, 32, fr + 16 * fq); s2 += shflx(s2, 16, fr + 16 * fq); s2 += shflx(s2, 32, fr + 16 * fq);
;                 if (fq == 0) { float* sp = stats_out + ((size_t)row * 32 + u.pn * 4 + wc) * 2; sp[0] = s1; sp[1] = s2; }
	v_lshlrev_b32_e32 v143, 16, v152
	v_and_b32_e32 v145, 0xffff0000, v152
	v_lshlrev_b32_e32 v149, 16, v153
	v_and_b32_e32 v151, 0xffff0000, v153
	v_lshlrev_b32_e32 v160, 16, v154
	v_and_b32_e32 v161, 0xffff0000, v154
	v_lshlrev_b32_e32 v172, 16, v155
	v_and_b32_e32 v173, 0xffff0000, v155
	v_sub_f32_e32 v153, v145, v156
	v_sub_f32_e32 v152, v143, v156
	v_sub_f32_e32 v155, v151, v156
	v_sub_f32_e32 v154, v149, v156
	v_sub_f32_e32 v161, v161, v156
	v_sub_f32_e32 v160, v160, v156
	v_sub_f32_e32 v173, v173, v156
	v_sub_f32_e32 v172, v172, v156
	v_pk_mul_f32 v[154:155], v[156:157], v[154:155] op_sel:[1,0]
	v_pk_mul_f32 v[152:153], v[156:157], v[152:153] op_sel:[1,0]
	v_pk_mul_f32 v[172:173], v[156:157], v[172:173] op_sel:[1,0]
	v_pk_mul_f32 v[156:157], v[156:157], v[160:161] op_sel:[1,0]
	v_pk_fma_f32 v[152:153], v[26:27], v[152:153], v[30:31]
	v_pk_fma_f32 v[154:155], v[28:29], v[154:155], v[32:33]
	v_pk_fma_f32 v[156:157], v[18:19], v[156:157], v[22:23]
	v_pk_fma_f32 v[160:161], v[20:21], v[172:173], v[24:25]
	v_pk_fma_f32 v[136:137], v[154:155], s[72:73], v[136:137] op_sel_hi:[1,0,1]
	v_pk_fma_f32 v[134:135], v[152:153], s[72:73], v[134:135] op_sel_hi:[1,0,1]
	v_pk_fma_f32 v[152:153], v[160:161], s[72:73], v[132:133] op_sel_hi:[1,0,1]
	v_pk_fma_f32 v[132:133], v[156:157], s[72:73], v[130:131] op_sel_hi:[1,0,1]
	v_cvt_pk_bf16_f32 v130, v134, v135
	v_cvt_pk_bf16_f32 v131, v136, v137
	v_lshlrev_b32_e32 v154, 16, v138
	v_lshlrev_b32_e32 v155, 16, v130
	v_cvt_pk_bf16_f32 v132, v132, v133
	v_cvt_pk_bf16_f32 v133, v152, v153
	v_mov_b32_e32 v151, v155
	v_and_b32_e32 v153, 0xffff0000, v130
	v_pk_mul_f32 v[156:157], v[154:155], v[154:155]
	v_pk_mul_f32 v[186:187], v[150:151], v[150:151]
	v_and_b32_e32 v152, 0xffff0000, v139
	v_mov_b32_e32 v149, v153
	global_store_dwordx4 v[158:159], v[130:133], off offset:16
	v_pk_mul_f32 v[172:173], v[148:149], v[148:149]
	v_pk_mul_f32 v[138:139], v[152:153], v[152:153]
	v_lshlrev_b32_e32 v158, 16, v140
	v_lshlrev_b32_e32 v159, 16, v131
	v_and_b32_e32 v131, 0xffff0000, v131
	v_and_b32_e32 v130, 0xffff0000, v141
	v_pk_mov_b32 v[176:177], v[154:155], v[156:157] op_sel:[1,0]
	v_pk_mov_b32 v[186:187], v[152:153], v[186:187] op_sel:[1,0]
	v_and_b32_e32 v135, 0xffff0000, v133
	v_and_b32_e32 v134, 0xffff0000, v132
	v_mov_b32_e32 v143, v131
	v_pk_add_f32 v[176:177], v[176:177], v[186:187]
	v_pk_mov_b32 v[172:173], v[158:159], v[172:173] op_sel:[1,0]
	v_pk_mov_b32 v[186:187], v[130:131], v[138:139] op_sel:[1,0]
	v_lshlrev_b32_e32 v136, 16, v132
	v_lshlrev_b32_e32 v137, 16, v133
	v_pk_mul_f32 v[132:133], v[134:135], v[134:135]
	v_pk_mul_f32 v[140:141], v[142:143], v[142:143]
	v_pk_mul_f32 v[174:175], v[130:131], v[130:131]
	v_pk_add_f32 v[172:173], v[172:173], v[186:187]
	v_pk_fma_f32 v[132:133], v[136:137], v[136:137], v[132:133]
	v_mov_b32_e32 v145, v159
	v_pk_add_f32 v[172:173], v[176:177], v[172:173]
	v_mov_b32_e32 v176, v136
	v_mov_b32_e32 v186, v134
	v_pk_mov_b32 v[136:137], v[136:137], v[140:141] op_sel:[1,0]
	v_pk_mov_b32 v[134:135], v[134:135], v[174:175] op_sel:[1,0]
	v_pk_add_f32 v[140:141], v[152:153], v[148:149]
	v_pk_mul_f32 v[160:161], v[158:159], v[158:159]
	v_pk_mul_f32 v[188:189], v[144:145], v[144:145]
	v_pk_add_f32 v[134:135], v[136:137], v[134:135]
	v_pk_add_f32 v[136:137], v[154:155], v[150:151]
	v_mov_b32_e32 v141, v139
	v_pk_add_f32 v[138:139], v[158:159], v[144:145]
	v_pk_add_f32 v[130:131], v[130:131], v[142:143]
	v_mov_b32_e32 v177, v160
	v_mov_b32_e32 v187, v188
	v_mov_b32_e32 v137, v157
	v_mov_b32_e32 v139, v161
	v_mov_b32_e32 v131, v175
	v_pk_add_f32 v[132:133], v[132:133], v[132:133] op_sel_hi:[0,1]
	v_pk_add_f32 v[176:177], v[176:177], v[186:187]
	v_pk_add_f32 v[136:137], v[136:137], v[140:141]
	v_pk_add_f32 v[130:131], v[138:139], v[130:131]
	v_pk_add_f32 v[134:135], v[176:177], v[134:135]
	v_pk_add_f32 v[130:131], v[136:137], v[130:131]
	v_mov_b32_e32 v132, v1
	v_pk_add_f32 v[134:135], v[172:173], v[134:135]
	v_pk_add_f32 v[130:131], v[130:131], v[132:133]
	s_nop 0
	v_pk_add_f32 v[130:131], v[134:135], v[130:131]
	ds_bpermute_b32 v132, v194, v130
	ds_bpermute_b32 v133, v194, v131
	s_waitcnt lgkmcnt(0)
	v_pk_add_f32 v[130:131], v[130:131], v[132:133]
	ds_bpermute_b32 v132, v195, v130
	ds_bpermute_b32 v133, v195, v131
	s_and_saveexec_b64 s[26:27], s[42:43]
	s_cbranch_execz .LBB0_133
	v_lshlrev_b64 v[134:135], 8, v[146:147]
	v_lshl_add_u64 v[134:135], s[10:11], 0, v[134:135]
	v_lshl_add_u64 v[134:135], s[24:25], 3, v[134:135]
	s_waitcnt lgkmcnt(0)
	v_pk_add_f32 v[130:131], v[130:131], v[132:133]
	global_store_dwordx2 v[134:135], v[130:131], off
; __device__ __forceinline__ float bf_lo(unsigned w) { return __uint_as_float(w << 16); }
; __device__ __forceinline__ float bf_hi(unsigned w) { return __uint_as_float(w & 0xffff0000u); }
;     __device__ __forceinline__ void operator()(const f32x4 (&acc)[2][2][4][2], const pg8::Unit& u, int wr, int wc, int fr, int fq, LAS unsigned char* lds, int par) const {
;     ...
;                 const int row = row0 + ai * 128 + m * 16, lrow = ai * 128 + wr * 64 + m * 16 + fr;
;                 const size_t ro = (size_t)row * D + c0;
;                 float mu = 0.f, rstd = 1.f; if (prev) { mu = rsb[2 * lrow]; rstd = rsb[2 * lrow + 1]; }
;                 float s1 = 0.f, s2 = 0.f;
; #pragma unroll
;                 for (int bj = 0; bj < 2; ++bj) {
;                     f32x4 r0, r1;
;                     if (prev) {
;                         const u32x4 w = *(const u32x4*)(tb + ro + bj * 8);
;                         r0 = (f32x4){bf_lo(w.x), bf_hi(w.x), bf_lo(w.y), bf_hi(w.y)}; r1 = (f32x4){bf_lo(w.z), bf_hi(w.z), bf_lo(w.w), bf_hi(w.w)};
;                         r0 = (r0 - mu) * rstd * gg[2 * bj] + bb[2 * bj]; r1 = (r1 - mu) * rstd * gg[2 * bj + 1] + bb[2 * bj + 1];
;                     } else { r0 = *(const f32x4*)(xin + ro + bj * 8); r1 = *(const f32x4*)(xin + ro + bj * 8 + 4); }
;                     const f32x4 t0 = r0 * ALPHA + acc[ai][bj][m][0], t1 = r1 * ALPHA + acc[ai][bj][m][1];
;                     if (xout != nullptr) { *(f32x4*)(xout + ro + bj * 8) = t0; *(f32x4*)(xout + ro + bj * 8 + 4) = t1; }
;                     const u32x4 pw = pack8(t0, t1);
;                     *(u32x4*)(tb + ro + bj * 8) = pw;
;                     const float a0 = bf_lo(pw.x), a1 = bf_hi(pw.x), a2 = bf_lo(pw.y), a3 = bf_hi(pw.y), a4 = bf_lo(pw.z), a5 = bf_hi(pw.z), a6 = bf_lo(pw.w), a7 = bf_hi(pw.w);
;                     s1 += ((a0 + a1) + (a2 + a3)) + ((a4 + a5) + (a6 + a7));
;                     s2 += ((a0 * a0 + a1 * a1) + (a2 * a2 + a3 * a3)) + ((a4 * a4 + a5 * a5) + (a6 * a6 + a7 * a7));
;                 }
;                 s1 += shflx(s1, 16, fr + 16 * fq); s1 += shflx(s1, 32, fr + 16 * fq); s2 += shflx(s2, 16, fr + 16 * fq); s2 += shflx(s2, 32, fr + 16 * fq);
;                 if (fq == 0) { float* sp = stats_out + ((size_t)row * 32 + u.pn * 4 + wc) * 2; sp[0] = s1; sp[1] = s2; }
.LBB0_133:
	s_or_b64 exec, exec, s[26:27]
	v_or_b32_e32 v130, 32, v184
	v_ashrrev_i32_e32 v131, 31, v130
	v_readlane_b32 s26, v251, 31
	s_waitcnt lgkmcnt(0)
	v_lshlrev_b64 v[132:133], 12, v[130:131]
	v_readlane_b32 s27, v251, 32
	ds_read_b64 v[140:141], v200 offset:256
	s_nop 0
	v_lshl_add_u64 v[132:133], s[26:27], 0, v[132:133]
	v_lshl_add_u64 v[142:143], v[182:183], 1, v[132:133]
	s_waitcnt vmcnt(3) lgkmcnt(0)
	v_mov_b32_e32 v132, v244
	v_mov_b32_e32 v133, v245
	v_mov_b32_e32 v134, v246
	v_mov_b32_e32 v135, v247
	v_lshlrev_b32_e32 v136, 16, v132
	v_and_b32_e32 v132, 0xffff0000, v132
	v_lshlrev_b32_e32 v137, 16, v133
	v_and_b32_e32 v138, 0xffff0000, v133
	v_lshlrev_b32_e32 v139, 16, v134
	v_and_b32_e32 v144, 0xffff0000, v134
	v_lshlrev_b32_e32 v145, 16, v135
	v_and_b32_e32 v146, 0xffff0000, v135
	v_sub_f32_e32 v133, v132, v140
	v_sub_f32_e32 v132, v136, v140
	v_sub_f32_e32 v135, v138, v140
	v_sub_f32_e32 v134, v137, v140
	v_sub_f32_e32 v137, v144, v140
	v_sub_f32_e32 v136, v139, v140
	v_sub_f32_e32 v139, v146, v140
	v_sub_f32_e32 v138, v145, v140
	v_pk_mul_f32 v[132:133], v[140:141], v[132:133] op_sel:[1,0]
	v_pk_mul_f32 v[138:139], v[140:141], v[138:139] op_sel:[1,0]
	v_pk_mul_f32 v[136:137], v[140:141], v[136:137] op_sel:[1,0]
	v_pk_mul_f32 v[134:135], v[140:141], v[134:135] op_sel:[1,0]
	v_pk_fma_f32 v[132:133], v[54:55], v[132:133], v[50:51]
	v_pk_fma_f32 v[136:137], v[42:43], v[136:137], v[46:47]
	v_pk_fma_f32 v[138:139], v[44:45], v[138:139], v[48:49]
	v_pk_fma_f32 v[134:135], v[56:57], v[134:135], v[52:53]
	v_pk_fma_f32 v[126:127], v[132:133], s[72:73], v[126:127] op_sel_hi:[1,0,1]
	v_pk_fma_f32 v[132:133], v[138:139], s[72:73], v[124:125] op_sel_hi:[1,0,1]
	v_pk_fma_f32 v[124:125], v[136:137], s[72:73], v[122:123] op_sel_hi:[1,0,1]
	v_pk_fma_f32 v[128:129], v[134:135], s[72:73], v[128:129] op_sel_hi:[1,0,1]
	v_cvt_pk_bf16_f32 v122, v126, v127
	s_nop 0
	v_cvt_pk_bf16_f32 v123, v128, v129
	v_cvt_pk_bf16_f32 v124, v124, v125
	v_cvt_pk_bf16_f32 v125, v132, v133
	s_waitcnt vmcnt(2)
	v_mov_b32_e32 v136, v252
	v_mov_b32_e32 v137, v253
	v_mov_b32_e32 v138, v254
	v_mov_b32_e32 v139, v255
	v_add_u32_e32 v210, 0x10000, v210
	global_load_dwordx4 v[244:247], v210, s[26:27]
	global_load_dwordx4 v[252:255], v210, s[26:27] offset:16
	v_and_b32_e32 v134, 0xffff0000, v122
	global_store_dwordx4 v[142:143], v[122:125], off
	v_lshlrev_b32_e32 v132, 16, v123
	v_lshlrev_b32_e32 v126, 16, v125
	v_and_b32_e32 v128, 0xffff0000, v124
	s_waitcnt lgkmcnt(0)
	v_lshlrev_b32_e32 v127, 16, v136
	v_and_b32_e32 v129, 0xffff0000, v136
	v_lshlrev_b32_e32 v133, 16, v137
	v_and_b32_e32 v135, 0xffff0000, v137
	v_lshlrev_b32_e32 v144, 16, v138
	v_and_b32_e32 v145, 0xffff0000, v138
	v_lshlrev_b32_e32 v146, 16, v139
	v_and_b32_e32 v147, 0xffff0000, v139
	v_sub_f32_e32 v137, v129, v140
	v_sub_f32_e32 v136, v127, v140
	v_sub_f32_e32 v139, v135, v140
	v_sub_f32_e32 v138, v133, v140
	v_sub_f32_e32 v145, v145, v140
	v_sub_f32_e32 v144, v144, v140
	v_sub_f32_e32 v147, v147, v140
	v_sub_f32_e32 v146, v146, v140
	v_pk_mul_f32 v[138:139], v[140:141], v[138:139] op_sel:[1,0]
	v_pk_mul_f32 v[136:137], v[140:141], v[136:137] op_sel:[1,0]
	v_pk_mul_f32 v[146:147], v[140:141], v[146:147] op_sel:[1,0]
	v_pk_mul_f32 v[140:141], v[140:141], v[144:145] op_sel:[1,0]
	v_pk_fma_f32 v[136:137], v[26:27], v[136:137], v[30:31]
	v_pk_fma_f32 v[138:139], v[28:29], v[138:139], v[32:33]
	v_pk_fma_f32 v[140:141], v[18:19], v[140:141], v[22:23]
	v_pk_fma_f32 v[144:145], v[20:21], v[146:147], v[24:25]
	v_pk_fma_f32 v[120:121], v[138:139], s[72:73], v[120:121] op_sel_hi:[1,0,1]
	v_pk_fma_f32 v[118:119], v[136:137], s[72:73], v[118:119] op_sel_hi:[1,0,1]
	v_pk_fma_f32 v[136:137], v[144:145], s[72:73], v[116:117] op_sel_hi:[1,0,1]
	v_pk_fma_f32 v[116:117], v[140:141], s[72:73], v[114:115] op_sel_hi:[1,0,1]
	v_cvt_pk_bf16_f32 v114, v118, v119
	v_cvt_pk_bf16_f32 v115, v120, v121
	v_lshlrev_b32_e32 v138, 16, v122
	v_lshlrev_b32_e32 v139, 16, v114
	v_cvt_pk_bf16_f32 v116, v116, v117
	v_cvt_pk_bf16_f32 v117, v136, v137
	v_mov_b32_e32 v135, v139
	v_and_b32_e32 v137, 0xffff0000, v114
	v_pk_mul_f32 v[140:141], v[138:139], v[138:139]
	v_pk_mul_f32 v[146:147], v[134:135], v[134:135]
	v_and_b32_e32 v136, 0xffff0000, v123
	v_mov_b32_e32 v133, v137
	global_store_dwordx4 v[142:143], v[114:117], off offset:16
	v_pk_mul_f32 v[150:151], v[132:133], v[132:133]
	v_pk_mul_f32 v[122:123], v[136:137], v[136:137]
	v_lshlrev_b32_e32 v142, 16, v124
	v_lshlrev_b32_e32 v143, 16, v115
	v_and_b32_e32 v115, 0xffff0000, v115
	v_and_b32_e32 v114, 0xffff0000, v125
	v_pk_mov_b32 v[154:155], v[138:139], v[140:141] op_sel:[1,0]
	v_pk_mov_b32 v[146:147], v[136:137], v[146:147] op_sel:[1,0]
	v_and_b32_e32 v119, 0xffff0000, v117
	v_and_b32_e32 v118, 0xffff0000, v116
	v_mov_b32_e32 v127, v115
	v_pk_add_f32 v[146:147], v[154:155], v[146:147]
	v_pk_mov_b32 v[150:151], v[142:143], v[150:151] op_sel:[1,0]
	v_pk_mov_b32 v[154:155], v[114:115], v[122:123] op_sel:[1,0]
	v_lshlrev_b32_e32 v120, 16, v116
	v_lshlrev_b32_e32 v121, 16, v117
	v_pk_mul_f32 v[116:117], v[118:119], v[118:119]
	v_pk_mul_f32 v[124:125], v[126:127], v[126:127]
	v_pk_mul_f32 v[152:153], v[114:115], v[114:115]
	v_pk_add_f32 v[150:151], v[150:151], v[154:155]
	v_pk_fma_f32 v[116:117], v[120:121], v[120:121], v[116:117]
	v_mov_b32_e32 v129, v143
	v_pk_add_f32 v[146:147], v[146:147], v[150:151]
	v_mov_b32_e32 v150, v120
	v_mov_b32_e32 v154, v118
	v_pk_mov_b32 v[120:121], v[120:121], v[124:125] op_sel:[1,0]
	v_pk_mov_b32 v[118:119], v[118:119], v[152:153] op_sel:[1,0]
	v_pk_add_f32 v[124:125], v[136:137], v[132:133]
	v_pk_mul_f32 v[144:145], v[142:143], v[142:143]
	v_pk_mul_f32 v[148:149], v[128:129], v[128:129]
	v_pk_add_f32 v[118:119], v[120:121], v[118:119]
	v_pk_add_f32 v[120:121], v[138:139], v[134:135]
	v_mov_b32_e32 v125, v123
	v_pk_add_f32 v[122:123], v[142:143], v[128:129]
	v_pk_add_f32 v[114:115], v[114:115], v[126:127]
	v_mov_b32_e32 v151, v144
	v_mov_b32_e32 v155, v148
	v_mov_b32_e32 v121, v141
	v_mov_b32_e32 v123, v145
	v_mov_b32_e32 v115, v153
	v_pk_add_f32 v[116:117], v[116:117], v[116:117] op_sel_hi:[0,1]
	v_pk_add_f32 v[148:149], v[150:151], v[154:155]
	v_pk_add_f32 v[120:121], v[120:121], v[124:125]
	v_pk_add_f32 v[114:115], v[122:123], v[114:115]
	v_pk_add_f32 v[118:119], v[148:149], v[118:119]
	v_pk_add_f32 v[114:115], v[120:121], v[114:115]
	v_mov_b32_e32 v116, v1
	v_pk_add_f32 v[118:119], v[146:147], v[118:119]
	v_pk_add_f32 v[114:115], v[114:115], v[116:117]
	s_nop 0
	v_pk_add_f32 v[114:115], v[118:119], v[114:115]
	ds_bpermute_b32 v116, v194, v114
	ds_bpermute_b32 v117, v194, v115
	s_waitcnt lgkmcnt(0)
	v_pk_add_f32 v[114:115], v[114:115], v[116:117]
	ds_bpermute_b32 v116, v195, v114
	ds_bpermute_b32 v117, v195, v115
	s_and_saveexec_b64 s[26:27], s[42:43]
	s_cbranch_execz .LBB0_135
; __device__ __forceinline__ float bf_lo(unsigned w) { return __uint_as_float(w << 16); }
; __device__ __forceinline__ float bf_hi(unsigned w) { return __uint_as_float(w & 0xffff0000u); }
;     __device__ __forceinline__ void operator()(const f32x4 (&acc)[2][2][4][2], const pg8::Unit& u, int wr, int wc, int fr, int fq, LAS unsigned char* lds, int par) const {
;     ...
;                 const int row = row0 + ai * 128 + m * 16, lrow = ai * 128 + wr * 64 + m * 16 + fr;
;                 const size_t ro = (size_t)row * D + c0;
;                 float mu = 0.f, rstd = 1.f; if (prev) { mu = rsb[2 * lrow]; rstd = rsb[2 * lrow + 1]; }
;                 float s1 = 0.f, s2 = 0.f;
; #pragma unroll
;                 for (int bj = 0; bj < 2; ++bj) {
;                     f32x4 r0, r1;
;                     if (prev) {
;                         const u32x4 w = *(const u32x4*)(tb + ro + bj * 8);
;                         r0 = (f32x4){bf_lo(w.x), bf_hi(w.x), bf_lo(w.y), bf_hi(w.y)}; r1 = (f32x4){bf_lo(w.z), bf_hi(w.z), bf_lo(w.w), bf_hi(w.w)};
;                         r0 = (r0 - mu) * rstd * gg[2 * bj] + bb[2 * bj]; r1 = (r1 - mu) * rstd * gg[2 * bj + 1] + bb[2 * bj + 1];
;                     } else { r0 = *(const f32x4*)(xin + ro + bj * 8); r1 = *(const f32x4*)(xin + ro + bj * 8 + 4); }
;                     const f32x4 t0 = r0 * ALPHA + acc[ai][bj][m][0], t1 = r1 * ALPHA + acc[ai][bj][m][1];
;                     if (xout != nullptr) { *(f32x4*)(xout + ro + bj * 8) = t0; *(f32x4*)(xout + ro + bj * 8 + 4) = t1; }
;                     const u32x4 pw = pack8(t0, t1);
;                     *(u32x4*)(tb + ro + bj * 8) = pw;
;                     const float a0 = bf_lo(pw.x), a1 = bf_hi(pw.x), a2 = bf_lo(pw.y), a3 = bf_hi(pw.y), a4 = bf_lo(pw.z), a5 = bf_hi(pw.z), a6 = bf_lo(pw.w), a7 = bf_hi(pw.w);
;                     s1 += ((a0 + a1) + (a2 + a3)) + ((a4 + a5) + (a6 + a7));
;                     s2 += ((a0 * a0 + a1 * a1) + (a2 * a2 + a3 * a3)) + ((a4 * a4 + a5 * a5) + (a6 * a6 + a7 * a7));
;                 }
;                 s1 += shflx(s1, 16, fr + 16 * fq); s1 += shflx(s1, 32, fr + 16 * fq); s2 += shflx(s2, 16, fr + 16 * fq); s2 += shflx(s2, 32, fr + 16 * fq);
;                 if (fq == 0) { float* sp = stats_out + ((size_t)row * 32 + u.pn * 4 + wc) * 2; sp[0] = s1; sp[1] = s2; }
	v_lshlrev_b64 v[118:119], 8, v[130:131]
	v_lshl_add_u64 v[118:119], s[10:11], 0, v[118:119]
	v_lshl_add_u64 v[118:119], s[24:25], 3, v[118:119]
	s_waitcnt lgkmcnt(0)
	v_pk_add_f32 v[114:115], v[114:115], v[116:117]
	global_store_dwordx2 v[118:119], v[114:115], off
.LBB0_135:
	s_or_b64 exec, exec, s[26:27]
	v_or_b32_e32 v114, 48, v184
	v_ashrrev_i32_e32 v115, 31, v114
	v_readlane_b32 s26, v251, 31
	s_waitcnt lgkmcnt(0)
	v_lshlrev_b64 v[116:117], 12, v[114:115]
	v_readlane_b32 s27, v251, 32
	ds_read_b64 v[124:125], v200 offset:384
	s_nop 0
	v_lshl_add_u64 v[116:117], s[26:27], 0, v[116:117]
	v_lshl_add_u64 v[126:127], v[182:183], 1, v[116:117]
	s_waitcnt vmcnt(3) lgkmcnt(0)
	v_mov_b32_e32 v116, v244
	v_mov_b32_e32 v117, v245
	v_mov_b32_e32 v118, v246
	v_mov_b32_e32 v119, v247
	v_lshlrev_b32_e32 v120, 16, v116
	v_and_b32_e32 v116, 0xffff0000, v116
	v_lshlrev_b32_e32 v121, 16, v117
	v_and_b32_e32 v122, 0xffff0000, v117
	v_lshlrev_b32_e32 v123, 16, v118
	v_and_b32_e32 v128, 0xffff0000, v118
	v_lshlrev_b32_e32 v129, 16, v119
	v_and_b32_e32 v130, 0xffff0000, v119
	v_sub_f32_e32 v117, v116, v124
	v_sub_f32_e32 v116, v120, v124
	v_sub_f32_e32 v119, v122, v124
	v_sub_f32_e32 v118, v121, v124
	v_sub_f32_e32 v121, v128, v124
	v_sub_f32_e32 v120, v123, v124
	v_sub_f32_e32 v123, v130, v124
	v_sub_f32_e32 v122, v129, v124
	v_pk_mul_f32 v[116:117], v[124:125], v[116:117] op_sel:[1,0]
	v_pk_mul_f32 v[122:123], v[124:125], v[122:123] op_sel:[1,0]
	v_pk_mul_f32 v[120:121], v[124:125], v[120:121] op_sel:[1,0]
	v_pk_mul_f32 v[118:119], v[124:125], v[118:119] op_sel:[1,0]
	v_pk_fma_f32 v[116:117], v[54:55], v[116:117], v[50:51]
	v_pk_fma_f32 v[120:121], v[42:43], v[120:121], v[46:47]
	v_pk_fma_f32 v[122:123], v[44:45], v[122:123], v[48:49]
	v_pk_fma_f32 v[118:119], v[56:57], v[118:119], v[52:53]
	v_pk_fma_f32 v[110:111], v[116:117], s[72:73], v[110:111] op_sel_hi:[1,0,1]
	v_pk_fma_f32 v[116:117], v[122:123], s[72:73], v[108:109] op_sel_hi:[1,0,1]
	v_pk_fma_f32 v[108:109], v[120:121], s[72:73], v[106:107] op_sel_hi:[1,0,1]
	v_pk_fma_f32 v[112:113], v[118:119], s[72:73], v[112:113] op_sel_hi:[1,0,1]
	v_cvt_pk_bf16_f32 v106, v110, v111
	s_nop 0
	v_cvt_pk_bf16_f32 v107, v112, v113
	v_cvt_pk_bf16_f32 v108, v108, v109
	v_cvt_pk_bf16_f32 v109, v116, v117
	s_waitcnt vmcnt(2)
	v_mov_b32_e32 v120, v252
	v_mov_b32_e32 v121, v253
	v_mov_b32_e32 v122, v254
	v_mov_b32_e32 v123, v255
	v_add_u32_e32 v210, 0x50000, v210
	global_load_dwordx4 v[244:247], v210, s[26:27]
	global_load_dwordx4 v[252:255], v210, s[26:27] offset:16
	v_and_b32_e32 v118, 0xffff0000, v106
	global_store_dwordx4 v[126:127], v[106:109], off
	v_lshlrev_b32_e32 v116, 16, v107
	v_lshlrev_b32_e32 v110, 16, v109
	v_and_b32_e32 v112, 0xffff0000, v108
	s_waitcnt lgkmcnt(0)
	v_lshlrev_b32_e32 v111, 16, v120
	v_and_b32_e32 v113, 0xffff0000, v120
	v_lshlrev_b32_e32 v117, 16, v121
	v_and_b32_e32 v119, 0xffff0000, v121
	v_lshlrev_b32_e32 v128, 16, v122
	v_and_b32_e32 v129, 0xffff0000, v122
	v_lshlrev_b32_e32 v130, 16, v123
	v_and_b32_e32 v131, 0xffff0000, v123
	v_sub_f32_e32 v121, v113, v124
	v_sub_f32_e32 v120, v111, v124
	v_sub_f32_e32 v123, v119, v124
	v_sub_f32_e32 v122, v117, v124
	v_sub_f32_e32 v129, v129, v124
	v_sub_f32_e32 v128, v128, v124
	v_sub_f32_e32 v131, v131, v124
	v_sub_f32_e32 v130, v130, v124
	v_pk_mul_f32 v[122:123], v[124:125], v[122:123] op_sel:[1,0]
	v_pk_mul_f32 v[120:121], v[124:125], v[120:121] op_sel:[1,0]
	v_pk_mul_f32 v[130:131], v[124:125], v[130:131] op_sel:[1,0]
	v_pk_mul_f32 v[124:125], v[124:125], v[128:129] op_sel:[1,0]
	v_pk_fma_f32 v[120:121], v[26:27], v[120:121], v[30:31]
	v_pk_fma_f32 v[122:123], v[28:29], v[122:123], v[32:33]
	v_pk_fma_f32 v[124:125], v[18:19], v[124:125], v[22:23]
	v_pk_fma_f32 v[128:129], v[20:21], v[130:131], v[24:25]
	v_pk_fma_f32 v[104:105], v[122:123], s[72:73], v[104:105] op_sel_hi:[1,0,1]
	v_pk_fma_f32 v[102:103], v[120:121], s[72:73], v[102:103] op_sel_hi:[1,0,1]
	v_pk_fma_f32 v[120:121], v[128:129], s[72:73], v[100:101] op_sel_hi:[1,0,1]
	v_pk_fma_f32 v[100:101], v[124:125], s[72:73], v[98:99] op_sel_hi:[1,0,1]
	v_cvt_pk_bf16_f32 v98, v102, v103
	v_cvt_pk_bf16_f32 v99, v104, v105
	v_lshlrev_b32_e32 v122, 16, v106
	v_lshlrev_b32_e32 v123, 16, v98
	v_cvt_pk_bf16_f32 v100, v100, v101
	v_cvt_pk_bf16_f32 v101, v120, v121
	v_mov_b32_e32 v119, v123
	v_and_b32_e32 v121, 0xffff0000, v98
	v_pk_mul_f32 v[124:125], v[122:123], v[122:123]
	v_pk_mul_f32 v[130:131], v[118:119], v[118:119]
	v_and_b32_e32 v120, 0xffff0000, v107
	v_mov_b32_e32 v117, v121
	global_store_dwordx4 v[126:127], v[98:101], off offset:16
	v_pk_mul_f32 v[134:135], v[116:117], v[116:117]
	v_pk_mul_f32 v[106:107], v[120:121], v[120:121]
	v_lshlrev_b32_e32 v126, 16, v108
	v_lshlrev_b32_e32 v127, 16, v99
	v_and_b32_e32 v99, 0xffff0000, v99
	v_and_b32_e32 v98, 0xffff0000, v109
	v_pk_mov_b32 v[138:139], v[122:123], v[124:125] op_sel:[1,0]
	v_pk_mov_b32 v[130:131], v[120:121], v[130:131] op_sel:[1,0]
	v_and_b32_e32 v103, 0xffff0000, v101
	v_and_b32_e32 v102, 0xffff0000, v100
	v_mov_b32_e32 v111, v99
	v_pk_add_f32 v[130:131], v[138:139], v[130:131]
	v_pk_mov_b32 v[134:135], v[126:127], v[134:135] op_sel:[1,0]
	v_pk_mov_b32 v[138:139], v[98:99], v[106:107] op_sel:[1,0]
	v_lshlrev_b32_e32 v104, 16, v100
	v_lshlrev_b32_e32 v105, 16, v101
	v_pk_mul_f32 v[100:101], v[102:103], v[102:103]
	v_pk_mul_f32 v[108:109], v[110:111], v[110:111]
	v_pk_mul_f32 v[136:137], v[98:99], v[98:99]
	v_pk_add_f32 v[134:135], v[134:135], v[138:139]
	v_pk_fma_f32 v[100:101], v[104:105], v[104:105], v[100:101]
	v_mov_b32_e32 v113, v127
	v_pk_add_f32 v[130:131], v[130:131], v[134:135]
	v_mov_b32_e32 v134, v104
	v_mov_b32_e32 v138, v102
	v_pk_mov_b32 v[104:105], v[104:105], v[108:109] op_sel:[1,0]
	v_pk_mov_b32 v[102:103], v[102:103], v[136:137] op_sel:[1,0]
	v_pk_add_f32 v[108:109], v[120:121], v[116:117]
	v_pk_mul_f32 v[128:129], v[126:127], v[126:127]
	v_pk_mul_f32 v[132:133], v[112:113], v[112:113]
	v_pk_add_f32 v[102:103], v[104:105], v[102:103]
	v_pk_add_f32 v[104:105], v[122:123], v[118:119]
	v_mov_b32_e32 v109, v107
	v_pk_add_f32 v[106:107], v[126:127], v[112:113]
	v_pk_add_f32 v[98:99], v[98:99], v[110:111]
	v_mov_b32_e32 v135, v128
	v_mov_b32_e32 v139, v132
	v_mov_b32_e32 v105, v125
	v_mov_b32_e32 v107, v129
	v_mov_b32_e32 v99, v137
	v_pk_add_f32 v[100:101], v[100:101], v[100:101] op_sel_hi:[0,1]
	v_pk_add_f32 v[132:133], v[134:135], v[138:139]
	v_pk_add_f32 v[104:105], v[104:105], v[108:109]
	v_pk_add_f32 v[98:99], v[106:107], v[98:99]
	v_pk_add_f32 v[102:103], v[132:133], v[102:103]
	v_pk_add_f32 v[98:99], v[104:105], v[98:99]
	v_mov_b32_e32 v100, v1
	v_pk_add_f32 v[102:103], v[130:131], v[102:103]
	v_pk_add_f32 v[98:99], v[98:99], v[100:101]
	s_nop 0
	v_pk_add_f32 v[98:99], v[102:103], v[98:99]
	ds_bpermute_b32 v100, v194, v98
	ds_bpermute_b32 v101, v194, v99
	s_waitcnt lgkmcnt(0)
	v_pk_add_f32 v[98:99], v[98:99], v[100:101]
	ds_bpermute_b32 v100, v195, v98
	ds_bpermute_b32 v101, v195, v99
	s_and_saveexec_b64 s[26:27], s[42:43]
	s_cbranch_execz .LBB0_137
; __device__ __forceinline__ float bf_lo(unsigned w) { return __uint_as_float(w << 16); }
; __device__ __forceinline__ float bf_hi(unsigned w) { return __uint_as_float(w & 0xffff0000u); }
;     __device__ __forceinline__ void operator()(const f32x4 (&acc)[2][2][4][2], const pg8::Unit& u, int wr, int wc, int fr, int fq, LAS unsigned char* lds, int par) const {
;     ...
;                 const int row = row0 + ai * 128 + m * 16, lrow = ai * 128 + wr * 64 + m * 16 + fr;
;                 const size_t ro = (size_t)row * D + c0;
;                 float mu = 0.f, rstd = 1.f; if (prev) { mu = rsb[2 * lrow]; rstd = rsb[2 * lrow + 1]; }
;                 float s1 = 0.f, s2 = 0.f;
; #pragma unroll
;                 for (int bj = 0; bj < 2; ++bj) {
;                     f32x4 r0, r1;
;                     if (prev) {
;                         const u32x4 w = *(const u32x4*)(tb + ro + bj * 8);
;                         r0 = (f32x4){bf_lo(w.x), bf_hi(w.x), bf_lo(w.y), bf_hi(w.y)}; r1 = (f32x4){bf_lo(w.z), bf_hi(w.z), bf_lo(w.w), bf_hi(w.w)};
;                         r0 = (r0 - mu) * rstd * gg[2 * bj] + bb[2 * bj]; r1 = (r1 - mu) * rstd * gg[2 * bj + 1] + bb[2 * bj + 1];
;                     } else { r0 = *(const f32x4*)(xin + ro + bj * 8); r1 = *(const f32x4*)(xin + ro + bj * 8 + 4); }
;                     const f32x4 t0 = r0 * ALPHA + acc[ai][bj][m][0], t1 = r1 * ALPHA + acc[ai][bj][m][1];
;                     if (xout != nullptr) { *(f32x4*)(xout + ro + bj * 8) = t0; *(f32x4*)(xout + ro + bj * 8 + 4) = t1; }
;                     const u32x4 pw = pack8(t0, t1);
;                     *(u32x4*)(tb + ro + bj * 8) = pw;
;                     const float a0 = bf_lo(pw.x), a1 = bf_hi(pw.x), a2 = bf_lo(pw.y), a3 = bf_hi(pw.y), a4 = bf_lo(pw.z), a5 = bf_hi(pw.z), a6 = bf_lo(pw.w), a7 = bf_hi(pw.w);
;                     s1 += ((a0 + a1) + (a2 + a3)) + ((a4 + a5) + (a6 + a7));
;                     s2 += ((a0 * a0 + a1 * a1) + (a2 * a2 + a3 * a3)) + ((a4 * a4 + a5 * a5) + (a6 * a6 + a7 * a7));
;                 }
;                 s1 += shflx(s1, 16, fr + 16 * fq); s1 += shflx(s1, 32, fr + 16 * fq); s2 += shflx(s2, 16, fr + 16 * fq); s2 += shflx(s2, 32, fr + 16 * fq);
;                 if (fq == 0) { float* sp = stats_out + ((size_t)row * 32 + u.pn * 4 + wc) * 2; sp[0] = s1; sp[1] = s2; }
	v_lshlrev_b64 v[102:103], 8, v[114:115]
	v_lshl_add_u64 v[102:103], s[10:11], 0, v[102:103]
	v_lshl_add_u64 v[102:103], s[24:25], 3, v[102:103]
	s_waitcnt lgkmcnt(0)
	v_pk_add_f32 v[98:99], v[98:99], v[100:101]
	global_store_dwordx2 v[102:103], v[98:99], off
.LBB0_137:
	s_or_b64 exec, exec, s[26:27]
	v_add_u32_e32 v98, 0x80, v184
	v_ashrrev_i32_e32 v99, 31, v98
	v_readlane_b32 s26, v251, 31
	s_waitcnt lgkmcnt(0)
	v_lshlrev_b64 v[100:101], 12, v[98:99]
	v_readlane_b32 s27, v251, 32
	ds_read_b64 v[108:109], v200 offset:1024
	s_nop 0
	v_lshl_add_u64 v[100:101], s[26:27], 0, v[100:101]
	v_lshl_add_u64 v[110:111], v[182:183], 1, v[100:101]
	s_waitcnt vmcnt(3) lgkmcnt(0)
	v_mov_b32_e32 v100, v244
	v_mov_b32_e32 v101, v245
	v_mov_b32_e32 v102, v246
	v_mov_b32_e32 v103, v247
	v_lshlrev_b32_e32 v104, 16, v100
	v_and_b32_e32 v100, 0xffff0000, v100
	v_lshlrev_b32_e32 v105, 16, v101
	v_and_b32_e32 v106, 0xffff0000, v101
	v_lshlrev_b32_e32 v107, 16, v102
	v_and_b32_e32 v112, 0xffff0000, v102
	v_lshlrev_b32_e32 v113, 16, v103
	v_and_b32_e32 v114, 0xffff0000, v103
	v_sub_f32_e32 v101, v100, v108
	v_sub_f32_e32 v100, v104, v108
	v_sub_f32_e32 v103, v106, v108
	v_sub_f32_e32 v102, v105, v108
	v_sub_f32_e32 v105, v112, v108
	v_sub_f32_e32 v104, v107, v108
	v_sub_f32_e32 v107, v114, v108
	v_sub_f32_e32 v106, v113, v108
	v_pk_mul_f32 v[100:101], v[108:109], v[100:101] op_sel:[1,0]
	v_pk_mul_f32 v[106:107], v[108:109], v[106:107] op_sel:[1,0]
	v_pk_mul_f32 v[104:105], v[108:109], v[104:105] op_sel:[1,0]
	v_pk_mul_f32 v[102:103], v[108:109], v[102:103] op_sel:[1,0]
	v_pk_fma_f32 v[100:101], v[54:55], v[100:101], v[50:51]
	v_pk_fma_f32 v[104:105], v[42:43], v[104:105], v[46:47]
	v_pk_fma_f32 v[106:107], v[44:45], v[106:107], v[48:49]
	v_pk_fma_f32 v[102:103], v[56:57], v[102:103], v[52:53]
	v_pk_fma_f32 v[94:95], v[100:101], s[72:73], v[94:95] op_sel_hi:[1,0,1]
	v_pk_fma_f32 v[100:101], v[106:107], s[72:73], v[92:93] op_sel_hi:[1,0,1]
	v_pk_fma_f32 v[92:93], v[104:105], s[72:73], v[90:91] op_sel_hi:[1,0,1]
	v_pk_fma_f32 v[96:97], v[102:103], s[72:73], v[96:97] op_sel_hi:[1,0,1]
	v_cvt_pk_bf16_f32 v90, v94, v95
	s_nop 0
	v_cvt_pk_bf16_f32 v91, v96, v97
	v_cvt_pk_bf16_f32 v92, v92, v93
	v_cvt_pk_bf16_f32 v93, v100, v101
	s_waitcnt vmcnt(2)
	v_mov_b32_e32 v104, v252
	v_mov_b32_e32 v105, v253
	v_mov_b32_e32 v106, v254
	v_mov_b32_e32 v107, v255
	v_add_u32_e32 v210, 0x10000, v210
	global_load_dwordx4 v[244:247], v210, s[26:27]
	global_load_dwordx4 v[252:255], v210, s[26:27] offset:16
	v_and_b32_e32 v102, 0xffff0000, v90
	global_store_dwordx4 v[110:111], v[90:93], off
	v_lshlrev_b32_e32 v100, 16, v91
	v_lshlrev_b32_e32 v94, 16, v93
	v_and_b32_e32 v96, 0xffff0000, v92
	s_waitcnt lgkmcnt(0)
	v_lshlrev_b32_e32 v95, 16, v104
	v_and_b32_e32 v97, 0xffff0000, v104
	v_lshlrev_b32_e32 v101, 16, v105
	v_and_b32_e32 v103, 0xffff0000, v105
	v_lshlrev_b32_e32 v112, 16, v106
	v_and_b32_e32 v113, 0xffff0000, v106
	v_lshlrev_b32_e32 v114, 16, v107
	v_and_b32_e32 v115, 0xffff0000, v107
	v_sub_f32_e32 v105, v97, v108
	v_sub_f32_e32 v104, v95, v108
	v_sub_f32_e32 v107, v103, v108
	v_sub_f32_e32 v106, v101, v108
	v_sub_f32_e32 v113, v113, v108
	v_sub_f32_e32 v112, v112, v108
	v_sub_f32_e32 v115, v115, v108
	v_sub_f32_e32 v114, v114, v108
	v_pk_mul_f32 v[106:107], v[108:109], v[106:107] op_sel:[1,0]
	v_pk_mul_f32 v[104:105], v[108:109], v[104:105] op_sel:[1,0]
	v_pk_mul_f32 v[114:115], v[108:109], v[114:115] op_sel:[1,0]
	v_pk_mul_f32 v[108:109], v[108:109], v[112:113] op_sel:[1,0]
	v_pk_fma_f32 v[104:105], v[26:27], v[104:105], v[30:31]
	v_pk_fma_f32 v[106:107], v[28:29], v[106:107], v[32:33]
	v_pk_fma_f32 v[108:109], v[18:19], v[108:109], v[22:23]
	v_pk_fma_f32 v[112:113], v[20:21], v[114:115], v[24:25]
	v_pk_fma_f32 v[88:89], v[106:107], s[72:73], v[88:89] op_sel_hi:[1,0,1]
	v_pk_fma_f32 v[86:87], v[104:105], s[72:73], v[86:87] op_sel_hi:[1,0,1]
	v_pk_fma_f32 v[104:105], v[112:113], s[72:73], v[84:85] op_sel_hi:[1,0,1]
	v_pk_fma_f32 v[84:85], v[108:109], s[72:73], v[82:83] op_sel_hi:[1,0,1]
	v_cvt_pk_bf16_f32 v82, v86, v87
	v_cvt_pk_bf16_f32 v83, v88, v89
	v_lshlrev_b32_e32 v106, 16, v90
	v_lshlrev_b32_e32 v107, 16, v82
	v_cvt_pk_bf16_f32 v84, v84, v85
	v_cvt_pk_bf16_f32 v85, v104, v105
	v_mov_b32_e32 v103, v107
	v_and_b32_e32 v105, 0xffff0000, v82
	v_pk_mul_f32 v[108:109], v[106:107], v[106:107]
	v_pk_mul_f32 v[114:115], v[102:103], v[102:103]
	v_and_b32_e32 v104, 0xffff0000, v91
	v_mov_b32_e32 v101, v105
	global_store_dwordx4 v[110:111], v[82:85], off offset:16
	v_pk_mul_f32 v[118:119], v[100:101], v[100:101]
	v_pk_mul_f32 v[90:91], v[104:105], v[104:105]
	v_lshlrev_b32_e32 v110, 16, v92
	v_lshlrev_b32_e32 v111, 16, v83
	v_and_b32_e32 v83, 0xffff0000, v83
	v_and_b32_e32 v82, 0xffff0000, v93
	v_pk_mov_b32 v[122:123], v[106:107], v[108:109] op_sel:[1,0]
	v_pk_mov_b32 v[114:115], v[104:105], v[114:115] op_sel:[1,0]
	v_and_b32_e32 v87, 0xffff0000, v85
	v_and_b32_e32 v86, 0xffff0000, v84
	v_mov_b32_e32 v95, v83
	v_pk_add_f32 v[114:115], v[122:123], v[114:115]
	v_pk_mov_b32 v[118:119], v[110:111], v[118:119] op_sel:[1,0]
	v_pk_mov_b32 v[122:123], v[82:83], v[90:91] op_sel:[1,0]
	v_lshlrev_b32_e32 v88, 16, v84
	v_lshlrev_b32_e32 v89, 16, v85
	v_pk_mul_f32 v[84:85], v[86:87], v[86:87]
	v_pk_mul_f32 v[92:93], v[94:95], v[94:95]
	v_pk_mul_f32 v[120:121], v[82:83], v[82:83]
	v_pk_add_f32 v[118:119], v[118:119], v[122:123]
	v_pk_fma_f32 v[84:85], v[88:89], v[88:89], v[84:85]
	v_mov_b32_e32 v97, v111
	v_pk_add_f32 v[114:115], v[114:115], v[118:119]
	v_mov_b32_e32 v118, v88
	v_mov_b32_e32 v122, v86
	v_pk_mov_b32 v[88:89], v[88:89], v[92:93] op_sel:[1,0]
	v_pk_mov_b32 v[86:87], v[86:87], v[120:121] op_sel:[1,0]
	v_pk_add_f32 v[92:93], v[104:105], v[100:101]
	v_pk_mul_f32 v[112:113], v[110:111], v[110:111]
	v_pk_mul_f32 v[116:117], v[96:97], v[96:97]
	v_pk_add_f32 v[86:87], v[88:89], v[86:87]
	v_pk_add_f32 v[88:89], v[106:107], v[102:103]
	v_mov_b32_e32 v93, v91
	v_pk_add_f32 v[90:91], v[110:111], v[96:97]
	v_pk_add_f32 v[82:83], v[82:83], v[94:95]
	v_mov_b32_e32 v119, v112
	v_mov_b32_e32 v123, v116
	v_mov_b32_e32 v89, v109
	v_mov_b32_e32 v91, v113
	v_mov_b32_e32 v83, v121
	v_pk_add_f32 v[84:85], v[84:85], v[84:85] op_sel_hi:[0,1]
	v_pk_add_f32 v[116:117], v[118:119], v[122:123]
	v_pk_add_f32 v[88:89], v[88:89], v[92:93]
	v_pk_add_f32 v[82:83], v[90:91], v[82:83]
	v_pk_add_f32 v[86:87], v[116:117], v[86:87]
	v_pk_add_f32 v[82:83], v[88:89], v[82:83]
	v_mov_b32_e32 v84, v1
	v_pk_add_f32 v[86:87], v[114:115], v[86:87]
	v_pk_add_f32 v[82:83], v[82:83], v[84:85]
	s_nop 0
	v_pk_add_f32 v[82:83], v[86:87], v[82:83]
	ds_bpermute_b32 v84, v194, v82
	ds_bpermute_b32 v85, v194, v83
	s_waitcnt lgkmcnt(0)
	v_pk_add_f32 v[82:83], v[82:83], v[84:85]
	ds_bpermute_b32 v84, v195, v82
	ds_bpermute_b32 v85, v195, v83
	s_and_saveexec_b64 s[26:27], s[42:43]
	s_cbranch_execz .LBB0_139
; __device__ __forceinline__ float bf_lo(unsigned w) { return __uint_as_float(w << 16); }
; __device__ __forceinline__ float bf_hi(unsigned w) { return __uint_as_float(w & 0xffff0000u); }
;     __device__ __forceinline__ void operator()(const f32x4 (&acc)[2][2][4][2], const pg8::Unit& u, int wr, int wc, int fr, int fq, LAS unsigned char* lds, int par) const {
;     ...
;                 const int row = row0 + ai * 128 + m * 16, lrow = ai * 128 + wr * 64 + m * 16 + fr;
;                 const size_t ro = (size_t)row * D + c0;
;                 float mu = 0.f, rstd = 1.f; if (prev) { mu = rsb[2 * lrow]; rstd = rsb[2 * lrow + 1]; }
;                 float s1 = 0.f, s2 = 0.f;
; #pragma unroll
;                 for (int bj = 0; bj < 2; ++bj) {
;                     f32x4 r0, r1;
;                     if (prev) {
;                         const u32x4 w = *(const u32x4*)(tb + ro + bj * 8);
;                         r0 = (f32x4){bf_lo(w.x), bf_hi(w.x), bf_lo(w.y), bf_hi(w.y)}; r1 = (f32x4){bf_lo(w.z), bf_hi(w.z), bf_lo(w.w), bf_hi(w.w)};
;                         r0 = (r0 - mu) * rstd * gg[2 * bj] + bb[2 * bj]; r1 = (r1 - mu) * rstd * gg[2 * bj + 1] + bb[2 * bj + 1];
;                     } else { r0 = *(const f32x4*)(xin + ro + bj * 8); r1 = *(const f32x4*)(xin + ro + bj * 8 + 4); }
;                     const f32x4 t0 = r0 * ALPHA + acc[ai][bj][m][0], t1 = r1 * ALPHA + acc[ai][bj][m][1];
;                     if (xout != nullptr) { *(f32x4*)(xout + ro + bj * 8) = t0; *(f32x4*)(xout + ro + bj * 8 + 4) = t1; }
;                     const u32x4 pw = pack8(t0, t1);
;                     *(u32x4*)(tb + ro + bj * 8) = pw;
;                     const float a0 = bf_lo(pw.x), a1 = bf_hi(pw.x), a2 = bf_lo(pw.y), a3 = bf_hi(pw.y), a4 = bf_lo(pw.z), a5 = bf_hi(pw.z), a6 = bf_lo(pw.w), a7 = bf_hi(pw.w);
;                     s1 += ((a0 + a1) + (a2 + a3)) + ((a4 + a5) + (a6 + a7));
;                     s2 += ((a0 * a0 + a1 * a1) + (a2 * a2 + a3 * a3)) + ((a4 * a4 + a5 * a5) + (a6 * a6 + a7 * a7));
;                 }
;                 s1 += shflx(s1, 16, fr + 16 * fq); s1 += shflx(s1, 32, fr + 16 * fq); s2 += shflx(s2, 16, fr + 16 * fq); s2 += shflx(s2, 32, fr + 16 * fq);
;                 if (fq == 0) { float* sp = stats_out + ((size_t)row * 32 + u.pn * 4 + wc) * 2; sp[0] = s1; sp[1] = s2; }
	v_lshlrev_b64 v[86:87], 8, v[98:99]
	v_lshl_add_u64 v[86:87], s[10:11], 0, v[86:87]
	v_lshl_add_u64 v[86:87], s[24:25], 3, v[86:87]
	s_waitcnt lgkmcnt(0)
	v_pk_add_f32 v[82:83], v[82:83], v[84:85]
	global_store_dwordx2 v[86:87], v[82:83], off
.LBB0_139:
	s_or_b64 exec, exec, s[26:27]
	v_add_u32_e32 v82, 0x90, v184
	v_ashrrev_i32_e32 v83, 31, v82
	v_readlane_b32 s26, v251, 31
	s_waitcnt lgkmcnt(0)
	v_lshlrev_b64 v[84:85], 12, v[82:83]
	v_readlane_b32 s27, v251, 32
	ds_read_b64 v[92:93], v200 offset:1152
	s_nop 0
	v_lshl_add_u64 v[84:85], s[26:27], 0, v[84:85]
	v_lshl_add_u64 v[94:95], v[182:183], 1, v[84:85]
	s_waitcnt vmcnt(3) lgkmcnt(0)
	v_mov_b32_e32 v84, v244
	v_mov_b32_e32 v85, v245
	v_mov_b32_e32 v86, v246
	v_mov_b32_e32 v87, v247
	v_lshlrev_b32_e32 v88, 16, v84
	v_and_b32_e32 v84, 0xffff0000, v84
	v_lshlrev_b32_e32 v89, 16, v85
	v_and_b32_e32 v90, 0xffff0000, v85
	v_lshlrev_b32_e32 v91, 16, v86
	v_and_b32_e32 v96, 0xffff0000, v86
	v_lshlrev_b32_e32 v97, 16, v87
	v_and_b32_e32 v98, 0xffff0000, v87
	v_sub_f32_e32 v85, v84, v92
	v_sub_f32_e32 v84, v88, v92
	v_sub_f32_e32 v87, v90, v92
	v_sub_f32_e32 v86, v89, v92
	v_sub_f32_e32 v89, v96, v92
	v_sub_f32_e32 v88, v91, v92
	v_sub_f32_e32 v91, v98, v92
	v_sub_f32_e32 v90, v97, v92
	v_pk_mul_f32 v[84:85], v[92:93], v[84:85] op_sel:[1,0]
	v_pk_mul_f32 v[90:91], v[92:93], v[90:91] op_sel:[1,0]
	v_pk_mul_f32 v[88:89], v[92:93], v[88:89] op_sel:[1,0]
	v_pk_mul_f32 v[86:87], v[92:93], v[86:87] op_sel:[1,0]
	v_pk_fma_f32 v[84:85], v[54:55], v[84:85], v[50:51]
	v_pk_fma_f32 v[88:89], v[42:43], v[88:89], v[46:47]
	v_pk_fma_f32 v[90:91], v[44:45], v[90:91], v[48:49]
	v_pk_fma_f32 v[86:87], v[56:57], v[86:87], v[52:53]
	v_pk_fma_f32 v[78:79], v[84:85], s[72:73], v[78:79] op_sel_hi:[1,0,1]
	v_pk_fma_f32 v[84:85], v[90:91], s[72:73], v[76:77] op_sel_hi:[1,0,1]
	v_pk_fma_f32 v[76:77], v[88:89], s[72:73], v[74:75] op_sel_hi:[1,0,1]
	v_pk_fma_f32 v[80:81], v[86:87], s[72:73], v[80:81] op_sel_hi:[1,0,1]
	v_cvt_pk_bf16_f32 v74, v78, v79
	s_nop 0
	v_cvt_pk_bf16_f32 v75, v80, v81
	v_cvt_pk_bf16_f32 v76, v76, v77
	v_cvt_pk_bf16_f32 v77, v84, v85
	s_waitcnt vmcnt(2)
	v_mov_b32_e32 v88, v252
	v_mov_b32_e32 v89, v253
	v_mov_b32_e32 v90, v254
	v_mov_b32_e32 v91, v255
	v_add_u32_e32 v210, 0x10000, v210
	global_load_dwordx4 v[244:247], v210, s[26:27]
	global_load_dwordx4 v[252:255], v210, s[26:27] offset:16
	v_and_b32_e32 v86, 0xffff0000, v74
	global_store_dwordx4 v[94:95], v[74:77], off
	v_lshlrev_b32_e32 v84, 16, v75
	v_lshlrev_b32_e32 v78, 16, v77
	v_and_b32_e32 v80, 0xffff0000, v76
	s_waitcnt lgkmcnt(0)
	v_lshlrev_b32_e32 v79, 16, v88
	v_and_b32_e32 v81, 0xffff0000, v88
	v_lshlrev_b32_e32 v85, 16, v89
	v_and_b32_e32 v87, 0xffff0000, v89
	v_lshlrev_b32_e32 v96, 16, v90
	v_and_b32_e32 v97, 0xffff0000, v90
	v_lshlrev_b32_e32 v98, 16, v91
	v_and_b32_e32 v99, 0xffff0000, v91
	v_sub_f32_e32 v89, v81, v92
	v_sub_f32_e32 v88, v79, v92
	v_sub_f32_e32 v91, v87, v92
	v_sub_f32_e32 v90, v85, v92
	v_sub_f32_e32 v97, v97, v92
	v_sub_f32_e32 v96, v96, v92
	v_sub_f32_e32 v99, v99, v92
	v_sub_f32_e32 v98, v98, v92
	v_pk_mul_f32 v[90:91], v[92:93], v[90:91] op_sel:[1,0]
	v_pk_mul_f32 v[88:89], v[92:93], v[88:89] op_sel:[1,0]
	v_pk_mul_f32 v[98:99], v[92:93], v[98:99] op_sel:[1,0]
	v_pk_mul_f32 v[92:93], v[92:93], v[96:97] op_sel:[1,0]
	v_pk_fma_f32 v[88:89], v[26:27], v[88:89], v[30:31]
	v_pk_fma_f32 v[90:91], v[28:29], v[90:91], v[32:33]
	v_pk_fma_f32 v[92:93], v[18:19], v[92:93], v[22:23]
	v_pk_fma_f32 v[96:97], v[20:21], v[98:99], v[24:25]
	v_pk_fma_f32 v[72:73], v[90:91], s[72:73], v[72:73] op_sel_hi:[1,0,1]
	v_pk_fma_f32 v[70:71], v[88:89], s[72:73], v[70:71] op_sel_hi:[1,0,1]
	v_pk_fma_f32 v[88:89], v[96:97], s[72:73], v[68:69] op_sel_hi:[1,0,1]
	v_pk_fma_f32 v[68:69], v[92:93], s[72:73], v[66:67] op_sel_hi:[1,0,1]
	v_cvt_pk_bf16_f32 v66, v70, v71
	v_cvt_pk_bf16_f32 v67, v72, v73
	v_lshlrev_b32_e32 v90, 16, v74
	v_lshlrev_b32_e32 v91, 16, v66
	v_cvt_pk_bf16_f32 v68, v68, v69
	v_cvt_pk_bf16_f32 v69, v88, v89
	v_mov_b32_e32 v87, v91
	v_and_b32_e32 v89, 0xffff0000, v66
	v_pk_mul_f32 v[92:93], v[90:91], v[90:91]
	v_pk_mul_f32 v[98:99], v[86:87], v[86:87]
	v_and_b32_e32 v88, 0xffff0000, v75
	v_mov_b32_e32 v85, v89
	global_store_dwordx4 v[94:95], v[66:69], off offset:16
	v_pk_mul_f32 v[102:103], v[84:85], v[84:85]
	v_pk_mul_f32 v[74:75], v[88:89], v[88:89]
	v_lshlrev_b32_e32 v94, 16, v76
	v_lshlrev_b32_e32 v95, 16, v67
	v_and_b32_e32 v67, 0xffff0000, v67
	v_and_b32_e32 v66, 0xffff0000, v77
	v_pk_mov_b32 v[106:107], v[90:91], v[92:93] op_sel:[1,0]
	v_pk_mov_b32 v[98:99], v[88:89], v[98:99] op_sel:[1,0]
	v_and_b32_e32 v71, 0xffff0000, v69
	v_and_b32_e32 v70, 0xffff0000, v68
	v_mov_b32_e32 v79, v67
	v_pk_add_f32 v[98:99], v[106:107], v[98:99]
	v_pk_mov_b32 v[102:103], v[94:95], v[102:103] op_sel:[1,0]
	v_pk_mov_b32 v[106:107], v[66:67], v[74:75] op_sel:[1,0]
	v_lshlrev_b32_e32 v72, 16, v68
	v_lshlrev_b32_e32 v73, 16, v69
	v_pk_mul_f32 v[68:69], v[70:71], v[70:71]
	v_pk_mul_f32 v[76:77], v[78:79], v[78:79]
	v_pk_mul_f32 v[104:105], v[66:67], v[66:67]
	v_pk_add_f32 v[102:103], v[102:103], v[106:107]
	v_pk_fma_f32 v[68:69], v[72:73], v[72:73], v[68:69]
	v_mov_b32_e32 v81, v95
	v_pk_add_f32 v[98:99], v[98:99], v[102:103]
	v_mov_b32_e32 v102, v72
	v_mov_b32_e32 v106, v70
	v_pk_mov_b32 v[72:73], v[72:73], v[76:77] op_sel:[1,0]
	v_pk_mov_b32 v[70:71], v[70:71], v[104:105] op_sel:[1,0]
	v_pk_add_f32 v[76:77], v[88:89], v[84:85]
	v_pk_mul_f32 v[96:97], v[94:95], v[94:95]
	v_pk_mul_f32 v[100:101], v[80:81], v[80:81]
	v_pk_add_f32 v[70:71], v[72:73], v[70:71]
	v_pk_add_f32 v[72:73], v[90:91], v[86:87]
	v_mov_b32_e32 v77, v75
	v_pk_add_f32 v[74:75], v[94:95], v[80:81]
	v_pk_add_f32 v[66:67], v[66:67], v[78:79]
	v_mov_b32_e32 v103, v96
	v_mov_b32_e32 v107, v100
	v_mov_b32_e32 v73, v93
	v_mov_b32_e32 v75, v97
	v_mov_b32_e32 v67, v105
	v_pk_add_f32 v[68:69], v[68:69], v[68:69] op_sel_hi:[0,1]
	v_pk_add_f32 v[100:101], v[102:103], v[106:107]
	v_pk_add_f32 v[72:73], v[72:73], v[76:77]
	v_pk_add_f32 v[66:67], v[74:75], v[66:67]
	v_pk_add_f32 v[70:71], v[100:101], v[70:71]
	v_pk_add_f32 v[66:67], v[72:73], v[66:67]
	v_mov_b32_e32 v68, v1
	v_pk_add_f32 v[70:71], v[98:99], v[70:71]
	v_pk_add_f32 v[66:67], v[66:67], v[68:69]
	s_nop 0
	v_pk_add_f32 v[66:67], v[70:71], v[66:67]
	ds_bpermute_b32 v68, v194, v66
	ds_bpermute_b32 v69, v194, v67
	s_waitcnt lgkmcnt(0)
	v_pk_add_f32 v[66:67], v[66:67], v[68:69]
	ds_bpermute_b32 v68, v195, v66
	ds_bpermute_b32 v69, v195, v67
	s_and_saveexec_b64 s[26:27], s[42:43]
	s_cbranch_execz .LBB0_141
	v_lshlrev_b64 v[70:71], 8, v[82:83]
	v_lshl_add_u64 v[70:71], s[10:11], 0, v[70:71]
	v_lshl_add_u64 v[70:71], s[24:25], 3, v[70:71]
	s_waitcnt lgkmcnt(0)
	v_pk_add_f32 v[66:67], v[66:67], v[68:69]
	global_store_dwordx2 v[70:71], v[66:67], off
; __device__ __forceinline__ float bf_lo(unsigned w) { return __uint_as_float(w << 16); }
; __device__ __forceinline__ float bf_hi(unsigned w) { return __uint_as_float(w & 0xffff0000u); }
;     __device__ __forceinline__ void operator()(const f32x4 (&acc)[2][2][4][2], const pg8::Unit& u, int wr, int wc, int fr, int fq, LAS unsigned char* lds, int par) const {
;     ...
;                 const int row = row0 + ai * 128 + m * 16, lrow = ai * 128 + wr * 64 + m * 16 + fr;
;                 const size_t ro = (size_t)row * D + c0;
;                 float mu = 0.f, rstd = 1.f; if (prev) { mu = rsb[2 * lrow]; rstd = rsb[2 * lrow + 1]; }
;                 float s1 = 0.f, s2 = 0.f;
; #pragma unroll
;                 for (int bj = 0; bj < 2; ++bj) {
;                     f32x4 r0, r1;
;                     if (prev) {
;                         const u32x4 w = *(const u32x4*)(tb + ro + bj * 8);
;                         r0 = (f32x4){bf_lo(w.x), bf_hi(w.x), bf_lo(w.y), bf_hi(w.y)}; r1 = (f32x4){bf_lo(w.z), bf_hi(w.z), bf_lo(w.w), bf_hi(w.w)};
;                         r0 = (r0 - mu) * rstd * gg[2 * bj] + bb[2 * bj]; r1 = (r1 - mu) * rstd * gg[2 * bj + 1] + bb[2 * bj + 1];
;                     } else { r0 = *(const f32x4*)(xin + ro + bj * 8); r1 = *(const f32x4*)(xin + ro + bj * 8 + 4); }
;                     const f32x4 t0 = r0 * ALPHA + acc[ai][bj][m][0], t1 = r1 * ALPHA + acc[ai][bj][m][1];
;                     if (xout != nullptr) { *(f32x4*)(xout + ro + bj * 8) = t0; *(f32x4*)(xout + ro + bj * 8 + 4) = t1; }
;                     const u32x4 pw = pack8(t0, t1);
;                     *(u32x4*)(tb + ro + bj * 8) = pw;
;                     const float a0 = bf_lo(pw.x), a1 = bf_hi(pw.x), a2 = bf_lo(pw.y), a3 = bf_hi(pw.y), a4 = bf_lo(pw.z), a5 = bf_hi(pw.z), a6 = bf_lo(pw.w), a7 = bf_hi(pw.w);
;                     s1 += ((a0 + a1) + (a2 + a3)) + ((a4 + a5) + (a6 + a7));
;                     s2 += ((a0 * a0 + a1 * a1) + (a2 * a2 + a3 * a3)) + ((a4 * a4 + a5 * a5) + (a6 * a6 + a7 * a7));
;                 }
;                 s1 += shflx(s1, 16, fr + 16 * fq); s1 += shflx(s1, 32, fr + 16 * fq); s2 += shflx(s2, 16, fr + 16 * fq); s2 += shflx(s2, 32, fr + 16 * fq);
;                 if (fq == 0) { float* sp = stats_out + ((size_t)row * 32 + u.pn * 4 + wc) * 2; sp[0] = s1; sp[1] = s2; }
.LBB0_141:
	s_or_b64 exec, exec, s[26:27]
	v_add_u32_e32 v66, 0xa0, v184
	v_ashrrev_i32_e32 v67, 31, v66
	v_readlane_b32 s26, v251, 31
	s_waitcnt lgkmcnt(0)
	v_lshlrev_b64 v[68:69], 12, v[66:67]
	v_readlane_b32 s27, v251, 32
	ds_read_b64 v[76:77], v200 offset:1280
	s_nop 0
	v_lshl_add_u64 v[68:69], s[26:27], 0, v[68:69]
	v_lshl_add_u64 v[78:79], v[182:183], 1, v[68:69]
	s_waitcnt vmcnt(3) lgkmcnt(0)
	v_mov_b32_e32 v68, v244
	v_mov_b32_e32 v69, v245
	v_mov_b32_e32 v70, v246
	v_mov_b32_e32 v71, v247
	v_lshlrev_b32_e32 v72, 16, v68
	v_and_b32_e32 v68, 0xffff0000, v68
	v_lshlrev_b32_e32 v73, 16, v69
	v_and_b32_e32 v74, 0xffff0000, v69
	v_lshlrev_b32_e32 v75, 16, v70
	v_and_b32_e32 v80, 0xffff0000, v70
	v_lshlrev_b32_e32 v81, 16, v71
	v_and_b32_e32 v82, 0xffff0000, v71
	v_sub_f32_e32 v69, v68, v76
	v_sub_f32_e32 v68, v72, v76
	v_sub_f32_e32 v71, v74, v76
	v_sub_f32_e32 v70, v73, v76
	v_sub_f32_e32 v73, v80, v76
	v_sub_f32_e32 v72, v75, v76
	v_sub_f32_e32 v75, v82, v76
	v_sub_f32_e32 v74, v81, v76
	v_pk_mul_f32 v[68:69], v[76:77], v[68:69] op_sel:[1,0]
	v_pk_mul_f32 v[74:75], v[76:77], v[74:75] op_sel:[1,0]
	v_pk_mul_f32 v[72:73], v[76:77], v[72:73] op_sel:[1,0]
	v_pk_mul_f32 v[70:71], v[76:77], v[70:71] op_sel:[1,0]
	v_pk_fma_f32 v[68:69], v[54:55], v[68:69], v[50:51]
	v_pk_fma_f32 v[72:73], v[42:43], v[72:73], v[46:47]
	v_pk_fma_f32 v[74:75], v[44:45], v[74:75], v[48:49]
	v_pk_fma_f32 v[70:71], v[56:57], v[70:71], v[52:53]
	v_pk_fma_f32 v[62:63], v[68:69], s[72:73], v[62:63] op_sel_hi:[1,0,1]
	v_pk_fma_f32 v[68:69], v[74:75], s[72:73], v[60:61] op_sel_hi:[1,0,1]
	v_pk_fma_f32 v[60:61], v[72:73], s[72:73], v[58:59] op_sel_hi:[1,0,1]
	v_pk_fma_f32 v[64:65], v[70:71], s[72:73], v[64:65] op_sel_hi:[1,0,1]
	v_cvt_pk_bf16_f32 v58, v62, v63
	s_nop 0
	v_cvt_pk_bf16_f32 v59, v64, v65
	v_cvt_pk_bf16_f32 v60, v60, v61
	v_cvt_pk_bf16_f32 v61, v68, v69
	s_waitcnt vmcnt(2)
	v_mov_b32_e32 v72, v252
	v_mov_b32_e32 v73, v253
	v_mov_b32_e32 v74, v254
	v_mov_b32_e32 v75, v255
	v_add_u32_e32 v210, 0x10000, v210
	global_load_dwordx4 v[244:247], v210, s[26:27]
	global_load_dwordx4 v[252:255], v210, s[26:27] offset:16
	v_and_b32_e32 v70, 0xffff0000, v58
	global_store_dwordx4 v[78:79], v[58:61], off
	v_lshlrev_b32_e32 v68, 16, v59
	v_lshlrev_b32_e32 v62, 16, v61
	v_and_b32_e32 v64, 0xffff0000, v60
	s_waitcnt lgkmcnt(0)
	v_lshlrev_b32_e32 v63, 16, v72
	v_and_b32_e32 v65, 0xffff0000, v72
	v_lshlrev_b32_e32 v69, 16, v73
	v_and_b32_e32 v71, 0xffff0000, v73
	v_lshlrev_b32_e32 v80, 16, v74
	v_and_b32_e32 v81, 0xffff0000, v74
	v_lshlrev_b32_e32 v82, 16, v75
	v_and_b32_e32 v83, 0xffff0000, v75
	v_sub_f32_e32 v73, v65, v76
	v_sub_f32_e32 v72, v63, v76
	v_sub_f32_e32 v75, v71, v76
	v_sub_f32_e32 v74, v69, v76
	v_sub_f32_e32 v81, v81, v76
	v_sub_f32_e32 v80, v80, v76
	v_sub_f32_e32 v83, v83, v76
	v_sub_f32_e32 v82, v82, v76
	v_pk_mul_f32 v[74:75], v[76:77], v[74:75] op_sel:[1,0]
	v_pk_mul_f32 v[72:73], v[76:77], v[72:73] op_sel:[1,0]
	v_pk_mul_f32 v[82:83], v[76:77], v[82:83] op_sel:[1,0]
	v_pk_mul_f32 v[76:77], v[76:77], v[80:81] op_sel:[1,0]
	v_pk_fma_f32 v[72:73], v[26:27], v[72:73], v[30:31]
	v_pk_fma_f32 v[74:75], v[28:29], v[74:75], v[32:33]
	v_pk_fma_f32 v[76:77], v[18:19], v[76:77], v[22:23]
	v_pk_fma_f32 v[80:81], v[20:21], v[82:83], v[24:25]
	v_pk_fma_f32 v[40:41], v[74:75], s[72:73], v[40:41] op_sel_hi:[1,0,1]
	v_pk_fma_f32 v[38:39], v[72:73], s[72:73], v[38:39] op_sel_hi:[1,0,1]
	v_pk_fma_f32 v[72:73], v[80:81], s[72:73], v[36:37] op_sel_hi:[1,0,1]
	v_pk_fma_f32 v[36:37], v[76:77], s[72:73], v[34:35] op_sel_hi:[1,0,1]
	v_cvt_pk_bf16_f32 v34, v38, v39
	v_cvt_pk_bf16_f32 v35, v40, v41
	v_lshlrev_b32_e32 v74, 16, v58
	v_lshlrev_b32_e32 v75, 16, v34
	v_cvt_pk_bf16_f32 v36, v36, v37
	v_cvt_pk_bf16_f32 v37, v72, v73
	v_mov_b32_e32 v71, v75
	v_and_b32_e32 v73, 0xffff0000, v34
	v_pk_mul_f32 v[76:77], v[74:75], v[74:75]
	v_pk_mul_f32 v[82:83], v[70:71], v[70:71]
	v_and_b32_e32 v72, 0xffff0000, v59
	v_mov_b32_e32 v69, v73
	global_store_dwordx4 v[78:79], v[34:37], off offset:16
	v_pk_mul_f32 v[86:87], v[68:69], v[68:69]
	v_pk_mul_f32 v[58:59], v[72:73], v[72:73]
	v_lshlrev_b32_e32 v78, 16, v60
	v_lshlrev_b32_e32 v79, 16, v35
	v_and_b32_e32 v35, 0xffff0000, v35
	v_and_b32_e32 v34, 0xffff0000, v61
	v_pk_mov_b32 v[90:91], v[74:75], v[76:77] op_sel:[1,0]
	v_pk_mov_b32 v[82:83], v[72:73], v[82:83] op_sel:[1,0]
	v_and_b32_e32 v39, 0xffff0000, v37
	v_and_b32_e32 v38, 0xffff0000, v36
	v_mov_b32_e32 v63, v35
	v_pk_add_f32 v[82:83], v[90:91], v[82:83]
	v_pk_mov_b32 v[86:87], v[78:79], v[86:87] op_sel:[1,0]
	v_pk_mov_b32 v[90:91], v[34:35], v[58:59] op_sel:[1,0]
	v_lshlrev_b32_e32 v40, 16, v36
	v_lshlrev_b32_e32 v41, 16, v37
	v_pk_mul_f32 v[36:37], v[38:39], v[38:39]
	v_pk_mul_f32 v[60:61], v[62:63], v[62:63]
	v_pk_mul_f32 v[88:89], v[34:35], v[34:35]
	v_pk_add_f32 v[86:87], v[86:87], v[90:91]
	v_pk_fma_f32 v[36:37], v[40:41], v[40:41], v[36:37]
	v_mov_b32_e32 v65, v79
	v_pk_add_f32 v[82:83], v[82:83], v[86:87]
	v_mov_b32_e32 v86, v40
	v_mov_b32_e32 v90, v38
	v_pk_mov_b32 v[40:41], v[40:41], v[60:61] op_sel:[1,0]
	v_pk_mov_b32 v[38:39], v[38:39], v[88:89] op_sel:[1,0]
	v_pk_add_f32 v[60:61], v[72:73], v[68:69]
	v_pk_mul_f32 v[80:81], v[78:79], v[78:79]
	v_pk_mul_f32 v[84:85], v[64:65], v[64:65]
	v_pk_add_f32 v[38:39], v[40:41], v[38:39]
	v_pk_add_f32 v[40:41], v[74:75], v[70:71]
	v_mov_b32_e32 v61, v59
	v_pk_add_f32 v[58:59], v[78:79], v[64:65]
	v_pk_add_f32 v[34:35], v[34:35], v[62:63]
	v_mov_b32_e32 v87, v80
	v_mov_b32_e32 v91, v84
	v_mov_b32_e32 v41, v77
	v_mov_b32_e32 v59, v81
	v_mov_b32_e32 v35, v89
	v_pk_add_f32 v[36:37], v[36:37], v[36:37] op_sel_hi:[0,1]
	v_pk_add_f32 v[84:85], v[86:87], v[90:91]
	v_pk_add_f32 v[40:41], v[40:41], v[60:61]
	v_pk_add_f32 v[34:35], v[58:59], v[34:35]
	v_pk_add_f32 v[38:39], v[84:85], v[38:39]
	v_pk_add_f32 v[34:35], v[40:41], v[34:35]
	v_mov_b32_e32 v36, v1
	v_pk_add_f32 v[38:39], v[82:83], v[38:39]
	v_pk_add_f32 v[34:35], v[34:35], v[36:37]
	s_nop 0
	v_pk_add_f32 v[34:35], v[38:39], v[34:35]
	ds_bpermute_b32 v36, v194, v34
	ds_bpermute_b32 v37, v194, v35
	s_waitcnt lgkmcnt(0)
	v_pk_add_f32 v[34:35], v[34:35], v[36:37]
	ds_bpermute_b32 v36, v195, v34
	ds_bpermute_b32 v37, v195, v35
	s_and_saveexec_b64 s[26:27], s[42:43]
	s_cbranch_execz .LBB0_143
	v_lshlrev_b64 v[38:39], 8, v[66:67]
	v_lshl_add_u64 v[38:39], s[10:11], 0, v[38:39]
	v_lshl_add_u64 v[38:39], s[24:25], 3, v[38:39]
	s_waitcnt lgkmcnt(0)
	v_pk_add_f32 v[34:35], v[34:35], v[36:37]
	global_store_dwordx2 v[38:39], v[34:35], off
; __device__ __forceinline__ float bf_lo(unsigned w) { return __uint_as_float(w << 16); }
; __device__ __forceinline__ float bf_hi(unsigned w) { return __uint_as_float(w & 0xffff0000u); }
;     __device__ __forceinline__ void operator()(const f32x4 (&acc)[2][2][4][2], const pg8::Unit& u, int wr, int wc, int fr, int fq, LAS unsigned char* lds, int par) const {
;     ...
;                 const int row = row0 + ai * 128 + m * 16, lrow = ai * 128 + wr * 64 + m * 16 + fr;
;                 const size_t ro = (size_t)row * D + c0;
;                 float mu = 0.f, rstd = 1.f; if (prev) { mu = rsb[2 * lrow]; rstd = rsb[2 * lrow + 1]; }
;                 float s1 = 0.f, s2 = 0.f;
; #pragma unroll
;                 for (int bj = 0; bj < 2; ++bj) {
;                     f32x4 r0, r1;
;                     if (prev) {
;                         const u32x4 w = *(const u32x4*)(tb + ro + bj * 8);
;                         r0 = (f32x4){bf_lo(w.x), bf_hi(w.x), bf_lo(w.y), bf_hi(w.y)}; r1 = (f32x4){bf_lo(w.z), bf_hi(w.z), bf_lo(w.w), bf_hi(w.w)};
;                         r0 = (r0 - mu) * rstd * gg[2 * bj] + bb[2 * bj]; r1 = (r1 - mu) * rstd * gg[2 * bj + 1] + bb[2 * bj + 1];
;                     } else { r0 = *(const f32x4*)(xin + ro + bj * 8); r1 = *(const f32x4*)(xin + ro + bj * 8 + 4); }
;                     const f32x4 t0 = r0 * ALPHA + acc[ai][bj][m][0], t1 = r1 * ALPHA + acc[ai][bj][m][1];
;                     if (xout != nullptr) { *(f32x4*)(xout + ro + bj * 8) = t0; *(f32x4*)(xout + ro + bj * 8 + 4) = t1; }
;                     const u32x4 pw = pack8(t0, t1);
;                     *(u32x4*)(tb + ro + bj * 8) = pw;
;                     const float a0 = bf_lo(pw.x), a1 = bf_hi(pw.x), a2 = bf_lo(pw.y), a3 = bf_hi(pw.y), a4 = bf_lo(pw.z), a5 = bf_hi(pw.z), a6 = bf_lo(pw.w), a7 = bf_hi(pw.w);
;                     s1 += ((a0 + a1) + (a2 + a3)) + ((a4 + a5) + (a6 + a7));
;                     s2 += ((a0 * a0 + a1 * a1) + (a2 * a2 + a3 * a3)) + ((a4 * a4 + a5 * a5) + (a6 * a6 + a7 * a7));
;                 }
;                 s1 += shflx(s1, 16, fr + 16 * fq); s1 += shflx(s1, 32, fr + 16 * fq); s2 += shflx(s2, 16, fr + 16 * fq); s2 += shflx(s2, 32, fr + 16 * fq);
;                 if (fq == 0) { float* sp = stats_out + ((size_t)row * 32 + u.pn * 4 + wc) * 2; sp[0] = s1; sp[1] = s2; }
.LBB0_143:
	s_or_b64 exec, exec, s[26:27]
	v_add_u32_e32 v34, 0xb0, v184
	v_ashrrev_i32_e32 v35, 31, v34
	v_readlane_b32 s26, v251, 31
	s_waitcnt lgkmcnt(0)
	v_lshlrev_b64 v[36:37], 12, v[34:35]
	v_readlane_b32 s27, v251, 32
	ds_read_b64 v[58:59], v200 offset:1408
	s_nop 0
	v_lshl_add_u64 v[36:37], s[26:27], 0, v[36:37]
	v_lshl_add_u64 v[60:61], v[182:183], 1, v[36:37]
	s_waitcnt vmcnt(3) lgkmcnt(0)
	v_mov_b32_e32 v36, v244
	v_mov_b32_e32 v37, v245
	v_mov_b32_e32 v38, v246
	v_mov_b32_e32 v39, v247
	v_lshlrev_b32_e32 v40, 16, v36
	v_and_b32_e32 v36, 0xffff0000, v36
	v_lshlrev_b32_e32 v41, 16, v37
	v_and_b32_e32 v62, 0xffff0000, v37
	v_sub_f32_e32 v37, v36, v58
	v_sub_f32_e32 v36, v40, v58
	v_lshlrev_b32_e32 v63, 16, v38
	v_and_b32_e32 v64, 0xffff0000, v38
	v_lshlrev_b32_e32 v65, 16, v39
	v_and_b32_e32 v66, 0xffff0000, v39
	v_pk_mul_f32 v[36:37], v[58:59], v[36:37] op_sel:[1,0]
	v_sub_f32_e32 v38, v41, v58
	v_pk_fma_f32 v[36:37], v[54:55], v[36:37], v[50:51]
	v_sub_f32_e32 v41, v64, v58
	v_sub_f32_e32 v40, v63, v58
	v_sub_f32_e32 v51, v66, v58
	v_sub_f32_e32 v50, v65, v58
	v_sub_f32_e32 v39, v62, v58
	v_pk_mul_f32 v[50:51], v[58:59], v[50:51] op_sel:[1,0]
	v_pk_mul_f32 v[40:41], v[58:59], v[40:41] op_sel:[1,0]
	v_pk_mul_f32 v[38:39], v[58:59], v[38:39] op_sel:[1,0]
	v_pk_fma_f32 v[40:41], v[42:43], v[40:41], v[46:47]
	v_pk_fma_f32 v[42:43], v[44:45], v[50:51], v[48:49]
	v_pk_fma_f32 v[38:39], v[56:57], v[38:39], v[52:53]
	v_pk_fma_f32 v[14:15], v[36:37], s[72:73], v[14:15] op_sel_hi:[1,0,1]
	v_pk_fma_f32 v[36:37], v[42:43], s[72:73], v[12:13] op_sel_hi:[1,0,1]
	v_pk_fma_f32 v[12:13], v[40:41], s[72:73], v[10:11] op_sel_hi:[1,0,1]
	v_pk_fma_f32 v[16:17], v[38:39], s[72:73], v[16:17] op_sel_hi:[1,0,1]
	v_cvt_pk_bf16_f32 v10, v14, v15
	s_nop 0
	v_cvt_pk_bf16_f32 v11, v16, v17
	v_cvt_pk_bf16_f32 v12, v12, v13
	v_cvt_pk_bf16_f32 v13, v36, v37
	s_waitcnt vmcnt(2)
	v_mov_b32_e32 v40, v252
	v_mov_b32_e32 v41, v253
	v_mov_b32_e32 v42, v254
	v_mov_b32_e32 v43, v255
	v_and_b32_e32 v38, 0xffff0000, v10
	global_store_dwordx4 v[60:61], v[10:13], off
	v_lshlrev_b32_e32 v36, 16, v11
	v_lshlrev_b32_e32 v14, 16, v13
	v_and_b32_e32 v16, 0xffff0000, v12
	s_waitcnt lgkmcnt(0)
	v_lshlrev_b32_e32 v15, 16, v40
	v_and_b32_e32 v17, 0xffff0000, v40
	v_lshlrev_b32_e32 v37, 16, v41
	v_and_b32_e32 v39, 0xffff0000, v41
	v_lshlrev_b32_e32 v44, 16, v42
	v_and_b32_e32 v45, 0xffff0000, v42
	v_lshlrev_b32_e32 v46, 16, v43
	v_and_b32_e32 v47, 0xffff0000, v43
	v_sub_f32_e32 v41, v17, v58
	v_sub_f32_e32 v40, v15, v58
	v_sub_f32_e32 v43, v39, v58
	v_sub_f32_e32 v42, v37, v58
	v_pk_mul_f32 v[42:43], v[58:59], v[42:43] op_sel:[1,0]
	v_pk_mul_f32 v[40:41], v[58:59], v[40:41] op_sel:[1,0]
	v_pk_fma_f32 v[28:29], v[28:29], v[42:43], v[32:33]
	v_pk_fma_f32 v[26:27], v[26:27], v[40:41], v[30:31]
	v_sub_f32_e32 v31, v45, v58
	v_sub_f32_e32 v30, v44, v58
	v_sub_f32_e32 v33, v47, v58
	v_sub_f32_e32 v32, v46, v58
	v_pk_mul_f32 v[32:33], v[58:59], v[32:33] op_sel:[1,0]
	v_pk_mul_f32 v[30:31], v[58:59], v[30:31] op_sel:[1,0]
	v_pk_fma_f32 v[20:21], v[20:21], v[32:33], v[24:25]
	v_pk_fma_f32 v[18:19], v[18:19], v[30:31], v[22:23]
	v_pk_fma_f32 v[20:21], v[20:21], s[72:73], v[4:5] op_sel_hi:[1,0,1]
	v_pk_fma_f32 v[4:5], v[18:19], s[72:73], v[2:3] op_sel_hi:[1,0,1]
	v_pk_fma_f32 v[8:9], v[28:29], s[72:73], v[8:9] op_sel_hi:[1,0,1]
	v_pk_fma_f32 v[6:7], v[26:27], s[72:73], v[6:7] op_sel_hi:[1,0,1]
	v_and_b32_e32 v18, 0xffff0000, v11
	v_cvt_pk_bf16_f32 v2, v6, v7
	v_cvt_pk_bf16_f32 v3, v8, v9
	v_cvt_pk_bf16_f32 v4, v4, v5
	v_cvt_pk_bf16_f32 v5, v20, v21
	v_lshlrev_b32_e32 v20, 16, v10
	v_lshlrev_b32_e32 v21, 16, v2
	v_mov_b32_e32 v39, v21
	v_and_b32_e32 v19, 0xffff0000, v2
	v_pk_mul_f32 v[22:23], v[20:21], v[20:21]
	v_pk_mul_f32 v[28:29], v[38:39], v[38:39]
	v_mov_b32_e32 v37, v19
	global_store_dwordx4 v[60:61], v[2:5], off offset:16
	v_pk_mul_f32 v[32:33], v[36:37], v[36:37]
	v_pk_mul_f32 v[10:11], v[18:19], v[18:19]
	v_lshlrev_b32_e32 v24, 16, v12
	v_lshlrev_b32_e32 v25, 16, v3
	v_and_b32_e32 v3, 0xffff0000, v3
	v_and_b32_e32 v2, 0xffff0000, v13
	v_pk_mov_b32 v[42:43], v[20:21], v[22:23] op_sel:[1,0]
	v_pk_mov_b32 v[28:29], v[18:19], v[28:29] op_sel:[1,0]
	v_and_b32_e32 v7, 0xffff0000, v5
	v_and_b32_e32 v6, 0xffff0000, v4
	v_mov_b32_e32 v15, v3
	v_pk_add_f32 v[28:29], v[42:43], v[28:29]
	v_pk_mov_b32 v[32:33], v[24:25], v[32:33] op_sel:[1,0]
	v_pk_mov_b32 v[42:43], v[2:3], v[10:11] op_sel:[1,0]
	v_lshlrev_b32_e32 v8, 16, v4
	v_lshlrev_b32_e32 v9, 16, v5
	v_pk_mul_f32 v[4:5], v[6:7], v[6:7]
	v_pk_mul_f32 v[12:13], v[14:15], v[14:15]
	v_pk_mul_f32 v[40:41], v[2:3], v[2:3]
	v_pk_add_f32 v[32:33], v[32:33], v[42:43]
	v_pk_fma_f32 v[4:5], v[8:9], v[8:9], v[4:5]
	v_mov_b32_e32 v17, v25
	v_pk_add_f32 v[28:29], v[28:29], v[32:33]
	v_mov_b32_e32 v32, v8
	v_mov_b32_e32 v42, v6
	v_pk_mov_b32 v[8:9], v[8:9], v[12:13] op_sel:[1,0]
	v_pk_mov_b32 v[6:7], v[6:7], v[40:41] op_sel:[1,0]
	v_pk_add_f32 v[12:13], v[18:19], v[36:37]
	v_pk_mul_f32 v[26:27], v[24:25], v[24:25]
	v_pk_mul_f32 v[30:31], v[16:17], v[16:17]
	v_pk_add_f32 v[6:7], v[8:9], v[6:7]
	v_pk_add_f32 v[8:9], v[20:21], v[38:39]
	v_mov_b32_e32 v13, v11
	v_pk_add_f32 v[10:11], v[24:25], v[16:17]
	v_pk_add_f32 v[2:3], v[2:3], v[14:15]
	v_mov_b32_e32 v33, v26
	v_mov_b32_e32 v43, v30
	v_mov_b32_e32 v9, v23
	v_mov_b32_e32 v11, v27
	v_mov_b32_e32 v3, v41
	v_pk_add_f32 v[4:5], v[4:5], v[4:5] op_sel_hi:[0,1]
	v_pk_add_f32 v[30:31], v[32:33], v[42:43]
	v_pk_add_f32 v[8:9], v[8:9], v[12:13]
	v_pk_add_f32 v[2:3], v[10:11], v[2:3]
	v_pk_add_f32 v[6:7], v[30:31], v[6:7]
	v_pk_add_f32 v[2:3], v[8:9], v[2:3]
	v_mov_b32_e32 v4, v1
	v_pk_add_f32 v[6:7], v[28:29], v[6:7]
	v_pk_add_f32 v[2:3], v[2:3], v[4:5]
	s_nop 0
	v_pk_add_f32 v[2:3], v[6:7], v[2:3]
	ds_bpermute_b32 v4, v194, v2
	ds_bpermute_b32 v5, v194, v3
	s_waitcnt lgkmcnt(0)
	v_pk_add_f32 v[2:3], v[2:3], v[4:5]
	ds_bpermute_b32 v4, v195, v2
	ds_bpermute_b32 v5, v195, v3
	s_and_saveexec_b64 s[26:27], s[42:43]
	s_cbranch_execz .LBB0_145
	v_lshlrev_b64 v[6:7], 8, v[34:35]
	v_lshl_add_u64 v[6:7], s[10:11], 0, v[6:7]
	v_lshl_add_u64 v[6:7], s[24:25], 3, v[6:7]
	s_waitcnt lgkmcnt(0)
	v_pk_add_f32 v[2:3], v[2:3], v[4:5]
	global_store_dwordx2 v[6:7], v[2:3], off

; __device__ __forceinline__ float bf_lo(unsigned w) { return __uint_as_float(w << 16); }
; __device__ __forceinline__ float bf_hi(unsigned w) { return __uint_as_float(w & 0xffff0000u); }
; __device__ __forceinline__ u32x4 pack8(const f32x4 a, const f32x4 b) { u32x4 w; w.x = cvt_pk_bf16(a[0], a[1]); w.y = cvt_pk_bf16(a[2], a[3]); w.z = cvt_pk_bf16(b[0], b[1]); w.w = cvt_pk_bf16(b[2], b[3]); return w; }
;     __device__ __forceinline__ void operator()(const f32x4 (&acc)[2][2][4][2], const pg8::Unit& u, int wr, int wc, int fr, int fq, LAS unsigned char* lds, int par) const {
;     ...
;         const int row0 = u.pm * 256 + wr * 64 + fr, c0 = u.pn * 256 + wc * 64 + 16 * fq;
;         f32x4 gg[4], bb[4];
;         if (prev) {
; #pragma unroll
;             for (int i = 0; i < 4; ++i) { gg[i] = *(const f32x4*)(pg + c0 + 4 * i); bb[i] = *(const f32x4*)(pb + c0 + 4 * i); }
;         }
; #pragma unroll
;         for (int ai = 0; ai < 2; ++ai)
; #pragma unroll
;             for (int m = 0; m < 4; ++m) {
;                 const int row = row0 + ai * 128 + m * 16, lrow = ai * 128 + wr * 64 + m * 16 + fr;
;                 const size_t ro = (size_t)row * D + c0;
;                 float mu = 0.f, rstd = 1.f; if (prev) { mu = rsb[2 * lrow]; rstd = rsb[2 * lrow + 1]; }
;                 float s1 = 0.f, s2 = 0.f;
; #pragma unroll
;                 for (int bj = 0; bj < 2; ++bj) {
;                     f32x4 r0, r1;
;                     if (prev) {
;                         const u32x4 w = *(const u32x4*)(tb + ro + bj * 8);
;                         r0 = (f32x4){bf_lo(w.x), bf_hi(w.x), bf_lo(w.y), bf_hi(w.y)}; r1 = (f32x4){bf_lo(w.z), bf_hi(w.z), bf_lo(w.w), bf_hi(w.w)};
;                         r0 = (r0 - mu) * rstd * gg[2 * bj] + bb[2 * bj]; r1 = (r1 - mu) * rstd * gg[2 * bj + 1] + bb[2 * bj + 1];
;                     } else { r0 = *(const f32x4*)(xin + ro + bj * 8); r1 = *(const f32x4*)(xin + ro + bj * 8 + 4); }
;                     const f32x4 t0 = r0 * ALPHA + acc[ai][bj][m][0], t1 = r1 * ALPHA + acc[ai][bj][m][1];
;                     if (xout != nullptr) { *(f32x4*)(xout + ro + bj * 8) = t0; *(f32x4*)(xout + ro + bj * 8 + 4) = t1; }
;                     const u32x4 pw = pack8(t0, t1);
;                     *(u32x4*)(tb + ro + bj * 8) = pw;
.LBB0_209:
	v_lshl_add_u32 v184, s26, 8, v192
	v_ashrrev_i32_e32 v185, 31, v184
	v_readlane_b32 s26, v251, 31
	v_lshl_or_b32 v182, s24, 8, v198
	v_lshlrev_b64 v[18:19], 12, v[184:185]
	v_readlane_b32 s27, v251, 32
	v_ashrrev_i32_e32 v183, 31, v182
	s_lshl_b32 s15, s25, 11
	v_lshl_add_u64 v[18:19], s[26:27], 0, v[18:19]
	v_lshl_add_u64 v[186:187], v[182:183], 1, v[18:19]
	s_nop 1
	v_lshlrev_b32_e32 v210, 12, v184
	v_lshl_add_u32 v210, v182, 1, v210
	global_load_dwordx4 v[244:247], v210, s[26:27]
	global_load_dwordx4 v[252:255], v210, s[26:27] offset:16
	v_lshlrev_b64 v[18:19], 2, v[182:183]
	v_lshl_add_u64 v[30:31], s[6:7], 0, v[18:19]
	v_lshl_add_u64 v[22:23], s[4:5], 0, v[18:19]
	global_load_dwordx4 v[50:53], v[30:31], off
	global_load_dwordx4 v[54:57], v[22:23], off
	global_load_dwordx4 v[42:45], v[22:23], off offset:16
	global_load_dwordx4 v[46:49], v[30:31], off offset:16
	s_and_b32 s15, s15, 0x800
	v_add_u32_e32 v200, s15, v197
	ds_read_b64 v[172:173], v200
	global_load_dwordx4 v[18:21], v[22:23], off offset:48
	global_load_dwordx4 v[26:29], v[22:23], off offset:32
	s_nop 0
	global_load_dwordx4 v[22:25], v[30:31], off offset:48
	s_nop 0
	global_load_dwordx4 v[30:33], v[30:31], off offset:32
	s_lshl_b32 s24, s24, 2
	s_ashr_i32 s25, s24, 31
	s_or_b64 s[24:25], s[24:25], s[2:3]
	s_waitcnt vmcnt(0) lgkmcnt(0)
	v_mov_b32_e32 v212, v244
	v_mov_b32_e32 v213, v245
	v_mov_b32_e32 v214, v246
	v_mov_b32_e32 v215, v247
	v_lshlrev_b32_e32 v174, 16, v212
	v_and_b32_e32 v175, 0xffff0000, v212
	v_lshlrev_b32_e32 v176, 16, v213
	v_and_b32_e32 v177, 0xffff0000, v213
	v_lshlrev_b32_e32 v188, 16, v214
	v_and_b32_e32 v189, 0xffff0000, v214
	v_lshlrev_b32_e32 v201, 16, v215
	v_and_b32_e32 v211, 0xffff0000, v215
	v_sub_f32_e32 v175, v175, v172
	v_sub_f32_e32 v174, v174, v172
	v_sub_f32_e32 v177, v177, v172
	v_sub_f32_e32 v176, v176, v172
	v_sub_f32_e32 v189, v189, v172
	v_sub_f32_e32 v188, v188, v172
	v_sub_f32_e32 v213, v211, v172
	v_sub_f32_e32 v212, v201, v172
	v_pk_mul_f32 v[176:177], v[172:173], v[176:177] op_sel:[1,0]
	v_pk_mul_f32 v[174:175], v[172:173], v[174:175] op_sel:[1,0]
	v_pk_mul_f32 v[212:213], v[172:173], v[212:213] op_sel:[1,0]
	v_pk_mul_f32 v[188:189], v[172:173], v[188:189] op_sel:[1,0]
	v_pk_fma_f32 v[174:175], v[54:55], v[174:175], v[50:51]
	v_pk_fma_f32 v[176:177], v[56:57], v[176:177], v[52:53]
	v_pk_fma_f32 v[188:189], v[42:43], v[188:189], v[46:47]
	v_pk_fma_f32 v[212:213], v[44:45], v[212:213], v[48:49]
	v_pk_fma_f32 v[160:161], v[176:177], s[72:73], v[160:161] op_sel_hi:[1,0,1]
	v_pk_fma_f32 v[158:159], v[174:175], s[72:73], v[158:159] op_sel_hi:[1,0,1]
	v_pk_fma_f32 v[174:175], v[212:213], s[72:73], v[156:157] op_sel_hi:[1,0,1]
	v_pk_fma_f32 v[156:157], v[188:189], s[72:73], v[154:155] op_sel_hi:[1,0,1]
	v_cvt_pk_bf16_f32 v154, v158, v159
	v_cvt_pk_bf16_f32 v155, v160, v161
	s_nop 0
	v_cvt_pk_bf16_f32 v156, v156, v157
	v_cvt_pk_bf16_f32 v157, v174, v175
	v_mov_b32_e32 v158, v252
	v_mov_b32_e32 v159, v253
	v_mov_b32_e32 v160, v254
	v_mov_b32_e32 v161, v255
	v_add_u32_e32 v210, 0x10000, v210
	global_load_dwordx4 v[244:247], v210, s[26:27]
	global_load_dwordx4 v[252:255], v210, s[26:27] offset:16
	v_lshlrev_b32_e32 v176, 16, v155
	global_store_dwordx4 v[186:187], v[154:157], off
	v_lshlrev_b32_e32 v212, 16, v157
	v_and_b32_e32 v214, 0xffff0000, v155
	v_and_b32_e32 v216, 0xffff0000, v157
	v_and_b32_e32 v174, 0xffff0000, v154
	v_lshlrev_b32_e32 v154, 16, v154
	v_and_b32_e32 v188, 0xffff0000, v156
	v_lshlrev_b32_e32 v156, 16, v156
	s_waitcnt lgkmcnt(0)
	v_lshlrev_b32_e32 v155, 16, v158
	v_and_b32_e32 v157, 0xffff0000, v158
	v_lshlrev_b32_e32 v175, 16, v159
	v_and_b32_e32 v177, 0xffff0000, v159
	v_lshlrev_b32_e32 v211, 16, v161
	v_and_b32_e32 v213, 0xffff0000, v161
	v_sub_f32_e32 v159, v157, v172
	v_sub_f32_e32 v158, v155, v172
	v_lshlrev_b32_e32 v189, 16, v160
	v_and_b32_e32 v201, 0xffff0000, v160
	v_sub_f32_e32 v161, v177, v172
	v_sub_f32_e32 v160, v175, v172
	v_sub_f32_e32 v221, v213, v172
	v_sub_f32_e32 v220, v211, v172
	v_pk_mul_f32 v[158:159], v[172:173], v[158:159] op_sel:[1,0]
	v_sub_f32_e32 v219, v201, v172
	v_sub_f32_e32 v218, v189, v172
	v_pk_mul_f32 v[160:161], v[172:173], v[160:161] op_sel:[1,0]
	v_pk_mul_f32 v[220:221], v[172:173], v[220:221] op_sel:[1,0]
	v_pk_fma_f32 v[158:159], v[26:27], v[158:159], v[30:31]
	v_pk_mul_f32 v[172:173], v[172:173], v[218:219] op_sel:[1,0]
	v_pk_fma_f32 v[160:161], v[28:29], v[160:161], v[32:33]
	v_pk_fma_f32 v[218:219], v[20:21], v[220:221], v[24:25]
	v_pk_fma_f32 v[150:151], v[158:159], s[72:73], v[150:151] op_sel_hi:[1,0,1]
	v_pk_fma_f32 v[172:173], v[18:19], v[172:173], v[22:23]
	v_pk_fma_f32 v[152:153], v[160:161], s[72:73], v[152:153] op_sel_hi:[1,0,1]
	v_pk_fma_f32 v[148:149], v[218:219], s[72:73], v[148:149] op_sel_hi:[1,0,1]
	v_cvt_pk_bf16_f32 v150, v150, v151
	v_cvt_pk_bf16_f32 v151, v152, v153
	v_pk_fma_f32 v[146:147], v[172:173], s[72:73], v[146:147] op_sel_hi:[1,0,1]
	v_lshlrev_b32_e32 v155, 16, v150
	v_and_b32_e32 v215, 0xffff0000, v150
	v_lshlrev_b32_e32 v157, 16, v151
	v_and_b32_e32 v217, 0xffff0000, v151
	v_cvt_pk_bf16_f32 v152, v146, v147
	v_cvt_pk_bf16_f32 v153, v148, v149
	v_pk_mul_f32 v[160:161], v[154:155], v[154:155]
	v_and_b32_e32 v149, 0xffff0000, v153
	v_and_b32_e32 v148, 0xffff0000, v152
	v_mov_b32_e32 v175, v155
	v_mov_b32_e32 v177, v215
	v_mov_b32_e32 v189, v157
	v_mov_b32_e32 v213, v217
	v_lshlrev_b32_e32 v146, 16, v152
	v_lshlrev_b32_e32 v147, 16, v153
	v_pk_mul_f32 v[158:159], v[148:149], v[148:149]
	v_pk_mul_f32 v[172:173], v[214:215], v[214:215]
	v_pk_mul_f32 v[218:219], v[156:157], v[156:157]
	v_pk_mul_f32 v[220:221], v[216:217], v[216:217]
; __device__ __forceinline__ float bf_lo(unsigned w) { return __uint_as_float(w << 16); }
; __device__ __forceinline__ float bf_hi(unsigned w) { return __uint_as_float(w & 0xffff0000u); }
; __device__ __forceinline__ float shflx(float v, int k, int lane) { return __int_as_float(__builtin_amdgcn_ds_bpermute((lane ^ k) << 2, __float_as_int(v))); }
;     __device__ __forceinline__ void operator()(const f32x4 (&acc)[2][2][4][2], const pg8::Unit& u, int wr, int wc, int fr, int fq, LAS unsigned char* lds, int par) const {
;     ...
;                 const int row = row0 + ai * 128 + m * 16, lrow = ai * 128 + wr * 64 + m * 16 + fr;
;                 const size_t ro = (size_t)row * D + c0;
;                 float mu = 0.f, rstd = 1.f; if (prev) { mu = rsb[2 * lrow]; rstd = rsb[2 * lrow + 1]; }
;                 float s1 = 0.f, s2 = 0.f;
; #pragma unroll
;                 for (int bj = 0; bj < 2; ++bj) {
;                     f32x4 r0, r1;
;                     if (prev) {
;                         const u32x4 w = *(const u32x4*)(tb + ro + bj * 8);
;                         r0 = (f32x4){bf_lo(w.x), bf_hi(w.x), bf_lo(w.y), bf_hi(w.y)}; r1 = (f32x4){bf_lo(w.z), bf_hi(w.z), bf_lo(w.w), bf_hi(w.w)};
;                         r0 = (r0 - mu) * rstd * gg[2 * bj] + bb[2 * bj]; r1 = (r1 - mu) * rstd * gg[2 * bj + 1] + bb[2 * bj + 1];
;                     } else { r0 = *(const f32x4*)(xin + ro + bj * 8); r1 = *(const f32x4*)(xin + ro + bj * 8 + 4); }
;     ...
;                     const u32x4 pw = pack8(t0, t1);
;                     *(u32x4*)(tb + ro + bj * 8) = pw;
;                     const float a0 = bf_lo(pw.x), a1 = bf_hi(pw.x), a2 = bf_lo(pw.y), a3 = bf_hi(pw.y), a4 = bf_lo(pw.z), a5 = bf_hi(pw.z), a6 = bf_lo(pw.w), a7 = bf_hi(pw.w);
;                     s1 += ((a0 + a1) + (a2 + a3)) + ((a4 + a5) + (a6 + a7));
;                     s2 += ((a0 * a0 + a1 * a1) + (a2 * a2 + a3 * a3)) + ((a4 * a4 + a5 * a5) + (a6 * a6 + a7 * a7));
;                 }
;                 s1 += shflx(s1, 16, fr + 16 * fq); s1 += shflx(s1, 32, fr + 16 * fq); s2 += shflx(s2, 16, fr + 16 * fq); s2 += shflx(s2, 32, fr + 16 * fq);
;                 if (fq == 0) { float* sp = stats_out + ((size_t)row * 32 + u.pn * 4 + wc) * 2; sp[0] = s1; sp[1] = s2; }
	v_pk_mul_f32 v[226:227], v[174:175], v[174:175]
	v_pk_mul_f32 v[228:229], v[176:177], v[176:177]
	v_pk_mul_f32 v[230:231], v[188:189], v[188:189]
	v_pk_mul_f32 v[232:233], v[212:213], v[212:213]
	v_pk_mov_b32 v[234:235], v[154:155], v[160:161] op_sel:[1,0]
	v_pk_add_f32 v[154:155], v[154:155], v[174:175]
	v_pk_add_f32 v[174:175], v[214:215], v[176:177]
	v_pk_add_f32 v[176:177], v[156:157], v[188:189]
	v_pk_add_f32 v[188:189], v[216:217], v[212:213]
	v_mov_b32_e32 v222, v146
	v_mov_b32_e32 v224, v148
	v_pk_fma_f32 v[158:159], v[146:147], v[146:147], v[158:159]
	v_pk_mov_b32 v[236:237], v[216:217], v[172:173] op_sel:[1,0]
	v_mov_b32_e32 v223, v218
	v_pk_mov_b32 v[148:149], v[148:149], v[220:221] op_sel:[1,0]
	v_pk_mov_b32 v[212:213], v[214:215], v[226:227] op_sel:[1,0]
	v_pk_mov_b32 v[156:157], v[156:157], v[228:229] op_sel:[1,0]
	v_mov_b32_e32 v225, v230
	v_pk_mov_b32 v[146:147], v[146:147], v[232:233] op_sel:[1,0]
	v_mov_b32_e32 v155, v161
	v_mov_b32_e32 v175, v173
	v_mov_b32_e32 v177, v219
	v_mov_b32_e32 v189, v221
	v_pk_add_f32 v[158:159], v[158:159], v[158:159] op_sel_hi:[0,1]
	v_pk_add_f32 v[160:161], v[234:235], v[212:213]
	v_pk_add_f32 v[156:157], v[156:157], v[236:237]
	v_pk_add_f32 v[172:173], v[222:223], v[224:225]
	v_pk_add_f32 v[146:147], v[146:147], v[148:149]
	v_pk_add_f32 v[148:149], v[154:155], v[174:175]
	v_pk_add_f32 v[154:155], v[176:177], v[188:189]
	v_mov_b32_e32 v158, v1
	v_pk_add_f32 v[156:157], v[160:161], v[156:157]
	v_pk_add_f32 v[146:147], v[172:173], v[146:147]
	v_pk_add_f32 v[148:149], v[148:149], v[154:155]
	v_pk_add_f32 v[146:147], v[156:157], v[146:147]
	v_pk_add_f32 v[148:149], v[148:149], v[158:159]
	global_store_dwordx4 v[186:187], v[150:153], off offset:16
	v_pk_add_f32 v[146:147], v[146:147], v[148:149]
	ds_bpermute_b32 v148, v194, v146
	ds_bpermute_b32 v149, v194, v147
	s_waitcnt lgkmcnt(0)
	v_pk_add_f32 v[146:147], v[146:147], v[148:149]
	ds_bpermute_b32 v148, v195, v146
	ds_bpermute_b32 v149, v195, v147
	s_and_saveexec_b64 s[26:27], s[42:43]
	s_cbranch_execz .LBB0_211
	v_readlane_b32 s28, v251, 35
	v_lshlrev_b64 v[150:151], 8, v[184:185]
	v_readlane_b32 s29, v251, 36
	s_waitcnt lgkmcnt(0)
	v_pk_add_f32 v[146:147], v[146:147], v[148:149]
	v_lshl_add_u64 v[150:151], s[28:29], 0, v[150:151]
	v_lshl_add_u64 v[150:151], s[24:25], 3, v[150:151]
	global_store_dwordx2 v[150:151], v[146:147], off
.LBB0_211:
	s_or_b64 exec, exec, s[26:27]
	v_or_b32_e32 v146, 16, v184
	v_ashrrev_i32_e32 v147, 31, v146
	v_readlane_b32 s26, v251, 31
	s_waitcnt lgkmcnt(0)
	v_lshlrev_b64 v[148:149], 12, v[146:147]
	v_readlane_b32 s27, v251, 32
	ds_read_b64 v[156:157], v200 offset:128
	s_nop 0
	v_lshl_add_u64 v[148:149], s[26:27], 0, v[148:149]
	v_lshl_add_u64 v[158:159], v[182:183], 1, v[148:149]
	s_waitcnt vmcnt(3) lgkmcnt(0)
	v_mov_b32_e32 v148, v244
	v_mov_b32_e32 v149, v245
	v_mov_b32_e32 v150, v246
	v_mov_b32_e32 v151, v247
	v_lshlrev_b32_e32 v152, 16, v148
	v_and_b32_e32 v148, 0xffff0000, v148
	v_lshlrev_b32_e32 v153, 16, v149
	v_and_b32_e32 v154, 0xffff0000, v149
	v_lshlrev_b32_e32 v155, 16, v150
	v_and_b32_e32 v160, 0xffff0000, v150
	v_lshlrev_b32_e32 v161, 16, v151
	v_and_b32_e32 v172, 0xffff0000, v151
	v_sub_f32_e32 v149, v148, v156
	v_sub_f32_e32 v148, v152, v156
	v_sub_f32_e32 v151, v154, v156
	v_sub_f32_e32 v150, v153, v156
	v_sub_f32_e32 v153, v160, v156
	v_sub_f32_e32 v152, v155, v156
	v_sub_f32_e32 v155, v172, v156
	v_sub_f32_e32 v154, v161, v156
	v_pk_mul_f32 v[148:149], v[156:157], v[148:149] op_sel:[1,0]
	v_pk_mul_f32 v[154:155], v[156:157], v[154:155] op_sel:[1,0]
	v_pk_mul_f32 v[152:153], v[156:157], v[152:153] op_sel:[1,0]
	v_pk_mul_f32 v[150:151], v[156:157], v[150:151] op_sel:[1,0]
	v_pk_fma_f32 v[148:149], v[54:55], v[148:149], v[50:51]
	v_pk_fma_f32 v[152:153], v[42:43], v[152:153], v[46:47]
	v_pk_fma_f32 v[154:155], v[44:45], v[154:155], v[48:49]
	v_pk_fma_f32 v[150:151], v[56:57], v[150:151], v[52:53]
	v_pk_fma_f32 v[142:143], v[148:149], s[72:73], v[142:143] op_sel_hi:[1,0,1]
	v_pk_fma_f32 v[148:149], v[154:155], s[72:73], v[140:141] op_sel_hi:[1,0,1]
	v_pk_fma_f32 v[140:141], v[152:153], s[72:73], v[138:139] op_sel_hi:[1,0,1]
	v_pk_fma_f32 v[144:145], v[150:151], s[72:73], v[144:145] op_sel_hi:[1,0,1]
	v_cvt_pk_bf16_f32 v138, v142, v143
	s_nop 0
	v_cvt_pk_bf16_f32 v139, v144, v145
	v_cvt_pk_bf16_f32 v140, v140, v141
	v_cvt_pk_bf16_f32 v141, v148, v149
	s_waitcnt vmcnt(2)
	v_mov_b32_e32 v152, v252
	v_mov_b32_e32 v153, v253
	v_mov_b32_e32 v154, v254
	v_mov_b32_e32 v155, v255
	v_add_u32_e32 v210, 0x10000, v210
	global_load_dwordx4 v[244:247], v210, s[26:27]
	global_load_dwordx4 v[252:255], v210, s[26:27] offset:16
	v_and_b32_e32 v150, 0xffff0000, v138
	global_store_dwordx4 v[158:159], v[138:141], off
	v_lshlrev_b32_e32 v148, 16, v139
	v_lshlrev_b32_e32 v142, 16, v141
	v_and_b32_e32 v144, 0xffff0000, v140
	s_waitcnt lgkmcnt(0)
; __device__ __forceinline__ float bf_lo(unsigned w) { return __uint_as_float(w << 16); }
; __device__ __forceinline__ float bf_hi(unsigned w) { return __uint_as_float(w & 0xffff0000u); }
; __device__ __forceinline__ float shflx(float v, int k, int lane) { return __int_as_float(__builtin_amdgcn_ds_bpermute((lane ^ k) << 2, __float_as_int(v))); }
; __device__ __forceinline__ u32x4 pack8(const f32x4 a, const f32x4 b) { u32x4 w; w.x = cvt_pk_bf16(a[0], a[1]); w.y = cvt_pk_bf16(a[2], a[3]); w.z = cvt_pk_bf16(b[0], b[1]); w.w = cvt_pk_bf16(b[2], b[3]); return w; }
;     __device__ __forceinline__ void operator()(const f32x4 (&acc)[2][2][4][2], const pg8::Unit& u, int wr, int wc, int fr, int fq, LAS unsigned char* lds, int par) const {
;     ...
;                         r0 = (r0 - mu) * rstd * gg[2 * bj] + bb[2 * bj]; r1 = (r1 - mu) * rstd * gg[2 * bj + 1] + bb[2 * bj + 1];
;                     } else { r0 = *(const f32x4*)(xin + ro + bj * 8); r1 = *(const f32x4*)(xin + ro + bj * 8 + 4); }
;                     const f32x4 t0 = r0 * ALPHA + acc[ai][bj][m][0], t1 = r1 * ALPHA + acc[ai][bj][m][1];
;                     if (xout != nullptr) { *(f32x4*)(xout + ro + bj * 8) = t0; *(f32x4*)(xout + ro + bj * 8 + 4) = t1; }
;                     const u32x4 pw = pack8(t0, t1);
;                     *(u32x4*)(tb + ro + bj * 8) = pw;
;                     const float a0 = bf_lo(pw.x), a1 = bf_hi(pw.x), a2 = bf_lo(pw.y), a3 = bf_hi(pw.y), a4 = bf_lo(pw.z), a5 = bf_hi(pw.z), a6 = bf_lo(pw.w), a7 = bf_hi(pw.w);
;                     s1 += ((a0 + a1) + (a2 + a3)) + ((a4 + a5) + (a6 + a7));
;                     s2 += ((a0 * a0 + a1 * a1) + (a2 * a2 + a3 * a3)) + ((a4 * a4 + a5 * a5) + (a6 * a6 + a7 * a7));
;                 }
;                 s1 += shflx(s1, 16, fr + 16 * fq); s1 += shflx(s1, 32, fr + 16 * fq); s2 += shflx(s2, 16, fr + 16 * fq); s2 += shflx(s2, 32, fr + 16 * fq);
;                 if (fq == 0) { float* sp = stats_out + ((size_t)row * 32 + u.pn * 4 + wc) * 2; sp[0] = s1; sp[1] = s2; }
	v_lshlrev_b32_e32 v143, 16, v152
	v_and_b32_e32 v145, 0xffff0000, v152
	v_lshlrev_b32_e32 v149, 16, v153
	v_and_b32_e32 v151, 0xffff0000, v153
	v_lshlrev_b32_e32 v160, 16, v154
	v_and_b32_e32 v161, 0xffff0000, v154
	v_lshlrev_b32_e32 v172, 16, v155
	v_and_b32_e32 v173, 0xffff0000, v155
	v_sub_f32_e32 v153, v145, v156
	v_sub_f32_e32 v152, v143, v156
	v_sub_f32_e32 v155, v151, v156
	v_sub_f32_e32 v154, v149, v156
	v_sub_f32_e32 v161, v161, v156
	v_sub_f32_e32 v160, v160, v156
	v_sub_f32_e32 v173, v173, v156
	v_sub_f32_e32 v172, v172, v156
	v_pk_mul_f32 v[154:155], v[156:157], v[154:155] op_sel:[1,0]
	v_pk_mul_f32 v[152:153], v[156:157], v[152:153] op_sel:[1,0]
	v_pk_mul_f32 v[172:173], v[156:157], v[172:173] op_sel:[1,0]
	v_pk_mul_f32 v[156:157], v[156:157], v[160:161] op_sel:[1,0]
	v_pk_fma_f32 v[152:153], v[26:27], v[152:153], v[30:31]
	v_pk_fma_f32 v[154:155], v[28:29], v[154:155], v[32:33]
	v_pk_fma_f32 v[156:157], v[18:19], v[156:157], v[22:23]
	v_pk_fma_f32 v[160:161], v[20:21], v[172:173], v[24:25]
	v_pk_fma_f32 v[136:137], v[154:155], s[72:73], v[136:137] op_sel_hi:[1,0,1]
	v_pk_fma_f32 v[134:135], v[152:153], s[72:73], v[134:135] op_sel_hi:[1,0,1]
	v_pk_fma_f32 v[152:153], v[160:161], s[72:73], v[132:133] op_sel_hi:[1,0,1]
	v_pk_fma_f32 v[132:133], v[156:157], s[72:73], v[130:131] op_sel_hi:[1,0,1]
	v_cvt_pk_bf16_f32 v130, v134, v135
	v_cvt_pk_bf16_f32 v131, v136, v137
	v_lshlrev_b32_e32 v154, 16, v138
	v_lshlrev_b32_e32 v155, 16, v130
	v_cvt_pk_bf16_f32 v132, v132, v133
	v_cvt_pk_bf16_f32 v133, v152, v153
	v_mov_b32_e32 v151, v155
	v_and_b32_e32 v153, 0xffff0000, v130
	v_pk_mul_f32 v[156:157], v[154:155], v[154:155]
	v_pk_mul_f32 v[186:187], v[150:151], v[150:151]
	v_and_b32_e32 v152, 0xffff0000, v139
	v_mov_b32_e32 v149, v153
	global_store_dwordx4 v[158:159], v[130:133], off offset:16
	v_pk_mul_f32 v[172:173], v[148:149], v[148:149]
	v_pk_mul_f32 v[138:139], v[152:153], v[152:153]
	v_lshlrev_b32_e32 v158, 16, v140
	v_lshlrev_b32_e32 v159, 16, v131
	v_and_b32_e32 v131, 0xffff0000, v131
	v_and_b32_e32 v130, 0xffff0000, v141
	v_pk_mov_b32 v[176:177], v[154:155], v[156:157] op_sel:[1,0]
	v_pk_mov_b32 v[186:187], v[152:153], v[186:187] op_sel:[1,0]
	v_and_b32_e32 v135, 0xffff0000, v133
	v_and_b32_e32 v134, 0xffff0000, v132
	v_mov_b32_e32 v143, v131
	v_pk_add_f32 v[176:177], v[176:177], v[186:187]
	v_pk_mov_b32 v[172:173], v[158:159], v[172:173] op_sel:[1,0]
	v_pk_mov_b32 v[186:187], v[130:131], v[138:139] op_sel:[1,0]
	v_lshlrev_b32_e32 v136, 16, v132
	v_lshlrev_b32_e32 v137, 16, v133
	v_pk_mul_f32 v[132:133], v[134:135], v[134:135]
	v_pk_mul_f32 v[140:141], v[142:143], v[142:143]
	v_pk_mul_f32 v[174:175], v[130:131], v[130:131]
	v_pk_add_f32 v[172:173], v[172:173], v[186:187]
	v_pk_fma_f32 v[132:133], v[136:137], v[136:137], v[132:133]
	v_mov_b32_e32 v145, v159
	v_pk_add_f32 v[172:173], v[176:177], v[172:173]
	v_mov_b32_e32 v176, v136
	v_mov_b32_e32 v186, v134
	v_pk_mov_b32 v[136:137], v[136:137], v[140:141] op_sel:[1,0]
	v_pk_mov_b32 v[134:135], v[134:135], v[174:175] op_sel:[1,0]
	v_pk_add_f32 v[140:141], v[152:153], v[148:149]
	v_pk_mul_f32 v[160:161], v[158:159], v[158:159]
	v_pk_mul_f32 v[188:189], v[144:145], v[144:145]
	v_pk_add_f32 v[134:135], v[136:137], v[134:135]
	v_pk_add_f32 v[136:137], v[154:155], v[150:151]
	v_mov_b32_e32 v141, v139
	v_pk_add_f32 v[138:139], v[158:159], v[144:145]
	v_pk_add_f32 v[130:131], v[130:131], v[142:143]
	v_mov_b32_e32 v177, v160
	v_mov_b32_e32 v187, v188
	v_mov_b32_e32 v137, v157
	v_mov_b32_e32 v139, v161
	v_mov_b32_e32 v131, v175
	v_pk_add_f32 v[132:133], v[132:133], v[132:133] op_sel_hi:[0,1]
	v_pk_add_f32 v[176:177], v[176:177], v[186:187]
	v_pk_add_f32 v[136:137], v[136:137], v[140:141]
	v_pk_add_f32 v[130:131], v[138:139], v[130:131]
	v_pk_add_f32 v[134:135], v[176:177], v[134:135]
	v_pk_add_f32 v[130:131], v[136:137], v[130:131]
	v_mov_b32_e32 v132, v1
	v_pk_add_f32 v[134:135], v[172:173], v[134:135]
	v_pk_add_f32 v[130:131], v[130:131], v[132:133]
	s_nop 0
	v_pk_add_f32 v[130:131], v[134:135], v[130:131]
	ds_bpermute_b32 v132, v194, v130
	ds_bpermute_b32 v133, v194, v131
	s_waitcnt lgkmcnt(0)
	v_pk_add_f32 v[130:131], v[130:131], v[132:133]
	ds_bpermute_b32 v132, v195, v130
	ds_bpermute_b32 v133, v195, v131
	s_and_saveexec_b64 s[26:27], s[42:43]
	s_cbranch_execz .LBB0_213
	v_readlane_b32 s28, v251, 35
	v_lshlrev_b64 v[134:135], 8, v[146:147]
	v_readlane_b32 s29, v251, 36
	s_waitcnt lgkmcnt(0)
	v_pk_add_f32 v[130:131], v[130:131], v[132:133]
	v_lshl_add_u64 v[134:135], s[28:29], 0, v[134:135]
	v_lshl_add_u64 v[134:135], s[24:25], 3, v[134:135]
	global_store_dwordx2 v[134:135], v[130:131], off
; __device__ __forceinline__ float bf_lo(unsigned w) { return __uint_as_float(w << 16); }
; __device__ __forceinline__ float bf_hi(unsigned w) { return __uint_as_float(w & 0xffff0000u); }
;     __device__ __forceinline__ void operator()(const f32x4 (&acc)[2][2][4][2], const pg8::Unit& u, int wr, int wc, int fr, int fq, LAS unsigned char* lds, int par) const {
;     ...
;                 const int row = row0 + ai * 128 + m * 16, lrow = ai * 128 + wr * 64 + m * 16 + fr;
;                 const size_t ro = (size_t)row * D + c0;
;                 float mu = 0.f, rstd = 1.f; if (prev) { mu = rsb[2 * lrow]; rstd = rsb[2 * lrow + 1]; }
;                 float s1 = 0.f, s2 = 0.f;
; #pragma unroll
;                 for (int bj = 0; bj < 2; ++bj) {
;                     f32x4 r0, r1;
;                     if (prev) {
;                         const u32x4 w = *(const u32x4*)(tb + ro + bj * 8);
;                         r0 = (f32x4){bf_lo(w.x), bf_hi(w.x), bf_lo(w.y), bf_hi(w.y)}; r1 = (f32x4){bf_lo(w.z), bf_hi(w.z), bf_lo(w.w), bf_hi(w.w)};
;                         r0 = (r0 - mu) * rstd * gg[2 * bj] + bb[2 * bj]; r1 = (r1 - mu) * rstd * gg[2 * bj + 1] + bb[2 * bj + 1];
;                     } else { r0 = *(const f32x4*)(xin + ro + bj * 8); r1 = *(const f32x4*)(xin + ro + bj * 8 + 4); }
;                     const f32x4 t0 = r0 * ALPHA + acc[ai][bj][m][0], t1 = r1 * ALPHA + acc[ai][bj][m][1];
;                     if (xout != nullptr) { *(f32x4*)(xout + ro + bj * 8) = t0; *(f32x4*)(xout + ro + bj * 8 + 4) = t1; }
;                     const u32x4 pw = pack8(t0, t1);
;                     *(u32x4*)(tb + ro + bj * 8) = pw;
;                     const float a0 = bf_lo(pw.x), a1 = bf_hi(pw.x), a2 = bf_lo(pw.y), a3 = bf_hi(pw.y), a4 = bf_lo(pw.z), a5 = bf_hi(pw.z), a6 = bf_lo(pw.w), a7 = bf_hi(pw.w);
;                     s1 += ((a0 + a1) + (a2 + a3)) + ((a4 + a5) + (a6 + a7));
;                     s2 += ((a0 * a0 + a1 * a1) + (a2 * a2 + a3 * a3)) + ((a4 * a4 + a5 * a5) + (a6 * a6 + a7 * a7));
;                 }
;                 s1 += shflx(s1, 16, fr + 16 * fq); s1 += shflx(s1, 32, fr + 16 * fq); s2 += shflx(s2, 16, fr + 16 * fq); s2 += shflx(s2, 32, fr + 16 * fq);
;                 if (fq == 0) { float* sp = stats_out + ((size_t)row * 32 + u.pn * 4 + wc) * 2; sp[0] = s1; sp[1] = s2; }
.LBB0_213:
	s_or_b64 exec, exec, s[26:27]
	v_or_b32_e32 v130, 32, v184
	v_ashrrev_i32_e32 v131, 31, v130
	v_readlane_b32 s26, v251, 31
	s_waitcnt lgkmcnt(0)
	v_lshlrev_b64 v[132:133], 12, v[130:131]
	v_readlane_b32 s27, v251, 32
	ds_read_b64 v[140:141], v200 offset:256
	s_nop 0
	v_lshl_add_u64 v[132:133], s[26:27], 0, v[132:133]
	v_lshl_add_u64 v[142:143], v[182:183], 1, v[132:133]
	s_waitcnt vmcnt(3) lgkmcnt(0)
	v_mov_b32_e32 v132, v244
	v_mov_b32_e32 v133, v245
	v_mov_b32_e32 v134, v246
	v_mov_b32_e32 v135, v247
	v_lshlrev_b32_e32 v136, 16, v132
	v_and_b32_e32 v132, 0xffff0000, v132
	v_lshlrev_b32_e32 v137, 16, v133
	v_and_b32_e32 v138, 0xffff0000, v133
	v_lshlrev_b32_e32 v139, 16, v134
	v_and_b32_e32 v144, 0xffff0000, v134
	v_lshlrev_b32_e32 v145, 16, v135
	v_and_b32_e32 v146, 0xffff0000, v135
	v_sub_f32_e32 v133, v132, v140
	v_sub_f32_e32 v132, v136, v140
	v_sub_f32_e32 v135, v138, v140
	v_sub_f32_e32 v134, v137, v140
	v_sub_f32_e32 v137, v144, v140
	v_sub_f32_e32 v136, v139, v140
	v_sub_f32_e32 v139, v146, v140
	v_sub_f32_e32 v138, v145, v140
	v_pk_mul_f32 v[132:133], v[140:141], v[132:133] op_sel:[1,0]
	v_pk_mul_f32 v[138:139], v[140:141], v[138:139] op_sel:[1,0]
	v_pk_mul_f32 v[136:137], v[140:141], v[136:137] op_sel:[1,0]
	v_pk_mul_f32 v[134:135], v[140:141], v[134:135] op_sel:[1,0]
	v_pk_fma_f32 v[132:133], v[54:55], v[132:133], v[50:51]
	v_pk_fma_f32 v[136:137], v[42:43], v[136:137], v[46:47]
	v_pk_fma_f32 v[138:139], v[44:45], v[138:139], v[48:49]
	v_pk_fma_f32 v[134:135], v[56:57], v[134:135], v[52:53]
	v_pk_fma_f32 v[126:127], v[132:133], s[72:73], v[126:127] op_sel_hi:[1,0,1]
	v_pk_fma_f32 v[132:133], v[138:139], s[72:73], v[124:125] op_sel_hi:[1,0,1]
	v_pk_fma_f32 v[124:125], v[136:137], s[72:73], v[122:123] op_sel_hi:[1,0,1]
	v_pk_fma_f32 v[128:129], v[134:135], s[72:73], v[128:129] op_sel_hi:[1,0,1]
	v_cvt_pk_bf16_f32 v122, v126, v127
	s_nop 0
	v_cvt_pk_bf16_f32 v123, v128, v129
	v_cvt_pk_bf16_f32 v124, v124, v125
	v_cvt_pk_bf16_f32 v125, v132, v133
	s_waitcnt vmcnt(2)
	v_mov_b32_e32 v136, v252
	v_mov_b32_e32 v137, v253
	v_mov_b32_e32 v138, v254
	v_mov_b32_e32 v139, v255
	v_add_u32_e32 v210, 0x10000, v210
	global_load_dwordx4 v[244:247], v210, s[26:27]
	global_load_dwordx4 v[252:255], v210, s[26:27] offset:16
	v_and_b32_e32 v134, 0xffff0000, v122
	global_store_dwordx4 v[142:143], v[122:125], off
	v_lshlrev_b32_e32 v132, 16, v123
	v_lshlrev_b32_e32 v126, 16, v125
	v_and_b32_e32 v128, 0xffff0000, v124
	s_waitcnt lgkmcnt(0)
	v_lshlrev_b32_e32 v127, 16, v136
	v_and_b32_e32 v129, 0xffff0000, v136
	v_lshlrev_b32_e32 v133, 16, v137
	v_and_b32_e32 v135, 0xffff0000, v137
	v_lshlrev_b32_e32 v144, 16, v138
	v_and_b32_e32 v145, 0xffff0000, v138
	v_lshlrev_b32_e32 v146, 16, v139
	v_and_b32_e32 v147, 0xffff0000, v139
	v_sub_f32_e32 v137, v129, v140
	v_sub_f32_e32 v136, v127, v140
	v_sub_f32_e32 v139, v135, v140
	v_sub_f32_e32 v138, v133, v140
	v_sub_f32_e32 v145, v145, v140
	v_sub_f32_e32 v144, v144, v140
	v_sub_f32_e32 v147, v147, v140
	v_sub_f32_e32 v146, v146, v140
	v_pk_mul_f32 v[138:139], v[140:141], v[138:139] op_sel:[1,0]
	v_pk_mul_f32 v[136:137], v[140:141], v[136:137] op_sel:[1,0]
	v_pk_mul_f32 v[146:147], v[140:141], v[146:147] op_sel:[1,0]
	v_pk_mul_f32 v[140:141], v[140:141], v[144:145] op_sel:[1,0]
	v_pk_fma_f32 v[136:137], v[26:27], v[136:137], v[30:31]
	v_pk_fma_f32 v[138:139], v[28:29], v[138:139], v[32:33]
	v_pk_fma_f32 v[140:141], v[18:19], v[140:141], v[22:23]
	v_pk_fma_f32 v[144:145], v[20:21], v[146:147], v[24:25]
	v_pk_fma_f32 v[120:121], v[138:139], s[72:73], v[120:121] op_sel_hi:[1,0,1]
	v_pk_fma_f32 v[118:119], v[136:137], s[72:73], v[118:119] op_sel_hi:[1,0,1]
	v_pk_fma_f32 v[136:137], v[144:145], s[72:73], v[116:117] op_sel_hi:[1,0,1]
	v_pk_fma_f32 v[116:117], v[140:141], s[72:73], v[114:115] op_sel_hi:[1,0,1]
	v_cvt_pk_bf16_f32 v114, v118, v119
	v_cvt_pk_bf16_f32 v115, v120, v121
	v_lshlrev_b32_e32 v138, 16, v122
	v_lshlrev_b32_e32 v139, 16, v114
	v_cvt_pk_bf16_f32 v116, v116, v117
	v_cvt_pk_bf16_f32 v117, v136, v137
	v_mov_b32_e32 v135, v139
	v_and_b32_e32 v137, 0xffff0000, v114
	v_pk_mul_f32 v[140:141], v[138:139], v[138:139]
	v_pk_mul_f32 v[146:147], v[134:135], v[134:135]
	v_and_b32_e32 v136, 0xffff0000, v123
	v_mov_b32_e32 v133, v137
	global_store_dwordx4 v[142:143], v[114:117], off offset:16
	v_pk_mul_f32 v[150:151], v[132:133], v[132:133]
	v_pk_mul_f32 v[122:123], v[136:137], v[136:137]
	v_lshlrev_b32_e32 v142, 16, v124
	v_lshlrev_b32_e32 v143, 16, v115
	v_and_b32_e32 v115, 0xffff0000, v115
	v_and_b32_e32 v114, 0xffff0000, v125
	v_pk_mov_b32 v[154:155], v[138:139], v[140:141] op_sel:[1,0]
	v_pk_mov_b32 v[146:147], v[136:137], v[146:147] op_sel:[1,0]
	v_and_b32_e32 v119, 0xffff0000, v117
	v_and_b32_e32 v118, 0xffff0000, v116
	v_mov_b32_e32 v127, v115
	v_pk_add_f32 v[146:147], v[154:155], v[146:147]
	v_pk_mov_b32 v[150:151], v[142:143], v[150:151] op_sel:[1,0]
	v_pk_mov_b32 v[154:155], v[114:115], v[122:123] op_sel:[1,0]
	v_lshlrev_b32_e32 v120, 16, v116
	v_lshlrev_b32_e32 v121, 16, v117
	v_pk_mul_f32 v[116:117], v[118:119], v[118:119]
	v_pk_mul_f32 v[124:125], v[126:127], v[126:127]
	v_pk_mul_f32 v[152:153], v[114:115], v[114:115]
	v_pk_add_f32 v[150:151], v[150:151], v[154:155]
	v_pk_fma_f32 v[116:117], v[120:121], v[120:121], v[116:117]
	v_mov_b32_e32 v129, v143
	v_pk_add_f32 v[146:147], v[146:147], v[150:151]
	v_mov_b32_e32 v150, v120
	v_mov_b32_e32 v154, v118
	v_pk_mov_b32 v[120:121], v[120:121], v[124:125] op_sel:[1,0]
	v_pk_mov_b32 v[118:119], v[118:119], v[152:153] op_sel:[1,0]
	v_pk_add_f32 v[124:125], v[136:137], v[132:133]
	v_pk_mul_f32 v[144:145], v[142:143], v[142:143]
	v_pk_mul_f32 v[148:149], v[128:129], v[128:129]
	v_pk_add_f32 v[118:119], v[120:121], v[118:119]
	v_pk_add_f32 v[120:121], v[138:139], v[134:135]
	v_mov_b32_e32 v125, v123
	v_pk_add_f32 v[122:123], v[142:143], v[128:129]
	v_pk_add_f32 v[114:115], v[114:115], v[126:127]
	v_mov_b32_e32 v151, v144
	v_mov_b32_e32 v155, v148
	v_mov_b32_e32 v121, v141
	v_mov_b32_e32 v123, v145
	v_mov_b32_e32 v115, v153
	v_pk_add_f32 v[116:117], v[116:117], v[116:117] op_sel_hi:[0,1]
	v_pk_add_f32 v[148:149], v[150:151], v[154:155]
	v_pk_add_f32 v[120:121], v[120:121], v[124:125]
	v_pk_add_f32 v[114:115], v[122:123], v[114:115]
	v_pk_add_f32 v[118:119], v[148:149], v[118:119]
	v_pk_add_f32 v[114:115], v[120:121], v[114:115]
	v_mov_b32_e32 v116, v1
	v_pk_add_f32 v[118:119], v[146:147], v[118:119]
	v_pk_add_f32 v[114:115], v[114:115], v[116:117]
	s_nop 0
	v_pk_add_f32 v[114:115], v[118:119], v[114:115]
	ds_bpermute_b32 v116, v194, v114
	ds_bpermute_b32 v117, v194, v115
	s_waitcnt lgkmcnt(0)
	v_pk_add_f32 v[114:115], v[114:115], v[116:117]
	ds_bpermute_b32 v116, v195, v114
	ds_bpermute_b32 v117, v195, v115
	s_and_saveexec_b64 s[26:27], s[42:43]
	s_cbranch_execz .LBB0_215
; __device__ __forceinline__ float bf_lo(unsigned w) { return __uint_as_float(w << 16); }
; __device__ __forceinline__ float bf_hi(unsigned w) { return __uint_as_float(w & 0xffff0000u); }
;     __device__ __forceinline__ void operator()(const f32x4 (&acc)[2][2][4][2], const pg8::Unit& u, int wr, int wc, int fr, int fq, LAS unsigned char* lds, int par) const {
;     ...
;                 const int row = row0 + ai * 128 + m * 16, lrow = ai * 128 + wr * 64 + m * 16 + fr;
;                 const size_t ro = (size_t)row * D + c0;
;                 float mu = 0.f, rstd = 1.f; if (prev) { mu = rsb[2 * lrow]; rstd = rsb[2 * lrow + 1]; }
;                 float s1 = 0.f, s2 = 0.f;
; #pragma unroll
;                 for (int bj = 0; bj < 2; ++bj) {
;                     f32x4 r0, r1;
;                     if (prev) {
;                         const u32x4 w = *(const u32x4*)(tb + ro + bj * 8);
;                         r0 = (f32x4){bf_lo(w.x), bf_hi(w.x), bf_lo(w.y), bf_hi(w.y)}; r1 = (f32x4){bf_lo(w.z), bf_hi(w.z), bf_lo(w.w), bf_hi(w.w)};
;                         r0 = (r0 - mu) * rstd * gg[2 * bj] + bb[2 * bj]; r1 = (r1 - mu) * rstd * gg[2 * bj + 1] + bb[2 * bj + 1];
;                     } else { r0 = *(const f32x4*)(xin + ro + bj * 8); r1 = *(const f32x4*)(xin + ro + bj * 8 + 4); }
;                     const f32x4 t0 = r0 * ALPHA + acc[ai][bj][m][0], t1 = r1 * ALPHA + acc[ai][bj][m][1];
;                     if (xout != nullptr) { *(f32x4*)(xout + ro + bj * 8) = t0; *(f32x4*)(xout + ro + bj * 8 + 4) = t1; }
;                     const u32x4 pw = pack8(t0, t1);
;                     *(u32x4*)(tb + ro + bj * 8) = pw;
;                     const float a0 = bf_lo(pw.x), a1 = bf_hi(pw.x), a2 = bf_lo(pw.y), a3 = bf_hi(pw.y), a4 = bf_lo(pw.z), a5 = bf_hi(pw.z), a6 = bf_lo(pw.w), a7 = bf_hi(pw.w);
;                     s1 += ((a0 + a1) + (a2 + a3)) + ((a4 + a5) + (a6 + a7));
;                     s2 += ((a0 * a0 + a1 * a1) + (a2 * a2 + a3 * a3)) + ((a4 * a4 + a5 * a5) + (a6 * a6 + a7 * a7));
;                 }
;                 s1 += shflx(s1, 16, fr + 16 * fq); s1 += shflx(s1, 32, fr + 16 * fq); s2 += shflx(s2, 16, fr + 16 * fq); s2 += shflx(s2, 32, fr + 16 * fq);
;                 if (fq == 0) { float* sp = stats_out + ((size_t)row * 32 + u.pn * 4 + wc) * 2; sp[0] = s1; sp[1] = s2; }
	v_readlane_b32 s28, v251, 35
	v_lshlrev_b64 v[118:119], 8, v[130:131]
	v_readlane_b32 s29, v251, 36
	s_waitcnt lgkmcnt(0)
	v_pk_add_f32 v[114:115], v[114:115], v[116:117]
	v_lshl_add_u64 v[118:119], s[28:29], 0, v[118:119]
	v_lshl_add_u64 v[118:119], s[24:25], 3, v[118:119]
	global_store_dwordx2 v[118:119], v[114:115], off
.LBB0_215:
	s_or_b64 exec, exec, s[26:27]
	v_or_b32_e32 v114, 48, v184
	v_ashrrev_i32_e32 v115, 31, v114
	v_readlane_b32 s26, v251, 31
	s_waitcnt lgkmcnt(0)
	v_lshlrev_b64 v[116:117], 12, v[114:115]
	v_readlane_b32 s27, v251, 32
	ds_read_b64 v[124:125], v200 offset:384
	s_nop 0
	v_lshl_add_u64 v[116:117], s[26:27], 0, v[116:117]
	v_lshl_add_u64 v[126:127], v[182:183], 1, v[116:117]
	s_waitcnt vmcnt(3) lgkmcnt(0)
	v_mov_b32_e32 v116, v244
	v_mov_b32_e32 v117, v245
	v_mov_b32_e32 v118, v246
	v_mov_b32_e32 v119, v247
	v_lshlrev_b32_e32 v120, 16, v116
	v_and_b32_e32 v116, 0xffff0000, v116
	v_lshlrev_b32_e32 v121, 16, v117
	v_and_b32_e32 v122, 0xffff0000, v117
	v_lshlrev_b32_e32 v123, 16, v118
	v_and_b32_e32 v128, 0xffff0000, v118
	v_lshlrev_b32_e32 v129, 16, v119
	v_and_b32_e32 v130, 0xffff0000, v119
	v_sub_f32_e32 v117, v116, v124
	v_sub_f32_e32 v116, v120, v124
	v_sub_f32_e32 v119, v122, v124
	v_sub_f32_e32 v118, v121, v124
	v_sub_f32_e32 v121, v128, v124
	v_sub_f32_e32 v120, v123, v124
	v_sub_f32_e32 v123, v130, v124
	v_sub_f32_e32 v122, v129, v124
	v_pk_mul_f32 v[116:117], v[124:125], v[116:117] op_sel:[1,0]
	v_pk_mul_f32 v[122:123], v[124:125], v[122:123] op_sel:[1,0]
	v_pk_mul_f32 v[120:121], v[124:125], v[120:121] op_sel:[1,0]
	v_pk_mul_f32 v[118:119], v[124:125], v[118:119] op_sel:[1,0]
	v_pk_fma_f32 v[116:117], v[54:55], v[116:117], v[50:51]
	v_pk_fma_f32 v[120:121], v[42:43], v[120:121], v[46:47]
	v_pk_fma_f32 v[122:123], v[44:45], v[122:123], v[48:49]
	v_pk_fma_f32 v[118:119], v[56:57], v[118:119], v[52:53]
	v_pk_fma_f32 v[110:111], v[116:117], s[72:73], v[110:111] op_sel_hi:[1,0,1]
	v_pk_fma_f32 v[116:117], v[122:123], s[72:73], v[108:109] op_sel_hi:[1,0,1]
	v_pk_fma_f32 v[108:109], v[120:121], s[72:73], v[106:107] op_sel_hi:[1,0,1]
	v_pk_fma_f32 v[112:113], v[118:119], s[72:73], v[112:113] op_sel_hi:[1,0,1]
	v_cvt_pk_bf16_f32 v106, v110, v111
	s_nop 0
	v_cvt_pk_bf16_f32 v107, v112, v113
	v_cvt_pk_bf16_f32 v108, v108, v109
	v_cvt_pk_bf16_f32 v109, v116, v117
	s_waitcnt vmcnt(2)
	v_mov_b32_e32 v120, v252
	v_mov_b32_e32 v121, v253
	v_mov_b32_e32 v122, v254
	v_mov_b32_e32 v123, v255
	v_add_u32_e32 v210, 0x50000, v210
	global_load_dwordx4 v[244:247], v210, s[26:27]
	global_load_dwordx4 v[252:255], v210, s[26:27] offset:16
	v_and_b32_e32 v118, 0xffff0000, v106
	global_store_dwordx4 v[126:127], v[106:109], off
	v_lshlrev_b32_e32 v116, 16, v107
	v_lshlrev_b32_e32 v110, 16, v109
	v_and_b32_e32 v112, 0xffff0000, v108
	s_waitcnt lgkmcnt(0)
	v_lshlrev_b32_e32 v111, 16, v120
	v_and_b32_e32 v113, 0xffff0000, v120
	v_lshlrev_b32_e32 v117, 16, v121
	v_and_b32_e32 v119, 0xffff0000, v121
	v_lshlrev_b32_e32 v128, 16, v122
	v_and_b32_e32 v129, 0xffff0000, v122
	v_lshlrev_b32_e32 v130, 16, v123
	v_and_b32_e32 v131, 0xffff0000, v123
	v_sub_f32_e32 v121, v113, v124
	v_sub_f32_e32 v120, v111, v124
	v_sub_f32_e32 v123, v119, v124
	v_sub_f32_e32 v122, v117, v124
	v_sub_f32_e32 v129, v129, v124
	v_sub_f32_e32 v128, v128, v124
	v_sub_f32_e32 v131, v131, v124
	v_sub_f32_e32 v130, v130, v124
	v_pk_mul_f32 v[122:123], v[124:125], v[122:123] op_sel:[1,0]
	v_pk_mul_f32 v[120:121], v[124:125], v[120:121] op_sel:[1,0]
	v_pk_mul_f32 v[130:131], v[124:125], v[130:131] op_sel:[1,0]
	v_pk_mul_f32 v[124:125], v[124:125], v[128:129] op_sel:[1,0]
	v_pk_fma_f32 v[120:121], v[26:27], v[120:121], v[30:31]
	v_pk_fma_f32 v[122:123], v[28:29], v[122:123], v[32:33]
	v_pk_fma_f32 v[124:125], v[18:19], v[124:125], v[22:23]
	v_pk_fma_f32 v[128:129], v[20:21], v[130:131], v[24:25]
	v_pk_fma_f32 v[104:105], v[122:123], s[72:73], v[104:105] op_sel_hi:[1,0,1]
	v_pk_fma_f32 v[102:103], v[120:121], s[72:73], v[102:103] op_sel_hi:[1,0,1]
	v_pk_fma_f32 v[120:121], v[128:129], s[72:73], v[100:101] op_sel_hi:[1,0,1]
	v_pk_fma_f32 v[100:101], v[124:125], s[72:73], v[98:99] op_sel_hi:[1,0,1]
	v_cvt_pk_bf16_f32 v98, v102, v103
	v_cvt_pk_bf16_f32 v99, v104, v105
	v_lshlrev_b32_e32 v122, 16, v106
	v_lshlrev_b32_e32 v123, 16, v98
	v_cvt_pk_bf16_f32 v100, v100, v101
	v_cvt_pk_bf16_f32 v101, v120, v121
	v_mov_b32_e32 v119, v123
	v_and_b32_e32 v121, 0xffff0000, v98
	v_pk_mul_f32 v[124:125], v[122:123], v[122:123]
	v_pk_mul_f32 v[130:131], v[118:119], v[118:119]
	v_and_b32_e32 v120, 0xffff0000, v107
	v_mov_b32_e32 v117, v121
	global_store_dwordx4 v[126:127], v[98:101], off offset:16
	v_pk_mul_f32 v[134:135], v[116:117], v[116:117]
	v_pk_mul_f32 v[106:107], v[120:121], v[120:121]
	v_lshlrev_b32_e32 v126, 16, v108
	v_lshlrev_b32_e32 v127, 16, v99
	v_and_b32_e32 v99, 0xffff0000, v99
	v_and_b32_e32 v98, 0xffff0000, v109
	v_pk_mov_b32 v[138:139], v[122:123], v[124:125] op_sel:[1,0]
	v_pk_mov_b32 v[130:131], v[120:121], v[130:131] op_sel:[1,0]
	v_and_b32_e32 v103, 0xffff0000, v101
	v_and_b32_e32 v102, 0xffff0000, v100
	v_mov_b32_e32 v111, v99
	v_pk_add_f32 v[130:131], v[138:139], v[130:131]
	v_pk_mov_b32 v[134:135], v[126:127], v[134:135] op_sel:[1,0]
	v_pk_mov_b32 v[138:139], v[98:99], v[106:107] op_sel:[1,0]
	v_lshlrev_b32_e32 v104, 16, v100
	v_lshlrev_b32_e32 v105, 16, v101
	v_pk_mul_f32 v[100:101], v[102:103], v[102:103]
	v_pk_mul_f32 v[108:109], v[110:111], v[110:111]
	v_pk_mul_f32 v[136:137], v[98:99], v[98:99]
	v_pk_add_f32 v[134:135], v[134:135], v[138:139]
	v_pk_fma_f32 v[100:101], v[104:105], v[104:105], v[100:101]
	v_mov_b32_e32 v113, v127
	v_pk_add_f32 v[130:131], v[130:131], v[134:135]
	v_mov_b32_e32 v134, v104
	v_mov_b32_e32 v138, v102
	v_pk_mov_b32 v[104:105], v[104:105], v[108:109] op_sel:[1,0]
	v_pk_mov_b32 v[102:103], v[102:103], v[136:137] op_sel:[1,0]
	v_pk_add_f32 v[108:109], v[120:121], v[116:117]
	v_pk_mul_f32 v[128:129], v[126:127], v[126:127]
	v_pk_mul_f32 v[132:133], v[112:113], v[112:113]
	v_pk_add_f32 v[102:103], v[104:105], v[102:103]
	v_pk_add_f32 v[104:105], v[122:123], v[118:119]
	v_mov_b32_e32 v109, v107
	v_pk_add_f32 v[106:107], v[126:127], v[112:113]
	v_pk_add_f32 v[98:99], v[98:99], v[110:111]
	v_mov_b32_e32 v135, v128
	v_mov_b32_e32 v139, v132
	v_mov_b32_e32 v105, v125
	v_mov_b32_e32 v107, v129
	v_mov_b32_e32 v99, v137
	v_pk_add_f32 v[100:101], v[100:101], v[100:101] op_sel_hi:[0,1]
	v_pk_add_f32 v[132:133], v[134:135], v[138:139]
	v_pk_add_f32 v[104:105], v[104:105], v[108:109]
	v_pk_add_f32 v[98:99], v[106:107], v[98:99]
	v_pk_add_f32 v[102:103], v[132:133], v[102:103]
	v_pk_add_f32 v[98:99], v[104:105], v[98:99]
	v_mov_b32_e32 v100, v1
	v_pk_add_f32 v[102:103], v[130:131], v[102:103]
	v_pk_add_f32 v[98:99], v[98:99], v[100:101]
	s_nop 0
	v_pk_add_f32 v[98:99], v[102:103], v[98:99]
	ds_bpermute_b32 v100, v194, v98
	ds_bpermute_b32 v101, v194, v99
	s_waitcnt lgkmcnt(0)
; __device__ __forceinline__ float bf_lo(unsigned w) { return __uint_as_float(w << 16); }
; __device__ __forceinline__ float bf_hi(unsigned w) { return __uint_as_float(w & 0xffff0000u); }
;     __device__ __forceinline__ void operator()(const f32x4 (&acc)[2][2][4][2], const pg8::Unit& u, int wr, int wc, int fr, int fq, LAS unsigned char* lds, int par) const {
;     ...
;                 const int row = row0 + ai * 128 + m * 16, lrow = ai * 128 + wr * 64 + m * 16 + fr;
;                 const size_t ro = (size_t)row * D + c0;
;                 float mu = 0.f, rstd = 1.f; if (prev) { mu = rsb[2 * lrow]; rstd = rsb[2 * lrow + 1]; }
;                 float s1 = 0.f, s2 = 0.f;
; #pragma unroll
;                 for (int bj = 0; bj < 2; ++bj) {
;                     f32x4 r0, r1;
;                     if (prev) {
;                         const u32x4 w = *(const u32x4*)(tb + ro + bj * 8);
;                         r0 = (f32x4){bf_lo(w.x), bf_hi(w.x), bf_lo(w.y), bf_hi(w.y)}; r1 = (f32x4){bf_lo(w.z), bf_hi(w.z), bf_lo(w.w), bf_hi(w.w)};
;                         r0 = (r0 - mu) * rstd * gg[2 * bj] + bb[2 * bj]; r1 = (r1 - mu) * rstd * gg[2 * bj + 1] + bb[2 * bj + 1];
;                     } else { r0 = *(const f32x4*)(xin + ro + bj * 8); r1 = *(const f32x4*)(xin + ro + bj * 8 + 4); }
;                     const f32x4 t0 = r0 * ALPHA + acc[ai][bj][m][0], t1 = r1 * ALPHA + acc[ai][bj][m][1];
;                     if (xout != nullptr) { *(f32x4*)(xout + ro + bj * 8) = t0; *(f32x4*)(xout + ro + bj * 8 + 4) = t1; }
;                     const u32x4 pw = pack8(t0, t1);
;                     *(u32x4*)(tb + ro + bj * 8) = pw;
;                     const float a0 = bf_lo(pw.x), a1 = bf_hi(pw.x), a2 = bf_lo(pw.y), a3 = bf_hi(pw.y), a4 = bf_lo(pw.z), a5 = bf_hi(pw.z), a6 = bf_lo(pw.w), a7 = bf_hi(pw.w);
;                     s1 += ((a0 + a1) + (a2 + a3)) + ((a4 + a5) + (a6 + a7));
;                     s2 += ((a0 * a0 + a1 * a1) + (a2 * a2 + a3 * a3)) + ((a4 * a4 + a5 * a5) + (a6 * a6 + a7 * a7));
;                 }
;                 s1 += shflx(s1, 16, fr + 16 * fq); s1 += shflx(s1, 32, fr + 16 * fq); s2 += shflx(s2, 16, fr + 16 * fq); s2 += shflx(s2, 32, fr + 16 * fq);
;                 if (fq == 0) { float* sp = stats_out + ((size_t)row * 32 + u.pn * 4 + wc) * 2; sp[0] = s1; sp[1] = s2; }
	v_pk_add_f32 v[98:99], v[98:99], v[100:101]
	ds_bpermute_b32 v100, v195, v98
	ds_bpermute_b32 v101, v195, v99
	s_and_saveexec_b64 s[26:27], s[42:43]
	s_cbranch_execz .LBB0_217
	v_readlane_b32 s28, v251, 35
	v_lshlrev_b64 v[102:103], 8, v[114:115]
	v_readlane_b32 s29, v251, 36
	s_waitcnt lgkmcnt(0)
	v_pk_add_f32 v[98:99], v[98:99], v[100:101]
	v_lshl_add_u64 v[102:103], s[28:29], 0, v[102:103]
	v_lshl_add_u64 v[102:103], s[24:25], 3, v[102:103]
	global_store_dwordx2 v[102:103], v[98:99], off
.LBB0_217:
	s_or_b64 exec, exec, s[26:27]
	v_add_u32_e32 v98, 0x80, v184
	v_ashrrev_i32_e32 v99, 31, v98
	v_readlane_b32 s26, v251, 31
	s_waitcnt lgkmcnt(0)
	v_lshlrev_b64 v[100:101], 12, v[98:99]
	v_readlane_b32 s27, v251, 32
	ds_read_b64 v[108:109], v200 offset:1024
	s_nop 0
	v_lshl_add_u64 v[100:101], s[26:27], 0, v[100:101]
	v_lshl_add_u64 v[110:111], v[182:183], 1, v[100:101]
	s_waitcnt vmcnt(3) lgkmcnt(0)
	v_mov_b32_e32 v100, v244
	v_mov_b32_e32 v101, v245
	v_mov_b32_e32 v102, v246
	v_mov_b32_e32 v103, v247
	v_lshlrev_b32_e32 v104, 16, v100
	v_and_b32_e32 v100, 0xffff0000, v100
	v_lshlrev_b32_e32 v105, 16, v101
	v_and_b32_e32 v106, 0xffff0000, v101
	v_lshlrev_b32_e32 v107, 16, v102
	v_and_b32_e32 v112, 0xffff0000, v102
	v_lshlrev_b32_e32 v113, 16, v103
	v_and_b32_e32 v114, 0xffff0000, v103
	v_sub_f32_e32 v101, v100, v108
	v_sub_f32_e32 v100, v104, v108
	v_sub_f32_e32 v103, v106, v108
	v_sub_f32_e32 v102, v105, v108
	v_sub_f32_e32 v105, v112, v108
	v_sub_f32_e32 v104, v107, v108
	v_sub_f32_e32 v107, v114, v108
	v_sub_f32_e32 v106, v113, v108
	v_pk_mul_f32 v[100:101], v[108:109], v[100:101] op_sel:[1,0]
	v_pk_mul_f32 v[106:107], v[108:109], v[106:107] op_sel:[1,0]
	v_pk_mul_f32 v[104:105], v[108:109], v[104:105] op_sel:[1,0]
	v_pk_mul_f32 v[102:103], v[108:109], v[102:103] op_sel:[1,0]
	v_pk_fma_f32 v[100:101], v[54:55], v[100:101], v[50:51]
	v_pk_fma_f32 v[104:105], v[42:43], v[104:105], v[46:47]
	v_pk_fma_f32 v[106:107], v[44:45], v[106:107], v[48:49]
	v_pk_fma_f32 v[102:103], v[56:57], v[102:103], v[52:53]
	v_pk_fma_f32 v[94:95], v[100:101], s[72:73], v[94:95] op_sel_hi:[1,0,1]
	v_pk_fma_f32 v[100:101], v[106:107], s[72:73], v[92:93] op_sel_hi:[1,0,1]
	v_pk_fma_f32 v[92:93], v[104:105], s[72:73], v[90:91] op_sel_hi:[1,0,1]
	v_pk_fma_f32 v[96:97], v[102:103], s[72:73], v[96:97] op_sel_hi:[1,0,1]
	v_cvt_pk_bf16_f32 v90, v94, v95
	s_nop 0
	v_cvt_pk_bf16_f32 v91, v96, v97
	v_cvt_pk_bf16_f32 v92, v92, v93
	v_cvt_pk_bf16_f32 v93, v100, v101
	s_waitcnt vmcnt(2)
	v_mov_b32_e32 v104, v252
	v_mov_b32_e32 v105, v253
	v_mov_b32_e32 v106, v254
	v_mov_b32_e32 v107, v255
	v_add_u32_e32 v210, 0x10000, v210
	global_load_dwordx4 v[244:247], v210, s[26:27]
	global_load_dwordx4 v[252:255], v210, s[26:27] offset:16
	v_and_b32_e32 v102, 0xffff0000, v90
	global_store_dwordx4 v[110:111], v[90:93], off
	v_lshlrev_b32_e32 v100, 16, v91
	v_lshlrev_b32_e32 v94, 16, v93
	v_and_b32_e32 v96, 0xffff0000, v92
	s_waitcnt lgkmcnt(0)
	v_lshlrev_b32_e32 v95, 16, v104
	v_and_b32_e32 v97, 0xffff0000, v104
	v_lshlrev_b32_e32 v101, 16, v105
	v_and_b32_e32 v103, 0xffff0000, v105
	v_lshlrev_b32_e32 v112, 16, v106
	v_and_b32_e32 v113, 0xffff0000, v106
	v_lshlrev_b32_e32 v114, 16, v107
	v_and_b32_e32 v115, 0xffff0000, v107
	v_sub_f32_e32 v105, v97, v108
	v_sub_f32_e32 v104, v95, v108
	v_sub_f32_e32 v107, v103, v108
	v_sub_f32_e32 v106, v101, v108
	v_sub_f32_e32 v113, v113, v108
	v_sub_f32_e32 v112, v112, v108
	v_sub_f32_e32 v115, v115, v108
	v_sub_f32_e32 v114, v114, v108
	v_pk_mul_f32 v[106:107], v[108:109], v[106:107] op_sel:[1,0]
	v_pk_mul_f32 v[104:105], v[108:109], v[104:105] op_sel:[1,0]
	v_pk_mul_f32 v[114:115], v[108:109], v[114:115] op_sel:[1,0]
	v_pk_mul_f32 v[108:109], v[108:109], v[112:113] op_sel:[1,0]
	v_pk_fma_f32 v[104:105], v[26:27], v[104:105], v[30:31]
	v_pk_fma_f32 v[106:107], v[28:29], v[106:107], v[32:33]
	v_pk_fma_f32 v[108:109], v[18:19], v[108:109], v[22:23]
	v_pk_fma_f32 v[112:113], v[20:21], v[114:115], v[24:25]
	v_pk_fma_f32 v[88:89], v[106:107], s[72:73], v[88:89] op_sel_hi:[1,0,1]
	v_pk_fma_f32 v[86:87], v[104:105], s[72:73], v[86:87] op_sel_hi:[1,0,1]
	v_pk_fma_f32 v[104:105], v[112:113], s[72:73], v[84:85] op_sel_hi:[1,0,1]
	v_pk_fma_f32 v[84:85], v[108:109], s[72:73], v[82:83] op_sel_hi:[1,0,1]
	v_cvt_pk_bf16_f32 v82, v86, v87
	v_cvt_pk_bf16_f32 v83, v88, v89
	v_lshlrev_b32_e32 v106, 16, v90
	v_lshlrev_b32_e32 v107, 16, v82
	v_cvt_pk_bf16_f32 v84, v84, v85
	v_cvt_pk_bf16_f32 v85, v104, v105
	v_mov_b32_e32 v103, v107
	v_and_b32_e32 v105, 0xffff0000, v82
	v_pk_mul_f32 v[108:109], v[106:107], v[106:107]
	v_pk_mul_f32 v[114:115], v[102:103], v[102:103]
	v_and_b32_e32 v104, 0xffff0000, v91
	v_mov_b32_e32 v101, v105
	global_store_dwordx4 v[110:111], v[82:85], off offset:16
	v_pk_mul_f32 v[118:119], v[100:101], v[100:101]
	v_pk_mul_f32 v[90:91], v[104:105], v[104:105]
	v_lshlrev_b32_e32 v110, 16, v92
	v_lshlrev_b32_e32 v111, 16, v83
	v_and_b32_e32 v83, 0xffff0000, v83
	v_and_b32_e32 v82, 0xffff0000, v93
	v_pk_mov_b32 v[122:123], v[106:107], v[108:109] op_sel:[1,0]
	v_pk_mov_b32 v[114:115], v[104:105], v[114:115] op_sel:[1,0]
	v_and_b32_e32 v87, 0xffff0000, v85
	v_and_b32_e32 v86, 0xffff0000, v84
	v_mov_b32_e32 v95, v83
	v_pk_add_f32 v[114:115], v[122:123], v[114:115]
	v_pk_mov_b32 v[118:119], v[110:111], v[118:119] op_sel:[1,0]
	v_pk_mov_b32 v[122:123], v[82:83], v[90:91] op_sel:[1,0]
	v_lshlrev_b32_e32 v88, 16, v84
	v_lshlrev_b32_e32 v89, 16, v85
	v_pk_mul_f32 v[84:85], v[86:87], v[86:87]
	v_pk_mul_f32 v[92:93], v[94:95], v[94:95]
	v_pk_mul_f32 v[120:121], v[82:83], v[82:83]
	v_pk_add_f32 v[118:119], v[118:119], v[122:123]
	v_pk_fma_f32 v[84:85], v[88:89], v[88:89], v[84:85]
	v_mov_b32_e32 v97, v111
	v_pk_add_f32 v[114:115], v[114:115], v[118:119]
	v_mov_b32_e32 v118, v88
	v_mov_b32_e32 v122, v86
	v_pk_mov_b32 v[88:89], v[88:89], v[92:93] op_sel:[1,0]
	v_pk_mov_b32 v[86:87], v[86:87], v[120:121] op_sel:[1,0]
	v_pk_add_f32 v[92:93], v[104:105], v[100:101]
	v_pk_mul_f32 v[112:113], v[110:111], v[110:111]
	v_pk_mul_f32 v[116:117], v[96:97], v[96:97]
	v_pk_add_f32 v[86:87], v[88:89], v[86:87]
	v_pk_add_f32 v[88:89], v[106:107], v[102:103]
	v_mov_b32_e32 v93, v91
	v_pk_add_f32 v[90:91], v[110:111], v[96:97]
	v_pk_add_f32 v[82:83], v[82:83], v[94:95]
	v_mov_b32_e32 v119, v112
	v_mov_b32_e32 v123, v116
	v_mov_b32_e32 v89, v109
	v_mov_b32_e32 v91, v113
	v_mov_b32_e32 v83, v121
	v_pk_add_f32 v[84:85], v[84:85], v[84:85] op_sel_hi:[0,1]
	v_pk_add_f32 v[116:117], v[118:119], v[122:123]
	v_pk_add_f32 v[88:89], v[88:89], v[92:93]
	v_pk_add_f32 v[82:83], v[90:91], v[82:83]
	v_pk_add_f32 v[86:87], v[116:117], v[86:87]
	v_pk_add_f32 v[82:83], v[88:89], v[82:83]
	v_mov_b32_e32 v84, v1
	v_pk_add_f32 v[86:87], v[114:115], v[86:87]
	v_pk_add_f32 v[82:83], v[82:83], v[84:85]
	s_nop 0
	v_pk_add_f32 v[82:83], v[86:87], v[82:83]
	ds_bpermute_b32 v84, v194, v82
	ds_bpermute_b32 v85, v194, v83
	s_waitcnt lgkmcnt(0)
; __device__ __forceinline__ float bf_lo(unsigned w) { return __uint_as_float(w << 16); }
; __device__ __forceinline__ float bf_hi(unsigned w) { return __uint_as_float(w & 0xffff0000u); }
;     __device__ __forceinline__ void operator()(const f32x4 (&acc)[2][2][4][2], const pg8::Unit& u, int wr, int wc, int fr, int fq, LAS unsigned char* lds, int par) const {
;     ...
;                 const int row = row0 + ai * 128 + m * 16, lrow = ai * 128 + wr * 64 + m * 16 + fr;
;                 const size_t ro = (size_t)row * D + c0;
;                 float mu = 0.f, rstd = 1.f; if (prev) { mu = rsb[2 * lrow]; rstd = rsb[2 * lrow + 1]; }
;                 float s1 = 0.f, s2 = 0.f;
; #pragma unroll
;                 for (int bj = 0; bj < 2; ++bj) {
;                     f32x4 r0, r1;
;                     if (prev) {
;                         const u32x4 w = *(const u32x4*)(tb + ro + bj * 8);
;                         r0 = (f32x4){bf_lo(w.x), bf_hi(w.x), bf_lo(w.y), bf_hi(w.y)}; r1 = (f32x4){bf_lo(w.z), bf_hi(w.z), bf_lo(w.w), bf_hi(w.w)};
;                         r0 = (r0 - mu) * rstd * gg[2 * bj] + bb[2 * bj]; r1 = (r1 - mu) * rstd * gg[2 * bj + 1] + bb[2 * bj + 1];
;                     } else { r0 = *(const f32x4*)(xin + ro + bj * 8); r1 = *(const f32x4*)(xin + ro + bj * 8 + 4); }
;                     const f32x4 t0 = r0 * ALPHA + acc[ai][bj][m][0], t1 = r1 * ALPHA + acc[ai][bj][m][1];
;                     if (xout != nullptr) { *(f32x4*)(xout + ro + bj * 8) = t0; *(f32x4*)(xout + ro + bj * 8 + 4) = t1; }
;                     const u32x4 pw = pack8(t0, t1);
;                     *(u32x4*)(tb + ro + bj * 8) = pw;
;                     const float a0 = bf_lo(pw.x), a1 = bf_hi(pw.x), a2 = bf_lo(pw.y), a3 = bf_hi(pw.y), a4 = bf_lo(pw.z), a5 = bf_hi(pw.z), a6 = bf_lo(pw.w), a7 = bf_hi(pw.w);
;                     s1 += ((a0 + a1) + (a2 + a3)) + ((a4 + a5) + (a6 + a7));
;                     s2 += ((a0 * a0 + a1 * a1) + (a2 * a2 + a3 * a3)) + ((a4 * a4 + a5 * a5) + (a6 * a6 + a7 * a7));
;                 }
;                 s1 += shflx(s1, 16, fr + 16 * fq); s1 += shflx(s1, 32, fr + 16 * fq); s2 += shflx(s2, 16, fr + 16 * fq); s2 += shflx(s2, 32, fr + 16 * fq);
;                 if (fq == 0) { float* sp = stats_out + ((size_t)row * 32 + u.pn * 4 + wc) * 2; sp[0] = s1; sp[1] = s2; }
	v_pk_add_f32 v[82:83], v[82:83], v[84:85]
	ds_bpermute_b32 v84, v195, v82
	ds_bpermute_b32 v85, v195, v83
	s_and_saveexec_b64 s[26:27], s[42:43]
	s_cbranch_execz .LBB0_219
	v_readlane_b32 s28, v251, 35
	v_lshlrev_b64 v[86:87], 8, v[98:99]
	v_readlane_b32 s29, v251, 36
	s_waitcnt lgkmcnt(0)
	v_pk_add_f32 v[82:83], v[82:83], v[84:85]
	v_lshl_add_u64 v[86:87], s[28:29], 0, v[86:87]
	v_lshl_add_u64 v[86:87], s[24:25], 3, v[86:87]
	global_store_dwordx2 v[86:87], v[82:83], off
.LBB0_219:
	s_or_b64 exec, exec, s[26:27]
	v_add_u32_e32 v82, 0x90, v184
	v_ashrrev_i32_e32 v83, 31, v82
	v_readlane_b32 s26, v251, 31
	s_waitcnt lgkmcnt(0)
	v_lshlrev_b64 v[84:85], 12, v[82:83]
	v_readlane_b32 s27, v251, 32
	ds_read_b64 v[92:93], v200 offset:1152
	s_nop 0
	v_lshl_add_u64 v[84:85], s[26:27], 0, v[84:85]
	v_lshl_add_u64 v[94:95], v[182:183], 1, v[84:85]
	s_waitcnt vmcnt(3) lgkmcnt(0)
	v_mov_b32_e32 v84, v244
	v_mov_b32_e32 v85, v245
	v_mov_b32_e32 v86, v246
	v_mov_b32_e32 v87, v247
	v_lshlrev_b32_e32 v88, 16, v84
	v_and_b32_e32 v84, 0xffff0000, v84
	v_lshlrev_b32_e32 v89, 16, v85
	v_and_b32_e32 v90, 0xffff0000, v85
	v_lshlrev_b32_e32 v91, 16, v86
	v_and_b32_e32 v96, 0xffff0000, v86
	v_lshlrev_b32_e32 v97, 16, v87
	v_and_b32_e32 v98, 0xffff0000, v87
	v_sub_f32_e32 v85, v84, v92
	v_sub_f32_e32 v84, v88, v92
	v_sub_f32_e32 v87, v90, v92
	v_sub_f32_e32 v86, v89, v92
	v_sub_f32_e32 v89, v96, v92
	v_sub_f32_e32 v88, v91, v92
	v_sub_f32_e32 v91, v98, v92
	v_sub_f32_e32 v90, v97, v92
	v_pk_mul_f32 v[84:85], v[92:93], v[84:85] op_sel:[1,0]
	v_pk_mul_f32 v[90:91], v[92:93], v[90:91] op_sel:[1,0]
	v_pk_mul_f32 v[88:89], v[92:93], v[88:89] op_sel:[1,0]
	v_pk_mul_f32 v[86:87], v[92:93], v[86:87] op_sel:[1,0]
	v_pk_fma_f32 v[84:85], v[54:55], v[84:85], v[50:51]
	v_pk_fma_f32 v[88:89], v[42:43], v[88:89], v[46:47]
	v_pk_fma_f32 v[90:91], v[44:45], v[90:91], v[48:49]
	v_pk_fma_f32 v[86:87], v[56:57], v[86:87], v[52:53]
	v_pk_fma_f32 v[78:79], v[84:85], s[72:73], v[78:79] op_sel_hi:[1,0,1]
	v_pk_fma_f32 v[84:85], v[90:91], s[72:73], v[76:77] op_sel_hi:[1,0,1]
	v_pk_fma_f32 v[76:77], v[88:89], s[72:73], v[74:75] op_sel_hi:[1,0,1]
	v_pk_fma_f32 v[80:81], v[86:87], s[72:73], v[80:81] op_sel_hi:[1,0,1]
	v_cvt_pk_bf16_f32 v74, v78, v79
	s_nop 0
	v_cvt_pk_bf16_f32 v75, v80, v81
	v_cvt_pk_bf16_f32 v76, v76, v77
	v_cvt_pk_bf16_f32 v77, v84, v85
	s_waitcnt vmcnt(2)
	v_mov_b32_e32 v88, v252
	v_mov_b32_e32 v89, v253
	v_mov_b32_e32 v90, v254
	v_mov_b32_e32 v91, v255
	v_add_u32_e32 v210, 0x10000, v210
	global_load_dwordx4 v[244:247], v210, s[26:27]
	global_load_dwordx4 v[252:255], v210, s[26:27] offset:16
	v_and_b32_e32 v86, 0xffff0000, v74
	global_store_dwordx4 v[94:95], v[74:77], off
	v_lshlrev_b32_e32 v84, 16, v75
	v_lshlrev_b32_e32 v78, 16, v77
	v_and_b32_e32 v80, 0xffff0000, v76
	s_waitcnt lgkmcnt(0)
	v_lshlrev_b32_e32 v79, 16, v88
	v_and_b32_e32 v81, 0xffff0000, v88
	v_lshlrev_b32_e32 v85, 16, v89
	v_and_b32_e32 v87, 0xffff0000, v89
	v_lshlrev_b32_e32 v96, 16, v90
	v_and_b32_e32 v97, 0xffff0000, v90
	v_lshlrev_b32_e32 v98, 16, v91
	v_and_b32_e32 v99, 0xffff0000, v91
	v_sub_f32_e32 v89, v81, v92
	v_sub_f32_e32 v88, v79, v92
	v_sub_f32_e32 v91, v87, v92
	v_sub_f32_e32 v90, v85, v92
	v_sub_f32_e32 v97, v97, v92
	v_sub_f32_e32 v96, v96, v92
	v_sub_f32_e32 v99, v99, v92
	v_sub_f32_e32 v98, v98, v92
	v_pk_mul_f32 v[90:91], v[92:93], v[90:91] op_sel:[1,0]
	v_pk_mul_f32 v[88:89], v[92:93], v[88:89] op_sel:[1,0]
	v_pk_mul_f32 v[98:99], v[92:93], v[98:99] op_sel:[1,0]
	v_pk_mul_f32 v[92:93], v[92:93], v[96:97] op_sel:[1,0]
	v_pk_fma_f32 v[88:89], v[26:27], v[88:89], v[30:31]
	v_pk_fma_f32 v[90:91], v[28:29], v[90:91], v[32:33]
	v_pk_fma_f32 v[92:93], v[18:19], v[92:93], v[22:23]
	v_pk_fma_f32 v[96:97], v[20:21], v[98:99], v[24:25]
	v_pk_fma_f32 v[72:73], v[90:91], s[72:73], v[72:73] op_sel_hi:[1,0,1]
	v_pk_fma_f32 v[70:71], v[88:89], s[72:73], v[70:71] op_sel_hi:[1,0,1]
	v_pk_fma_f32 v[88:89], v[96:97], s[72:73], v[68:69] op_sel_hi:[1,0,1]
	v_pk_fma_f32 v[68:69], v[92:93], s[72:73], v[66:67] op_sel_hi:[1,0,1]
	v_cvt_pk_bf16_f32 v66, v70, v71
	v_cvt_pk_bf16_f32 v67, v72, v73
	v_lshlrev_b32_e32 v90, 16, v74
	v_lshlrev_b32_e32 v91, 16, v66
	v_cvt_pk_bf16_f32 v68, v68, v69
	v_cvt_pk_bf16_f32 v69, v88, v89
	v_mov_b32_e32 v87, v91
	v_and_b32_e32 v89, 0xffff0000, v66
	v_pk_mul_f32 v[92:93], v[90:91], v[90:91]
	v_pk_mul_f32 v[98:99], v[86:87], v[86:87]
	v_and_b32_e32 v88, 0xffff0000, v75
	v_mov_b32_e32 v85, v89
	global_store_dwordx4 v[94:95], v[66:69], off offset:16
	v_pk_mul_f32 v[102:103], v[84:85], v[84:85]
	v_pk_mul_f32 v[74:75], v[88:89], v[88:89]
	v_lshlrev_b32_e32 v94, 16, v76
	v_lshlrev_b32_e32 v95, 16, v67
	v_and_b32_e32 v67, 0xffff0000, v67
	v_and_b32_e32 v66, 0xffff0000, v77
	v_pk_mov_b32 v[106:107], v[90:91], v[92:93] op_sel:[1,0]
	v_pk_mov_b32 v[98:99], v[88:89], v[98:99] op_sel:[1,0]
	v_and_b32_e32 v71, 0xffff0000, v69
	v_and_b32_e32 v70, 0xffff0000, v68
	v_mov_b32_e32 v79, v67
	v_pk_add_f32 v[98:99], v[106:107], v[98:99]
	v_pk_mov_b32 v[102:103], v[94:95], v[102:103] op_sel:[1,0]
	v_pk_mov_b32 v[106:107], v[66:67], v[74:75] op_sel:[1,0]
	v_lshlrev_b32_e32 v72, 16, v68
	v_lshlrev_b32_e32 v73, 16, v69
	v_pk_mul_f32 v[68:69], v[70:71], v[70:71]
	v_pk_mul_f32 v[76:77], v[78:79], v[78:79]
	v_pk_mul_f32 v[104:105], v[66:67], v[66:67]
	v_pk_add_f32 v[102:103], v[102:103], v[106:107]
	v_pk_fma_f32 v[68:69], v[72:73], v[72:73], v[68:69]
	v_mov_b32_e32 v81, v95
	v_pk_add_f32 v[98:99], v[98:99], v[102:103]
	v_mov_b32_e32 v102, v72
	v_mov_b32_e32 v106, v70
	v_pk_mov_b32 v[72:73], v[72:73], v[76:77] op_sel:[1,0]
	v_pk_mov_b32 v[70:71], v[70:71], v[104:105] op_sel:[1,0]
	v_pk_add_f32 v[76:77], v[88:89], v[84:85]
	v_pk_mul_f32 v[96:97], v[94:95], v[94:95]
	v_pk_mul_f32 v[100:101], v[80:81], v[80:81]
	v_pk_add_f32 v[70:71], v[72:73], v[70:71]
	v_pk_add_f32 v[72:73], v[90:91], v[86:87]
	v_mov_b32_e32 v77, v75
	v_pk_add_f32 v[74:75], v[94:95], v[80:81]
	v_pk_add_f32 v[66:67], v[66:67], v[78:79]
	v_mov_b32_e32 v103, v96
	v_mov_b32_e32 v107, v100
	v_mov_b32_e32 v73, v93
	v_mov_b32_e32 v75, v97
	v_mov_b32_e32 v67, v105
	v_pk_add_f32 v[68:69], v[68:69], v[68:69] op_sel_hi:[0,1]
	v_pk_add_f32 v[100:101], v[102:103], v[106:107]
	v_pk_add_f32 v[72:73], v[72:73], v[76:77]
	v_pk_add_f32 v[66:67], v[74:75], v[66:67]
	v_pk_add_f32 v[70:71], v[100:101], v[70:71]
	v_pk_add_f32 v[66:67], v[72:73], v[66:67]
	v_mov_b32_e32 v68, v1
	v_pk_add_f32 v[70:71], v[98:99], v[70:71]
	v_pk_add_f32 v[66:67], v[66:67], v[68:69]
	s_nop 0
	v_pk_add_f32 v[66:67], v[70:71], v[66:67]
	ds_bpermute_b32 v68, v194, v66
	ds_bpermute_b32 v69, v194, v67
	s_waitcnt lgkmcnt(0)
	v_pk_add_f32 v[66:67], v[66:67], v[68:69]
	ds_bpermute_b32 v68, v195, v66
	ds_bpermute_b32 v69, v195, v67
	s_and_saveexec_b64 s[26:27], s[42:43]
	s_cbranch_execz .LBB0_221
; __device__ __forceinline__ float bf_lo(unsigned w) { return __uint_as_float(w << 16); }
; __device__ __forceinline__ float bf_hi(unsigned w) { return __uint_as_float(w & 0xffff0000u); }
;     __device__ __forceinline__ void operator()(const f32x4 (&acc)[2][2][4][2], const pg8::Unit& u, int wr, int wc, int fr, int fq, LAS unsigned char* lds, int par) const {
;     ...
;                 const int row = row0 + ai * 128 + m * 16, lrow = ai * 128 + wr * 64 + m * 16 + fr;
;                 const size_t ro = (size_t)row * D + c0;
;                 float mu = 0.f, rstd = 1.f; if (prev) { mu = rsb[2 * lrow]; rstd = rsb[2 * lrow + 1]; }
;                 float s1 = 0.f, s2 = 0.f;
; #pragma unroll
;                 for (int bj = 0; bj < 2; ++bj) {
;                     f32x4 r0, r1;
;                     if (prev) {
;                         const u32x4 w = *(const u32x4*)(tb + ro + bj * 8);
;                         r0 = (f32x4){bf_lo(w.x), bf_hi(w.x), bf_lo(w.y), bf_hi(w.y)}; r1 = (f32x4){bf_lo(w.z), bf_hi(w.z), bf_lo(w.w), bf_hi(w.w)};
;                         r0 = (r0 - mu) * rstd * gg[2 * bj] + bb[2 * bj]; r1 = (r1 - mu) * rstd * gg[2 * bj + 1] + bb[2 * bj + 1];
;                     } else { r0 = *(const f32x4*)(xin + ro + bj * 8); r1 = *(const f32x4*)(xin + ro + bj * 8 + 4); }
;                     const f32x4 t0 = r0 * ALPHA + acc[ai][bj][m][0], t1 = r1 * ALPHA + acc[ai][bj][m][1];
;                     if (xout != nullptr) { *(f32x4*)(xout + ro + bj * 8) = t0; *(f32x4*)(xout + ro + bj * 8 + 4) = t1; }
;                     const u32x4 pw = pack8(t0, t1);
;                     *(u32x4*)(tb + ro + bj * 8) = pw;
;                     const float a0 = bf_lo(pw.x), a1 = bf_hi(pw.x), a2 = bf_lo(pw.y), a3 = bf_hi(pw.y), a4 = bf_lo(pw.z), a5 = bf_hi(pw.z), a6 = bf_lo(pw.w), a7 = bf_hi(pw.w);
;                     s1 += ((a0 + a1) + (a2 + a3)) + ((a4 + a5) + (a6 + a7));
;                     s2 += ((a0 * a0 + a1 * a1) + (a2 * a2 + a3 * a3)) + ((a4 * a4 + a5 * a5) + (a6 * a6 + a7 * a7));
;                 }
;                 s1 += shflx(s1, 16, fr + 16 * fq); s1 += shflx(s1, 32, fr + 16 * fq); s2 += shflx(s2, 16, fr + 16 * fq); s2 += shflx(s2, 32, fr + 16 * fq);
;                 if (fq == 0) { float* sp = stats_out + ((size_t)row * 32 + u.pn * 4 + wc) * 2; sp[0] = s1; sp[1] = s2; }
	v_readlane_b32 s28, v251, 35
	v_lshlrev_b64 v[70:71], 8, v[82:83]
	v_readlane_b32 s29, v251, 36
	s_waitcnt lgkmcnt(0)
	v_pk_add_f32 v[66:67], v[66:67], v[68:69]
	v_lshl_add_u64 v[70:71], s[28:29], 0, v[70:71]
	v_lshl_add_u64 v[70:71], s[24:25], 3, v[70:71]
	global_store_dwordx2 v[70:71], v[66:67], off
.LBB0_221:
	s_or_b64 exec, exec, s[26:27]
	v_add_u32_e32 v66, 0xa0, v184
	v_ashrrev_i32_e32 v67, 31, v66
	v_readlane_b32 s26, v251, 31
	s_waitcnt lgkmcnt(0)
	v_lshlrev_b64 v[68:69], 12, v[66:67]
	v_readlane_b32 s27, v251, 32
	ds_read_b64 v[76:77], v200 offset:1280
	s_nop 0
	v_lshl_add_u64 v[68:69], s[26:27], 0, v[68:69]
	v_lshl_add_u64 v[78:79], v[182:183], 1, v[68:69]
	s_waitcnt vmcnt(3) lgkmcnt(0)
	v_mov_b32_e32 v68, v244
	v_mov_b32_e32 v69, v245
	v_mov_b32_e32 v70, v246
	v_mov_b32_e32 v71, v247
	v_lshlrev_b32_e32 v72, 16, v68
	v_and_b32_e32 v68, 0xffff0000, v68
	v_lshlrev_b32_e32 v73, 16, v69
	v_and_b32_e32 v74, 0xffff0000, v69
	v_lshlrev_b32_e32 v75, 16, v70
	v_and_b32_e32 v80, 0xffff0000, v70
	v_lshlrev_b32_e32 v81, 16, v71
	v_and_b32_e32 v82, 0xffff0000, v71
	v_sub_f32_e32 v69, v68, v76
	v_sub_f32_e32 v68, v72, v76
	v_sub_f32_e32 v71, v74, v76
	v_sub_f32_e32 v70, v73, v76
	v_sub_f32_e32 v73, v80, v76
	v_sub_f32_e32 v72, v75, v76
	v_sub_f32_e32 v75, v82, v76
	v_sub_f32_e32 v74, v81, v76
	v_pk_mul_f32 v[68:69], v[76:77], v[68:69] op_sel:[1,0]
	v_pk_mul_f32 v[74:75], v[76:77], v[74:75] op_sel:[1,0]
	v_pk_mul_f32 v[72:73], v[76:77], v[72:73] op_sel:[1,0]
	v_pk_mul_f32 v[70:71], v[76:77], v[70:71] op_sel:[1,0]
	v_pk_fma_f32 v[68:69], v[54:55], v[68:69], v[50:51]
	v_pk_fma_f32 v[72:73], v[42:43], v[72:73], v[46:47]
	v_pk_fma_f32 v[74:75], v[44:45], v[74:75], v[48:49]
	v_pk_fma_f32 v[70:71], v[56:57], v[70:71], v[52:53]
	v_pk_fma_f32 v[62:63], v[68:69], s[72:73], v[62:63] op_sel_hi:[1,0,1]
	v_pk_fma_f32 v[68:69], v[74:75], s[72:73], v[60:61] op_sel_hi:[1,0,1]
	v_pk_fma_f32 v[60:61], v[72:73], s[72:73], v[58:59] op_sel_hi:[1,0,1]
	v_pk_fma_f32 v[64:65], v[70:71], s[72:73], v[64:65] op_sel_hi:[1,0,1]
	v_cvt_pk_bf16_f32 v58, v62, v63
	s_nop 0
	v_cvt_pk_bf16_f32 v59, v64, v65
	v_cvt_pk_bf16_f32 v60, v60, v61
	v_cvt_pk_bf16_f32 v61, v68, v69
	s_waitcnt vmcnt(2)
	v_mov_b32_e32 v72, v252
	v_mov_b32_e32 v73, v253
	v_mov_b32_e32 v74, v254
	v_mov_b32_e32 v75, v255
	v_add_u32_e32 v210, 0x10000, v210
	global_load_dwordx4 v[244:247], v210, s[26:27]
	global_load_dwordx4 v[252:255], v210, s[26:27] offset:16
	v_and_b32_e32 v70, 0xffff0000, v58
	global_store_dwordx4 v[78:79], v[58:61], off
	v_lshlrev_b32_e32 v68, 16, v59
	v_lshlrev_b32_e32 v62, 16, v61
	v_and_b32_e32 v64, 0xffff0000, v60
	s_waitcnt lgkmcnt(0)
	v_lshlrev_b32_e32 v63, 16, v72
	v_and_b32_e32 v65, 0xffff0000, v72
	v_lshlrev_b32_e32 v69, 16, v73
	v_and_b32_e32 v71, 0xffff0000, v73
	v_lshlrev_b32_e32 v80, 16, v74
	v_and_b32_e32 v81, 0xffff0000, v74
	v_lshlrev_b32_e32 v82, 16, v75
	v_and_b32_e32 v83, 0xffff0000, v75
	v_sub_f32_e32 v73, v65, v76
	v_sub_f32_e32 v72, v63, v76
	v_sub_f32_e32 v75, v71, v76
	v_sub_f32_e32 v74, v69, v76
	v_sub_f32_e32 v81, v81, v76
	v_sub_f32_e32 v80, v80, v76
	v_sub_f32_e32 v83, v83, v76
	v_sub_f32_e32 v82, v82, v76
	v_pk_mul_f32 v[74:75], v[76:77], v[74:75] op_sel:[1,0]
	v_pk_mul_f32 v[72:73], v[76:77], v[72:73] op_sel:[1,0]
	v_pk_mul_f32 v[82:83], v[76:77], v[82:83] op_sel:[1,0]
	v_pk_mul_f32 v[76:77], v[76:77], v[80:81] op_sel:[1,0]
	v_pk_fma_f32 v[72:73], v[26:27], v[72:73], v[30:31]
	v_pk_fma_f32 v[74:75], v[28:29], v[74:75], v[32:33]
	v_pk_fma_f32 v[76:77], v[18:19], v[76:77], v[22:23]
	v_pk_fma_f32 v[80:81], v[20:21], v[82:83], v[24:25]
	v_pk_fma_f32 v[40:41], v[74:75], s[72:73], v[40:41] op_sel_hi:[1,0,1]
	v_pk_fma_f32 v[38:39], v[72:73], s[72:73], v[38:39] op_sel_hi:[1,0,1]
	v_pk_fma_f32 v[72:73], v[80:81], s[72:73], v[36:37] op_sel_hi:[1,0,1]
	v_pk_fma_f32 v[36:37], v[76:77], s[72:73], v[34:35] op_sel_hi:[1,0,1]
	v_cvt_pk_bf16_f32 v34, v38, v39
	v_cvt_pk_bf16_f32 v35, v40, v41
	v_lshlrev_b32_e32 v74, 16, v58
	v_lshlrev_b32_e32 v75, 16, v34
	v_cvt_pk_bf16_f32 v36, v36, v37
	v_cvt_pk_bf16_f32 v37, v72, v73
	v_mov_b32_e32 v71, v75
	v_and_b32_e32 v73, 0xffff0000, v34
	v_pk_mul_f32 v[76:77], v[74:75], v[74:75]
	v_pk_mul_f32 v[82:83], v[70:71], v[70:71]
	v_and_b32_e32 v72, 0xffff0000, v59
	v_mov_b32_e32 v69, v73
	global_store_dwordx4 v[78:79], v[34:37], off offset:16
	v_pk_mul_f32 v[86:87], v[68:69], v[68:69]
	v_pk_mul_f32 v[58:59], v[72:73], v[72:73]
	v_lshlrev_b32_e32 v78, 16, v60
	v_lshlrev_b32_e32 v79, 16, v35
	v_and_b32_e32 v35, 0xffff0000, v35
	v_and_b32_e32 v34, 0xffff0000, v61
	v_pk_mov_b32 v[90:91], v[74:75], v[76:77] op_sel:[1,0]
	v_pk_mov_b32 v[82:83], v[72:73], v[82:83] op_sel:[1,0]
	v_and_b32_e32 v39, 0xffff0000, v37
	v_and_b32_e32 v38, 0xffff0000, v36
	v_mov_b32_e32 v63, v35
	v_pk_add_f32 v[82:83], v[90:91], v[82:83]
	v_pk_mov_b32 v[86:87], v[78:79], v[86:87] op_sel:[1,0]
	v_pk_mov_b32 v[90:91], v[34:35], v[58:59] op_sel:[1,0]
	v_lshlrev_b32_e32 v40, 16, v36
	v_lshlrev_b32_e32 v41, 16, v37
	v_pk_mul_f32 v[36:37], v[38:39], v[38:39]
	v_pk_mul_f32 v[60:61], v[62:63], v[62:63]
	v_pk_mul_f32 v[88:89], v[34:35], v[34:35]
	v_pk_add_f32 v[86:87], v[86:87], v[90:91]
	v_pk_fma_f32 v[36:37], v[40:41], v[40:41], v[36:37]
	v_mov_b32_e32 v65, v79
	v_pk_add_f32 v[82:83], v[82:83], v[86:87]
	v_mov_b32_e32 v86, v40
	v_mov_b32_e32 v90, v38
	v_pk_mov_b32 v[40:41], v[40:41], v[60:61] op_sel:[1,0]
	v_pk_mov_b32 v[38:39], v[38:39], v[88:89] op_sel:[1,0]
	v_pk_add_f32 v[60:61], v[72:73], v[68:69]
	v_pk_mul_f32 v[80:81], v[78:79], v[78:79]
	v_pk_mul_f32 v[84:85], v[64:65], v[64:65]
	v_pk_add_f32 v[38:39], v[40:41], v[38:39]
	v_pk_add_f32 v[40:41], v[74:75], v[70:71]
	v_mov_b32_e32 v61, v59
	v_pk_add_f32 v[58:59], v[78:79], v[64:65]
	v_pk_add_f32 v[34:35], v[34:35], v[62:63]
	v_mov_b32_e32 v87, v80
	v_mov_b32_e32 v91, v84
	v_mov_b32_e32 v41, v77
	v_mov_b32_e32 v59, v81
	v_mov_b32_e32 v35, v89
	v_pk_add_f32 v[36:37], v[36:37], v[36:37] op_sel_hi:[0,1]
	v_pk_add_f32 v[84:85], v[86:87], v[90:91]
	v_pk_add_f32 v[40:41], v[40:41], v[60:61]
	v_pk_add_f32 v[34:35], v[58:59], v[34:35]
	v_pk_add_f32 v[38:39], v[84:85], v[38:39]
	v_pk_add_f32 v[34:35], v[40:41], v[34:35]
	v_mov_b32_e32 v36, v1
	v_pk_add_f32 v[38:39], v[82:83], v[38:39]
	v_pk_add_f32 v[34:35], v[34:35], v[36:37]
	s_nop 0
	v_pk_add_f32 v[34:35], v[38:39], v[34:35]
	ds_bpermute_b32 v36, v194, v34
	ds_bpermute_b32 v37, v194, v35
	s_waitcnt lgkmcnt(0)
	v_pk_add_f32 v[34:35], v[34:35], v[36:37]
	ds_bpermute_b32 v36, v195, v34
	ds_bpermute_b32 v37, v195, v35
	s_and_saveexec_b64 s[26:27], s[42:43]
	s_cbranch_execz .LBB0_223
	v_readlane_b32 s28, v251, 35
	v_lshlrev_b64 v[38:39], 8, v[66:67]
	v_readlane_b32 s29, v251, 36
	s_waitcnt lgkmcnt(0)
	v_pk_add_f32 v[34:35], v[34:35], v[36:37]
	v_lshl_add_u64 v[38:39], s[28:29], 0, v[38:39]
	v_lshl_add_u64 v[38:39], s[24:25], 3, v[38:39]
	global_store_dwordx2 v[38:39], v[34:35], off
; __device__ __forceinline__ float bf_lo(unsigned w) { return __uint_as_float(w << 16); }
; __device__ __forceinline__ float bf_hi(unsigned w) { return __uint_as_float(w & 0xffff0000u); }
;     __device__ __forceinline__ void operator()(const f32x4 (&acc)[2][2][4][2], const pg8::Unit& u, int wr, int wc, int fr, int fq, LAS unsigned char* lds, int par) const {
;     ...
;                 const int row = row0 + ai * 128 + m * 16, lrow = ai * 128 + wr * 64 + m * 16 + fr;
;                 const size_t ro = (size_t)row * D + c0;
;                 float mu = 0.f, rstd = 1.f; if (prev) { mu = rsb[2 * lrow]; rstd = rsb[2 * lrow + 1]; }
;                 float s1 = 0.f, s2 = 0.f;
; #pragma unroll
;                 for (int bj = 0; bj < 2; ++bj) {
;                     f32x4 r0, r1;
;                     if (prev) {
;                         const u32x4 w = *(const u32x4*)(tb + ro + bj * 8);
;                         r0 = (f32x4){bf_lo(w.x), bf_hi(w.x), bf_lo(w.y), bf_hi(w.y)}; r1 = (f32x4){bf_lo(w.z), bf_hi(w.z), bf_lo(w.w), bf_hi(w.w)};
;                         r0 = (r0 - mu) * rstd * gg[2 * bj] + bb[2 * bj]; r1 = (r1 - mu) * rstd * gg[2 * bj + 1] + bb[2 * bj + 1];
;                     } else { r0 = *(const f32x4*)(xin + ro + bj * 8); r1 = *(const f32x4*)(xin + ro + bj * 8 + 4); }
;                     const f32x4 t0 = r0 * ALPHA + acc[ai][bj][m][0], t1 = r1 * ALPHA + acc[ai][bj][m][1];
;                     if (xout != nullptr) { *(f32x4*)(xout + ro + bj * 8) = t0; *(f32x4*)(xout + ro + bj * 8 + 4) = t1; }
;                     const u32x4 pw = pack8(t0, t1);
;                     *(u32x4*)(tb + ro + bj * 8) = pw;
;                     const float a0 = bf_lo(pw.x), a1 = bf_hi(pw.x), a2 = bf_lo(pw.y), a3 = bf_hi(pw.y), a4 = bf_lo(pw.z), a5 = bf_hi(pw.z), a6 = bf_lo(pw.w), a7 = bf_hi(pw.w);
;                     s1 += ((a0 + a1) + (a2 + a3)) + ((a4 + a5) + (a6 + a7));
;                     s2 += ((a0 * a0 + a1 * a1) + (a2 * a2 + a3 * a3)) + ((a4 * a4 + a5 * a5) + (a6 * a6 + a7 * a7));
;                 }
;                 s1 += shflx(s1, 16, fr + 16 * fq); s1 += shflx(s1, 32, fr + 16 * fq); s2 += shflx(s2, 16, fr + 16 * fq); s2 += shflx(s2, 32, fr + 16 * fq);
;                 if (fq == 0) { float* sp = stats_out + ((size_t)row * 32 + u.pn * 4 + wc) * 2; sp[0] = s1; sp[1] = s2; }
.LBB0_223:
	s_or_b64 exec, exec, s[26:27]
	v_add_u32_e32 v34, 0xb0, v184
	v_ashrrev_i32_e32 v35, 31, v34
	v_readlane_b32 s26, v251, 31
	s_waitcnt lgkmcnt(0)
	v_lshlrev_b64 v[36:37], 12, v[34:35]
	v_readlane_b32 s27, v251, 32
	ds_read_b64 v[58:59], v200 offset:1408
	s_nop 0
	v_lshl_add_u64 v[36:37], s[26:27], 0, v[36:37]
	v_lshl_add_u64 v[60:61], v[182:183], 1, v[36:37]
	s_waitcnt vmcnt(3) lgkmcnt(0)
	v_mov_b32_e32 v36, v244
	v_mov_b32_e32 v37, v245
	v_mov_b32_e32 v38, v246
	v_mov_b32_e32 v39, v247
	v_lshlrev_b32_e32 v40, 16, v36
	v_and_b32_e32 v36, 0xffff0000, v36
	v_lshlrev_b32_e32 v41, 16, v37
	v_and_b32_e32 v62, 0xffff0000, v37
	v_sub_f32_e32 v37, v36, v58
	v_sub_f32_e32 v36, v40, v58
	v_lshlrev_b32_e32 v63, 16, v38
	v_and_b32_e32 v64, 0xffff0000, v38
	v_lshlrev_b32_e32 v65, 16, v39
	v_and_b32_e32 v66, 0xffff0000, v39
	v_pk_mul_f32 v[36:37], v[58:59], v[36:37] op_sel:[1,0]
	v_sub_f32_e32 v38, v41, v58
	v_pk_fma_f32 v[36:37], v[54:55], v[36:37], v[50:51]
	v_sub_f32_e32 v41, v64, v58
	v_sub_f32_e32 v40, v63, v58
	v_sub_f32_e32 v51, v66, v58
	v_sub_f32_e32 v50, v65, v58
	v_sub_f32_e32 v39, v62, v58
	v_pk_mul_f32 v[50:51], v[58:59], v[50:51] op_sel:[1,0]
	v_pk_mul_f32 v[40:41], v[58:59], v[40:41] op_sel:[1,0]
	v_pk_mul_f32 v[38:39], v[58:59], v[38:39] op_sel:[1,0]
	v_pk_fma_f32 v[40:41], v[42:43], v[40:41], v[46:47]
	v_pk_fma_f32 v[42:43], v[44:45], v[50:51], v[48:49]
	v_pk_fma_f32 v[38:39], v[56:57], v[38:39], v[52:53]
	v_pk_fma_f32 v[14:15], v[36:37], s[72:73], v[14:15] op_sel_hi:[1,0,1]
	v_pk_fma_f32 v[36:37], v[42:43], s[72:73], v[12:13] op_sel_hi:[1,0,1]
	v_pk_fma_f32 v[12:13], v[40:41], s[72:73], v[10:11] op_sel_hi:[1,0,1]
	v_pk_fma_f32 v[16:17], v[38:39], s[72:73], v[16:17] op_sel_hi:[1,0,1]
	v_cvt_pk_bf16_f32 v10, v14, v15
	s_nop 0
	v_cvt_pk_bf16_f32 v11, v16, v17
	v_cvt_pk_bf16_f32 v12, v12, v13
	v_cvt_pk_bf16_f32 v13, v36, v37
	s_waitcnt vmcnt(2)
	v_mov_b32_e32 v40, v252
	v_mov_b32_e32 v41, v253
	v_mov_b32_e32 v42, v254
	v_mov_b32_e32 v43, v255
	v_and_b32_e32 v38, 0xffff0000, v10
	global_store_dwordx4 v[60:61], v[10:13], off
	v_lshlrev_b32_e32 v36, 16, v11
	v_lshlrev_b32_e32 v14, 16, v13
	v_and_b32_e32 v16, 0xffff0000, v12
	s_waitcnt lgkmcnt(0)
	v_lshlrev_b32_e32 v15, 16, v40
	v_and_b32_e32 v17, 0xffff0000, v40
	v_lshlrev_b32_e32 v37, 16, v41
	v_and_b32_e32 v39, 0xffff0000, v41
	v_lshlrev_b32_e32 v44, 16, v42
	v_and_b32_e32 v45, 0xffff0000, v42
	v_lshlrev_b32_e32 v46, 16, v43
	v_and_b32_e32 v47, 0xffff0000, v43
	v_sub_f32_e32 v41, v17, v58
	v_sub_f32_e32 v40, v15, v58
	v_sub_f32_e32 v43, v39, v58
	v_sub_f32_e32 v42, v37, v58
	v_pk_mul_f32 v[42:43], v[58:59], v[42:43] op_sel:[1,0]
	v_pk_mul_f32 v[40:41], v[58:59], v[40:41] op_sel:[1,0]
	v_pk_fma_f32 v[28:29], v[28:29], v[42:43], v[32:33]
	v_pk_fma_f32 v[26:27], v[26:27], v[40:41], v[30:31]
	v_sub_f32_e32 v31, v45, v58
	v_sub_f32_e32 v30, v44, v58
	v_sub_f32_e32 v33, v47, v58
	v_sub_f32_e32 v32, v46, v58
	v_pk_mul_f32 v[32:33], v[58:59], v[32:33] op_sel:[1,0]
	v_pk_mul_f32 v[30:31], v[58:59], v[30:31] op_sel:[1,0]
	v_pk_fma_f32 v[20:21], v[20:21], v[32:33], v[24:25]
	v_pk_fma_f32 v[18:19], v[18:19], v[30:31], v[22:23]
	v_pk_fma_f32 v[20:21], v[20:21], s[72:73], v[4:5] op_sel_hi:[1,0,1]
	v_pk_fma_f32 v[4:5], v[18:19], s[72:73], v[2:3] op_sel_hi:[1,0,1]
	v_pk_fma_f32 v[8:9], v[28:29], s[72:73], v[8:9] op_sel_hi:[1,0,1]
	v_pk_fma_f32 v[6:7], v[26:27], s[72:73], v[6:7] op_sel_hi:[1,0,1]
	v_and_b32_e32 v18, 0xffff0000, v11
	v_cvt_pk_bf16_f32 v2, v6, v7
	v_cvt_pk_bf16_f32 v3, v8, v9
	v_cvt_pk_bf16_f32 v4, v4, v5
	v_cvt_pk_bf16_f32 v5, v20, v21
	v_lshlrev_b32_e32 v20, 16, v10
	v_lshlrev_b32_e32 v21, 16, v2
	v_mov_b32_e32 v39, v21
	v_and_b32_e32 v19, 0xffff0000, v2
	v_pk_mul_f32 v[22:23], v[20:21], v[20:21]
	v_pk_mul_f32 v[28:29], v[38:39], v[38:39]
	v_mov_b32_e32 v37, v19
	global_store_dwordx4 v[60:61], v[2:5], off offset:16
	v_pk_mul_f32 v[32:33], v[36:37], v[36:37]
	v_pk_mul_f32 v[10:11], v[18:19], v[18:19]
	v_lshlrev_b32_e32 v24, 16, v12
	v_lshlrev_b32_e32 v25, 16, v3
	v_and_b32_e32 v3, 0xffff0000, v3
	v_and_b32_e32 v2, 0xffff0000, v13
	v_pk_mov_b32 v[42:43], v[20:21], v[22:23] op_sel:[1,0]
	v_pk_mov_b32 v[28:29], v[18:19], v[28:29] op_sel:[1,0]
	v_and_b32_e32 v7, 0xffff0000, v5
	v_and_b32_e32 v6, 0xffff0000, v4
	v_mov_b32_e32 v15, v3
	v_pk_add_f32 v[28:29], v[42:43], v[28:29]
	v_pk_mov_b32 v[32:33], v[24:25], v[32:33] op_sel:[1,0]
	v_pk_mov_b32 v[42:43], v[2:3], v[10:11] op_sel:[1,0]
	v_lshlrev_b32_e32 v8, 16, v4
	v_lshlrev_b32_e32 v9, 16, v5
	v_pk_mul_f32 v[4:5], v[6:7], v[6:7]
	v_pk_mul_f32 v[12:13], v[14:15], v[14:15]
	v_pk_mul_f32 v[40:41], v[2:3], v[2:3]
	v_pk_add_f32 v[32:33], v[32:33], v[42:43]
	v_pk_fma_f32 v[4:5], v[8:9], v[8:9], v[4:5]
	v_mov_b32_e32 v17, v25
	v_pk_add_f32 v[28:29], v[28:29], v[32:33]
	v_mov_b32_e32 v32, v8
	v_mov_b32_e32 v42, v6
	v_pk_mov_b32 v[8:9], v[8:9], v[12:13] op_sel:[1,0]
	v_pk_mov_b32 v[6:7], v[6:7], v[40:41] op_sel:[1,0]
	v_pk_add_f32 v[12:13], v[18:19], v[36:37]
	v_pk_mul_f32 v[26:27], v[24:25], v[24:25]
	v_pk_mul_f32 v[30:31], v[16:17], v[16:17]
	v_pk_add_f32 v[6:7], v[8:9], v[6:7]
	v_pk_add_f32 v[8:9], v[20:21], v[38:39]
	v_mov_b32_e32 v13, v11
	v_pk_add_f32 v[10:11], v[24:25], v[16:17]
	v_pk_add_f32 v[2:3], v[2:3], v[14:15]
	v_mov_b32_e32 v33, v26
	v_mov_b32_e32 v43, v30
	v_mov_b32_e32 v9, v23
	v_mov_b32_e32 v11, v27
	v_mov_b32_e32 v3, v41
	v_pk_add_f32 v[4:5], v[4:5], v[4:5] op_sel_hi:[0,1]
	v_pk_add_f32 v[30:31], v[32:33], v[42:43]
	v_pk_add_f32 v[8:9], v[8:9], v[12:13]
	v_pk_add_f32 v[2:3], v[10:11], v[2:3]
	v_pk_add_f32 v[6:7], v[30:31], v[6:7]
	v_pk_add_f32 v[2:3], v[8:9], v[2:3]
	v_mov_b32_e32 v4, v1
	v_pk_add_f32 v[6:7], v[28:29], v[6:7]
	v_pk_add_f32 v[2:3], v[2:3], v[4:5]
	s_nop 0
	v_pk_add_f32 v[2:3], v[6:7], v[2:3]
	ds_bpermute_b32 v4, v194, v2
	ds_bpermute_b32 v5, v194, v3
	s_waitcnt lgkmcnt(0)
	v_pk_add_f32 v[2:3], v[2:3], v[4:5]
	ds_bpermute_b32 v4, v195, v2
	ds_bpermute_b32 v5, v195, v3
	s_and_saveexec_b64 s[26:27], s[42:43]
	s_cbranch_execz .LBB0_225
	v_readlane_b32 s28, v251, 35
	v_lshlrev_b64 v[6:7], 8, v[34:35]
	v_readlane_b32 s29, v251, 36
	s_waitcnt lgkmcnt(0)
	v_pk_add_f32 v[2:3], v[2:3], v[4:5]
	v_lshl_add_u64 v[6:7], s[28:29], 0, v[6:7]
	v_lshl_add_u64 v[6:7], s[24:25], 3, v[6:7]
	global_store_dwordx2 v[6:7], v[2:3], off
